# lever 4: one static s_setprio 1 for waves 4-7 before each big GEMM unit loop, per-segment s_setprio toggles deleted (seven 256x256 loops)
# baseline (speedup 1.0000x reference)
; #define PG8_STAGE(bufoff, gbase, voff) do { _Pragma("unroll") for (int _i = 0; _i < 2; ++_i) \
;         __builtin_amdgcn_global_load_lds((const unsigned*)((const char*)(gbase) + (voff)[_i]), (PG8_LAS unsigned*)(lds + (bufoff) + ldsw + _i * 8192), 16, 0, 0); } while (0)
; #define PG8_WAIT_V(n) asm volatile("s_waitcnt vmcnt(" #n ")" ::: "memory")
; #define PG8_BAR __builtin_amdgcn_s_barrier()
; template <class Epi, class Sched, bool ALIGN_EPI = false, bool SP2 = false>
; __device__ __forceinline__ void gemm_phase(PG8_LAS unsigned char* lds, const Gemm g, const Sched& S, const Epi& E, const int tid) {
;     ...
;         if (wr == 1) PG8_BAR;
;         PG8_WAIT_V(2); PG8_BAR;
;         PG8_STAGE(PG8_SB(1, 0), cB + kstep, voffB); PG8_STAGE(PG8_SA(1, 0), cA + kstep, voffA); PG8_STAGE(PG8_SB(1, 1), cB + hstepB + kstep, voffB);
;         PG8_WAIT_V(6); PG8_BAR;
;     } else {
;         PG8_STAGE(PG8_SB(0, 0), cB, voffB); PG8_STAGE(PG8_SA(0, 0), cA, voffA); PG8_STAGE(PG8_SB(0, 1), cB + hstepB, voffB); PG8_STAGE(PG8_SA(0, 1), cA + hstep, voffA);
;         if (wr == 1) PG8_BAR;
;         PG8_WAIT_V(4); PG8_BAR;
;         PG8_STAGE(PG8_SB(1, 0), cB + kstep, voffB); PG8_STAGE(PG8_SA(1, 0), cA + kstep, voffA); PG8_STAGE(PG8_SB(1, 1), cB + hstepB + kstep, voffB);
;         PG8_WAIT_V(6); PG8_BAR;
;     }
;     if constexpr (Epi::HAS_INIT) E.init_finish(acc, iw_);
.LBB0_179:
	v_mov_b32_e32 v137, v2
	v_lshl_add_u64 v[10:11], s[40:41], 0, v[136:137]
	v_mov_b32_e32 v141, v2
	v_lshlrev_b32_e32 v18, 1, v157
	v_lshlrev_b32_e32 v20, 2, v156
	v_lshl_add_u64 v[12:13], s[40:41], 0, v[140:141]
	v_mov_b32_e32 v135, v2
	s_and_b32 s5, s18, 3
	v_lshl_or_b32 v19, v156, 6, v18
	s_lshl_b32 s18, s20, 13
	v_and_b32_e32 v21, 32, v20
	s_add_i32 m0, s63, 0x18000
	v_lshl_add_u64 v[10:11], v[10:11], 0, s[52:53]
	v_lshl_add_u64 v[14:15], s[38:39], 0, v[134:135]
	v_mov_b32_e32 v139, v2
	v_bitop3_b32 v19, v19, s18, v21 bitop3:0xde
	v_or_b32_e32 v18, v18, v3
	s_lshl_b32 s18, s5, 12
	s_waitcnt vmcnt(2)
	s_barrier
	global_load_lds_dwordx4 v[10:11], off
	v_lshl_add_u64 v[10:11], v[12:13], 0, s[52:53]
	s_add_i32 m0, s63, 0x1a000
	s_add_i32 s78, s63, 0x8000
	s_add_i32 s79, s63, 0xa000
	v_lshl_add_u64 v[16:17], s[38:39], 0, v[138:139]
	v_bitop3_b32 v163, s18, v18, v21 bitop3:0xf6
	global_load_lds_dwordx4 v[10:11], off
	v_lshl_add_u64 v[10:11], v[14:15], 0, s[52:53]
	s_mov_b32 m0, s78
	s_add_u32 s18, s40, 0x10080
	global_load_lds_dwordx4 v[10:11], off
	v_lshl_add_u64 v[10:11], v[16:17], 0, s[52:53]
	s_mov_b32 m0, s79
	s_addc_u32 s19, s41, 0
	global_load_lds_dwordx4 v[10:11], off
	s_add_i32 m0, s63, 0x1c000
	v_lshl_add_u64 v[10:11], s[18:19], 0, v[136:137]
	global_load_lds_dwordx4 v[10:11], off
	v_lshl_add_u64 v[10:11], s[18:19], 0, v[140:141]
	s_add_i32 m0, s63, 0x1e000
	s_cmpk_lt_u32 s3, 0x100
	global_load_lds_dwordx4 v[10:11], off
	v_lshlrev_b32_e32 v10, 14, v4
	v_and_b32_e32 v10, 0xffff8000, v10
	v_lshl_add_u32 v5, v5, 11, v10
	v_and_b32_e32 v4, 1, v4
	v_lshl_or_b32 v4, v4, 6, v5
	v_lshl_add_u32 v142, v6, 1, v4
	v_lshlrev_b32_e32 v4, 14, v7
	s_cselect_b64 s[18:19], -1, 0
	s_lshl_b32 s3, s20, 8
	v_and_b32_e32 v4, 0xffff8000, v4
	s_waitcnt vmcnt(6)
	s_add_i32 s3, s3, 0
	v_lshl_add_u32 v4, v8, 11, v4
	v_and_b32_e32 v5, 1, v7
	s_add_i32 s3, s3, 0x20000
	v_lshl_or_b32 v4, v5, 6, v4
	v_lshl_or_b32 v162, s20, 6, v156
	s_lshl_b32 s80, s54, 3
	v_add_u32_e32 v164, s3, v20
	v_lshl_or_b32 v165, s5, 6, v157
	v_mov_b32_e32 v143, v2
	v_lshl_add_u32 v144, v9, 1, v4
	v_mov_b32_e32 v145, v2
	s_mov_b32 s81, 0
	v_add_u32_e32 v166, 0, v19
	s_barrier
	v_readfirstlane_b32 s98, v0
	s_nop 3
	s_and_b32 s98, s98, 0x3ff
	s_lshr_b32 s98, s98, 6
	s_cmp_ge_u32 s98, 4
	s_cbranch_scc0 .Lprio_done0
	s_setprio 1
.Lprio_done0:
	s_branch .LBB0_182
.LBB0_180:
	s_mov_b64 s[4:5], 0

;     DI bool next(int i, Unit& u) const { const int L = i * 32 + rank; if (L >= ppg * nN) return false; u.pm = ppg * grp + (L % ppg); const int p0 = L / ppg, p1 = p0 + rot; u.pn = rev ? nN - 1 - p0 : (p1 >= nN ? p1 - nN : p1); return true; }
; #define PG8_STAGE(bufoff, gbase, voff) do { _Pragma("unroll") for (int _i = 0; _i < 2; ++_i) \
;         __builtin_amdgcn_global_load_lds((const unsigned*)((const char*)(gbase) + (voff)[_i]), (PG8_LAS unsigned*)(lds + (bufoff) + ldsw + _i * 8192), 16, 0, 0); } while (0)
; #define PG8_LDA(dst, b, h) do { _Pragma("unroll") for (int m = 0; m < 4; ++m) _Pragma("unroll") for (int k = 0; k < 2; ++k) dst[m][k] = *(const PG8_LAS bf16x8*)(lds + PG8_SA(b, h) + aoff + m * 2048 + k * 1024); } while (0)
; #define PG8_LDB(dst, b, h) do { _Pragma("unroll") for (int n = 0; n < 2; ++n) _Pragma("unroll") for (int k = 0; k < 2; ++k) dst[n][k] = *(const PG8_LAS bf16x8*)(lds + PG8_SB(b, h) + boff + n * 2048 + k * 1024); } while (0)
; #define PG8_WAIT_V(n) asm volatile("s_waitcnt vmcnt(" #n ")" ::: "memory")
; #define PG8_WAIT_L(n) asm volatile("s_waitcnt lgkmcnt(" #n ")" ::: "memory")
; template <class Epi, class Sched, bool ALIGN_EPI = false, bool SP2 = false>
; __device__ __forceinline__ void gemm_phase(PG8_LAS unsigned char* lds, const Gemm g, const Sched& S, const Epi& E, const int tid) {
;     ...
;         const bool has_next = S.next(ui + 1, nxt);
;         const char* nA = has_next ? (const char*)g.A + (size_t)nxt.pm * tstep : cA; const char* nB = has_next ? (const char*)g.Bt + (size_t)nxt.pn * tstep : cB;
;         for (int t = 0; t < nt; t += 2) {
;             const bool last = (t == nt - 2);
;             const char* a1 = cA + (size_t)(t + 1) * kstep;
;             const char* a2 = last ? nA : cA + (size_t)(t + 2) * kstep; const char* b2 = last ? nB : cB + (size_t)(t + 2) * kstep;
;             const char* a3 = a2 + kstep; const char* b3 = b2 + kstep;
;             if (last && has_next) S.a_ready(nxt);
;             if constexpr (SP2) {
;             PG8_LDB(B0, 0, 0); PG8_LDB(B1, 0, 1); PG8_SCHED; PG8_LDA(At, 0, 0); PG8_STAGE(PG8_SA(1, 1), a1 + hstep, voffA);
;             PG8_WAIT_V(8); PG8_WAIT_L(0); PG8_BAR; PG8_MMA(0, 0, At, B0); PG8_MMA(0, 1, At, B1); PG8_BAR; PG8_SCHED;
;             PG8_LDA(At, 0, 1); PG8_STAGE(PG8_SB(0, 0), b2, voffB); PG8_STAGE(PG8_SB(0, 1), b2 + hstepB, voffB); PG8_STAGE(PG8_SA(0, 0), a2, voffA);
.LBB0_185:
	s_add_u32 s40, s38, 0xfffc0080
	s_addc_u32 s41, s39, -1
	s_add_i32 s82, 0, 0x10000
	s_cmp_eq_u32 s67, 12
	s_cselect_b32 s43, s3, s41
	s_cselect_b32 s42, s5, s40
	v_add_u32_e32 v154, s82, v163
	s_cselect_b32 s41, s21, s66
	s_cselect_b32 s40, s23, s37
	s_cmp_eq_u32 s67, 12
	s_cselect_b32 s32, 1, 0
	s_andn2_b32 s32, s32, s28
	s_add_i32 s84, 0, 0x14000
	ds_read_b128 v[146:149], v154
	ds_read_b128 v[150:153], v154 offset:1024
	ds_read_b128 v[170:173], v154 offset:2048
	ds_read_b128 v[174:177], v154 offset:3072
	v_add_u32_e32 v154, s84, v163
	ds_read_b128 v[178:181], v154
	ds_read_b128 v[182:185], v154 offset:1024
	ds_read_b128 v[186:189], v154 offset:2048
	ds_read_b128 v[190:193], v154 offset:3072
	v_lshl_add_u64 v[154:155], s[38:39], 0, v[142:143]
	s_add_i32 m0, s63, 0xc000
	ds_read_b128 v[194:197], v166
	ds_read_b128 v[198:201], v166 offset:1024
	ds_read_b128 v[212:215], v166 offset:2048
	ds_read_b128 v[216:219], v166 offset:3072
	ds_read_b128 v[220:223], v166 offset:4096
	ds_read_b128 v[224:227], v166 offset:5120
	ds_read_b128 v[228:231], v166 offset:6144
	ds_read_b128 v[232:235], v166 offset:7168
	global_load_lds_dwordx4 v[154:155], off
	v_lshl_add_u64 v[154:155], s[38:39], 0, v[144:145]
	s_add_i32 m0, s63, 0xe000
	s_nop 0
	global_load_lds_dwordx4 v[154:155], off
	s_waitcnt vmcnt(8)
	s_waitcnt lgkmcnt(0)
	s_barrier
	s_waitcnt lgkmcnt(0)
	v_mfma_f32_16x16x32_bf16 v[128:131], v[146:149], v[194:197], v[128:131]
	v_mfma_f32_16x16x32_bf16 v[124:127], v[170:173], v[194:197], v[124:127]
	v_mfma_f32_16x16x32_bf16 v[112:115], v[146:149], v[212:215], v[112:115]
	v_mfma_f32_16x16x32_bf16 v[108:111], v[170:173], v[212:215], v[108:111]
	v_mfma_f32_16x16x32_bf16 v[96:99], v[146:149], v[220:223], v[96:99]
	v_mfma_f32_16x16x32_bf16 v[92:95], v[170:173], v[220:223], v[92:95]
	v_mfma_f32_16x16x32_bf16 v[80:83], v[146:149], v[228:231], v[80:83]
	v_mfma_f32_16x16x32_bf16 v[76:79], v[170:173], v[228:231], v[76:79]
	v_mfma_f32_16x16x32_bf16 v[128:131], v[150:153], v[198:201], v[128:131]
	v_mfma_f32_16x16x32_bf16 v[124:127], v[174:177], v[198:201], v[124:127]
	v_mfma_f32_16x16x32_bf16 v[112:115], v[150:153], v[216:219], v[112:115]
	v_mfma_f32_16x16x32_bf16 v[108:111], v[174:177], v[216:219], v[108:111]
	v_mfma_f32_16x16x32_bf16 v[96:99], v[150:153], v[224:227], v[96:99]
	v_mfma_f32_16x16x32_bf16 v[92:95], v[174:177], v[224:227], v[92:95]
	v_mfma_f32_16x16x32_bf16 v[80:83], v[150:153], v[232:235], v[80:83]
	v_mfma_f32_16x16x32_bf16 v[76:79], v[174:177], v[232:235], v[76:79]
	v_mfma_f32_16x16x32_bf16 v[120:123], v[178:181], v[194:197], v[120:123]
	v_mfma_f32_16x16x32_bf16 v[116:119], v[186:189], v[194:197], v[116:119]
	v_mfma_f32_16x16x32_bf16 v[104:107], v[178:181], v[212:215], v[104:107]
	v_mfma_f32_16x16x32_bf16 v[100:103], v[186:189], v[212:215], v[100:103]
	v_mfma_f32_16x16x32_bf16 v[88:91], v[178:181], v[220:223], v[88:91]
	v_mfma_f32_16x16x32_bf16 v[84:87], v[186:189], v[220:223], v[84:87]
	v_mfma_f32_16x16x32_bf16 v[72:75], v[178:181], v[228:231], v[72:75]
	v_mfma_f32_16x16x32_bf16 v[68:71], v[186:189], v[228:231], v[68:71]
	v_mfma_f32_16x16x32_bf16 v[120:123], v[182:185], v[198:201], v[120:123]
	v_mfma_f32_16x16x32_bf16 v[116:119], v[190:193], v[198:201], v[116:119]
	v_mfma_f32_16x16x32_bf16 v[104:107], v[182:185], v[216:219], v[104:107]
	v_mfma_f32_16x16x32_bf16 v[100:103], v[190:193], v[216:219], v[100:103]
	v_mfma_f32_16x16x32_bf16 v[88:91], v[182:185], v[224:227], v[88:91]
	v_mfma_f32_16x16x32_bf16 v[84:87], v[190:193], v[224:227], v[84:87]
	v_mfma_f32_16x16x32_bf16 v[72:75], v[182:185], v[232:235], v[72:75]
	v_mfma_f32_16x16x32_bf16 v[68:71], v[190:193], v[232:235], v[68:71]
	s_barrier
	s_add_i32 s82, s82, s62
	v_lshl_add_u64 v[154:155], s[40:41], 0, v[136:137]
	s_mov_b32 m0, s82
	ds_read_b128 v[194:197], v166 offset:16384
	ds_read_b128 v[198:201], v166 offset:17408
	ds_read_b128 v[212:215], v166 offset:18432
	ds_read_b128 v[216:219], v166 offset:19456
	ds_read_b128 v[220:223], v166 offset:20480
	ds_read_b128 v[224:227], v166 offset:21504
	ds_read_b128 v[228:231], v166 offset:22528
	ds_read_b128 v[232:235], v166 offset:23552
	s_cmp_lg_u32 s32, 0
	s_cbranch_scc1 .Lbt0_0
	global_load_lds_dwordx4 v[154:155], off

; #define PG8_STAGE(bufoff, gbase, voff) do { _Pragma("unroll") for (int _i = 0; _i < 2; ++_i) \
;         __builtin_amdgcn_global_load_lds((const unsigned*)((const char*)(gbase) + (voff)[_i]), (PG8_LAS unsigned*)(lds + (bufoff) + ldsw + _i * 8192), 16, 0, 0); } while (0)
; #define PG8_LDA(dst, b, h) do { _Pragma("unroll") for (int m = 0; m < 4; ++m) _Pragma("unroll") for (int k = 0; k < 2; ++k) dst[m][k] = *(const PG8_LAS bf16x8*)(lds + PG8_SA(b, h) + aoff + m * 2048 + k * 1024); } while (0)
; #define PG8_LDB(dst, b, h) do { _Pragma("unroll") for (int n = 0; n < 2; ++n) _Pragma("unroll") for (int k = 0; k < 2; ++k) dst[n][k] = *(const PG8_LAS bf16x8*)(lds + PG8_SB(b, h) + boff + n * 2048 + k * 1024); } while (0)
; #define PG8_MMA(ai, bj, At, Bt) do { __builtin_amdgcn_s_setprio(1); _Pragma("unroll") for (int m = 0; m < 4; ++m) _Pragma("unroll") for (int n = 0; n < 2; ++n) _Pragma("unroll") for (int k = 0; k < 2; ++k) \
;         acc[ai][bj][m][n] = __builtin_amdgcn_mfma_f32_16x16x32_bf16(Bt[n][k], At[m][k], acc[ai][bj][m][n], 0, 0, 0); __builtin_amdgcn_s_setprio(0); } while (0)
; #define PG8_WAIT_V(n) asm volatile("s_waitcnt vmcnt(" #n ")" ::: "memory")
; #define PG8_WAIT_L(n) asm volatile("s_waitcnt lgkmcnt(" #n ")" ::: "memory")
; #define PG8_BAR __builtin_amdgcn_s_barrier()
; #define PG8_SCHED __builtin_amdgcn_sched_barrier(0)
; template <class Epi, class Sched, bool ALIGN_EPI = false, bool SP2 = false>
; __device__ __forceinline__ void gemm_phase(PG8_LAS unsigned char* lds, const Gemm g, const Sched& S, const Epi& E, const int tid) {
;     ...
;             PG8_WAIT_V(8); PG8_WAIT_L(0); PG8_BAR; PG8_MMA(1, 0, At, B0); PG8_MMA(1, 1, At, B1); PG8_BAR; PG8_SCHED;
;             PG8_LDB(B0, 1, 0); PG8_LDB(B1, 1, 1); PG8_SCHED; PG8_LDA(At, 1, 0); PG8_STAGE(PG8_SA(0, 1), a2 + hstep, voffA);
.Lbw0_2:
	s_waitcnt lgkmcnt(0)
	s_barrier
	s_waitcnt lgkmcnt(0)
	v_mfma_f32_16x16x32_bf16 v[64:67], v[146:149], v[194:197], v[64:67]
	v_mfma_f32_16x16x32_bf16 v[60:63], v[170:173], v[194:197], v[60:63]
	v_mfma_f32_16x16x32_bf16 v[48:51], v[146:149], v[212:215], v[48:51]
	v_mfma_f32_16x16x32_bf16 v[44:47], v[170:173], v[212:215], v[44:47]
	v_mfma_f32_16x16x32_bf16 v[32:35], v[146:149], v[220:223], v[32:35]
	v_mfma_f32_16x16x32_bf16 v[28:31], v[170:173], v[220:223], v[28:31]
	v_mfma_f32_16x16x32_bf16 v[16:19], v[146:149], v[228:231], v[16:19]
	v_mfma_f32_16x16x32_bf16 v[12:15], v[170:173], v[228:231], v[12:15]
	v_mfma_f32_16x16x32_bf16 v[64:67], v[150:153], v[198:201], v[64:67]
	v_mfma_f32_16x16x32_bf16 v[60:63], v[174:177], v[198:201], v[60:63]
	v_mfma_f32_16x16x32_bf16 v[48:51], v[150:153], v[216:219], v[48:51]
	v_mfma_f32_16x16x32_bf16 v[44:47], v[174:177], v[216:219], v[44:47]
	v_mfma_f32_16x16x32_bf16 v[32:35], v[150:153], v[224:227], v[32:35]
	v_mfma_f32_16x16x32_bf16 v[28:31], v[174:177], v[224:227], v[28:31]
	v_mfma_f32_16x16x32_bf16 v[16:19], v[150:153], v[232:235], v[16:19]
	v_mfma_f32_16x16x32_bf16 v[12:15], v[174:177], v[232:235], v[12:15]
	v_mfma_f32_16x16x32_bf16 v[56:59], v[178:181], v[194:197], v[56:59]
	v_mfma_f32_16x16x32_bf16 v[52:55], v[186:189], v[194:197], v[52:55]
	v_mfma_f32_16x16x32_bf16 v[40:43], v[178:181], v[212:215], v[40:43]
	v_mfma_f32_16x16x32_bf16 v[36:39], v[186:189], v[212:215], v[36:39]
	v_mfma_f32_16x16x32_bf16 v[24:27], v[178:181], v[220:223], v[24:27]
	v_mfma_f32_16x16x32_bf16 v[20:23], v[186:189], v[220:223], v[20:23]
	v_mfma_f32_16x16x32_bf16 v[8:11], v[178:181], v[228:231], v[8:11]
	v_mfma_f32_16x16x32_bf16 v[4:7], v[186:189], v[228:231], v[4:7]
	v_mfma_f32_16x16x32_bf16 v[56:59], v[182:185], v[198:201], v[56:59]
	v_mfma_f32_16x16x32_bf16 v[52:55], v[190:193], v[198:201], v[52:55]
	v_mfma_f32_16x16x32_bf16 v[40:43], v[182:185], v[216:219], v[40:43]
	v_mfma_f32_16x16x32_bf16 v[36:39], v[190:193], v[216:219], v[36:39]
	v_mfma_f32_16x16x32_bf16 v[24:27], v[182:185], v[224:227], v[24:27]
	v_mfma_f32_16x16x32_bf16 v[20:23], v[190:193], v[224:227], v[20:23]
	v_mfma_f32_16x16x32_bf16 v[8:11], v[182:185], v[232:235], v[8:11]
	v_mfma_f32_16x16x32_bf16 v[4:7], v[190:193], v[232:235], v[4:7]
	s_barrier
	s_add_i32 s82, 0, 0x18000
	v_add_u32_e32 v167, s82, v163
	s_add_i32 s83, 0, 0x1c000
	ds_read_b128 v[146:149], v167
	ds_read_b128 v[150:153], v167 offset:1024
	ds_read_b128 v[170:173], v167 offset:2048
	ds_read_b128 v[174:177], v167 offset:3072
	v_add_u32_e32 v167, s83, v163
	ds_read_b128 v[178:181], v167
	ds_read_b128 v[182:185], v167 offset:1024
	ds_read_b128 v[186:189], v167 offset:2048
	ds_read_b128 v[190:193], v167 offset:3072
	s_add_u32 s42, s42, 0x40000
	s_addc_u32 s43, s43, 0
	s_mov_b32 m0, s65
	v_lshl_add_u64 v[242:243], s[42:43], 0, v[134:135]
	ds_read_b128 v[194:197], v166 offset:32768
	ds_read_b128 v[198:201], v166 offset:33792
	ds_read_b128 v[212:215], v166 offset:34816
	ds_read_b128 v[216:219], v166 offset:35840
	ds_read_b128 v[220:223], v166 offset:36864
	ds_read_b128 v[224:227], v166 offset:37888
	ds_read_b128 v[228:231], v166 offset:38912
	ds_read_b128 v[232:235], v166 offset:39936
	s_cmp_lg_u32 s32, 0
	s_cbranch_scc1 .Lbt0_6
	global_load_lds_dwordx4 v[242:243], off

; #define PG8_STAGE(bufoff, gbase, voff) do { _Pragma("unroll") for (int _i = 0; _i < 2; ++_i) \
;         __builtin_amdgcn_global_load_lds((const unsigned*)((const char*)(gbase) + (voff)[_i]), (PG8_LAS unsigned*)(lds + (bufoff) + ldsw + _i * 8192), 16, 0, 0); } while (0)
; #define PG8_LDA(dst, b, h) do { _Pragma("unroll") for (int m = 0; m < 4; ++m) _Pragma("unroll") for (int k = 0; k < 2; ++k) dst[m][k] = *(const PG8_LAS bf16x8*)(lds + PG8_SA(b, h) + aoff + m * 2048 + k * 1024); } while (0)
; #define PG8_MMA(ai, bj, At, Bt) do { __builtin_amdgcn_s_setprio(1); _Pragma("unroll") for (int m = 0; m < 4; ++m) _Pragma("unroll") for (int n = 0; n < 2; ++n) _Pragma("unroll") for (int k = 0; k < 2; ++k) \
;         acc[ai][bj][m][n] = __builtin_amdgcn_mfma_f32_16x16x32_bf16(Bt[n][k], At[m][k], acc[ai][bj][m][n], 0, 0, 0); __builtin_amdgcn_s_setprio(0); } while (0)
; #define PG8_WAIT_V(n) asm volatile("s_waitcnt vmcnt(" #n ")" ::: "memory")
; #define PG8_WAIT_L(n) asm volatile("s_waitcnt lgkmcnt(" #n ")" ::: "memory")
; #define PG8_BAR __builtin_amdgcn_s_barrier()
; #define PG8_SCHED __builtin_amdgcn_sched_barrier(0)
; template <class Epi, class Sched, bool ALIGN_EPI = false, bool SP2 = false>
; __device__ __forceinline__ void gemm_phase(PG8_LAS unsigned char* lds, const Gemm g, const Sched& S, const Epi& E, const int tid) {
;     ...
;             PG8_WAIT_V(8); PG8_WAIT_L(0); PG8_BAR; PG8_MMA(0, 0, At, B0); PG8_MMA(0, 1, At, B1); PG8_BAR; PG8_SCHED;
;             PG8_LDA(At, 1, 1); PG8_STAGE(PG8_SB(1, 0), b3, voffB); PG8_STAGE(PG8_SB(1, 1), b3 + hstepB, voffB); PG8_STAGE(PG8_SA(1, 0), a3, voffA);
.Lbw0_0:
	s_waitcnt lgkmcnt(0)
	s_barrier
	s_waitcnt lgkmcnt(0)
	v_mfma_f32_16x16x32_bf16 v[128:131], v[146:149], v[194:197], v[128:131]
	v_mfma_f32_16x16x32_bf16 v[124:127], v[170:173], v[194:197], v[124:127]
	v_mfma_f32_16x16x32_bf16 v[112:115], v[146:149], v[212:215], v[112:115]
	v_mfma_f32_16x16x32_bf16 v[108:111], v[170:173], v[212:215], v[108:111]
	v_mfma_f32_16x16x32_bf16 v[96:99], v[146:149], v[220:223], v[96:99]
	v_mfma_f32_16x16x32_bf16 v[92:95], v[170:173], v[220:223], v[92:95]
	v_mfma_f32_16x16x32_bf16 v[80:83], v[146:149], v[228:231], v[80:83]
	v_mfma_f32_16x16x32_bf16 v[76:79], v[170:173], v[228:231], v[76:79]
	v_mfma_f32_16x16x32_bf16 v[128:131], v[150:153], v[198:201], v[128:131]
	v_mfma_f32_16x16x32_bf16 v[124:127], v[174:177], v[198:201], v[124:127]
	v_mfma_f32_16x16x32_bf16 v[112:115], v[150:153], v[216:219], v[112:115]
	v_mfma_f32_16x16x32_bf16 v[108:111], v[174:177], v[216:219], v[108:111]
	v_mfma_f32_16x16x32_bf16 v[96:99], v[150:153], v[224:227], v[96:99]
	v_mfma_f32_16x16x32_bf16 v[92:95], v[174:177], v[224:227], v[92:95]
	v_mfma_f32_16x16x32_bf16 v[80:83], v[150:153], v[232:235], v[80:83]
	v_mfma_f32_16x16x32_bf16 v[76:79], v[174:177], v[232:235], v[76:79]
	v_mfma_f32_16x16x32_bf16 v[120:123], v[178:181], v[194:197], v[120:123]
	v_mfma_f32_16x16x32_bf16 v[116:119], v[186:189], v[194:197], v[116:119]
	v_mfma_f32_16x16x32_bf16 v[104:107], v[178:181], v[212:215], v[104:107]
	v_mfma_f32_16x16x32_bf16 v[100:103], v[186:189], v[212:215], v[100:103]
	v_mfma_f32_16x16x32_bf16 v[88:91], v[178:181], v[220:223], v[88:91]
	v_mfma_f32_16x16x32_bf16 v[84:87], v[186:189], v[220:223], v[84:87]
	v_mfma_f32_16x16x32_bf16 v[72:75], v[178:181], v[228:231], v[72:75]
	v_mfma_f32_16x16x32_bf16 v[68:71], v[186:189], v[228:231], v[68:71]
	v_mfma_f32_16x16x32_bf16 v[120:123], v[182:185], v[198:201], v[120:123]
	v_mfma_f32_16x16x32_bf16 v[116:119], v[190:193], v[198:201], v[116:119]
	v_mfma_f32_16x16x32_bf16 v[104:107], v[182:185], v[216:219], v[104:107]
	v_mfma_f32_16x16x32_bf16 v[100:103], v[190:193], v[216:219], v[100:103]
	v_mfma_f32_16x16x32_bf16 v[88:91], v[182:185], v[224:227], v[88:91]
	v_mfma_f32_16x16x32_bf16 v[84:87], v[190:193], v[224:227], v[84:87]
	v_mfma_f32_16x16x32_bf16 v[72:75], v[182:185], v[232:235], v[72:75]
	v_mfma_f32_16x16x32_bf16 v[68:71], v[190:193], v[232:235], v[68:71]
	s_barrier
	s_add_i32 s42, s82, s62
	v_lshl_add_u64 v[154:155], v[154:155], 0, s[52:53]
	s_mov_b32 m0, s42
	ds_read_b128 v[194:197], v166 offset:49152
	ds_read_b128 v[198:201], v166 offset:50176
	ds_read_b128 v[212:215], v166 offset:51200
	ds_read_b128 v[216:219], v166 offset:52224
	ds_read_b128 v[220:223], v166 offset:53248
	ds_read_b128 v[224:227], v166 offset:54272
	ds_read_b128 v[228:231], v166 offset:55296
	ds_read_b128 v[232:235], v166 offset:56320
	s_cmp_lg_u32 s32, 0
	s_cbranch_scc1 .Lbt0_8
	global_load_lds_dwordx4 v[154:155], off

; #define PG8_STAGE(bufoff, gbase, voff) do { _Pragma("unroll") for (int _i = 0; _i < 2; ++_i) \
;         __builtin_amdgcn_global_load_lds((const unsigned*)((const char*)(gbase) + (voff)[_i]), (PG8_LAS unsigned*)(lds + (bufoff) + ldsw + _i * 8192), 16, 0, 0); } while (0)
; #define PG8_LDA(dst, b, h) do { _Pragma("unroll") for (int m = 0; m < 4; ++m) _Pragma("unroll") for (int k = 0; k < 2; ++k) dst[m][k] = *(const PG8_LAS bf16x8*)(lds + PG8_SA(b, h) + aoff + m * 2048 + k * 1024); } while (0)
; #define PG8_MMA(ai, bj, At, Bt) do { __builtin_amdgcn_s_setprio(1); _Pragma("unroll") for (int m = 0; m < 4; ++m) _Pragma("unroll") for (int n = 0; n < 2; ++n) _Pragma("unroll") for (int k = 0; k < 2; ++k) \
;         acc[ai][bj][m][n] = __builtin_amdgcn_mfma_f32_16x16x32_bf16(Bt[n][k], At[m][k], acc[ai][bj][m][n], 0, 0, 0); __builtin_amdgcn_s_setprio(0); } while (0)
; #define PG8_WAIT_V(n) asm volatile("s_waitcnt vmcnt(" #n ")" ::: "memory")
; #define PG8_WAIT_L(n) asm volatile("s_waitcnt lgkmcnt(" #n ")" ::: "memory")
; #define PG8_BAR __builtin_amdgcn_s_barrier()
; #define PG8_SCHED __builtin_amdgcn_sched_barrier(0)
; template <class Epi, class Sched, bool ALIGN_EPI = false, bool SP2 = false>
; __device__ __forceinline__ void gemm_phase(PG8_LAS unsigned char* lds, const Gemm g, const Sched& S, const Epi& E, const int tid) {
;     ...
;             PG8_LDA(At, 1, 1); PG8_STAGE(PG8_SB(1, 0), b3, voffB); PG8_STAGE(PG8_SB(1, 1), b3 + hstepB, voffB); PG8_STAGE(PG8_SA(1, 0), a3, voffA);
;             PG8_WAIT_V(8); PG8_WAIT_L(0); PG8_BAR; PG8_MMA(1, 0, At, B0); PG8_MMA(1, 1, At, B1); PG8_BAR; PG8_SCHED;
.Lbt0_13:
	s_waitcnt vmcnt(8)
	s_waitcnt lgkmcnt(0)
	s_barrier
	s_waitcnt lgkmcnt(0)
	v_mfma_f32_16x16x32_bf16 v[64:67], v[146:149], v[194:197], v[64:67]
	v_mfma_f32_16x16x32_bf16 v[60:63], v[170:173], v[194:197], v[60:63]
	v_mfma_f32_16x16x32_bf16 v[48:51], v[146:149], v[212:215], v[48:51]
	v_mfma_f32_16x16x32_bf16 v[44:47], v[170:173], v[212:215], v[44:47]
	v_mfma_f32_16x16x32_bf16 v[32:35], v[146:149], v[220:223], v[32:35]
	v_mfma_f32_16x16x32_bf16 v[28:31], v[170:173], v[220:223], v[28:31]
	v_mfma_f32_16x16x32_bf16 v[16:19], v[146:149], v[228:231], v[16:19]
	v_mfma_f32_16x16x32_bf16 v[12:15], v[170:173], v[228:231], v[12:15]
	v_mfma_f32_16x16x32_bf16 v[64:67], v[150:153], v[198:201], v[64:67]
	v_mfma_f32_16x16x32_bf16 v[60:63], v[174:177], v[198:201], v[60:63]
	v_mfma_f32_16x16x32_bf16 v[48:51], v[150:153], v[216:219], v[48:51]
	v_mfma_f32_16x16x32_bf16 v[44:47], v[174:177], v[216:219], v[44:47]
	v_mfma_f32_16x16x32_bf16 v[32:35], v[150:153], v[224:227], v[32:35]
	v_mfma_f32_16x16x32_bf16 v[28:31], v[174:177], v[224:227], v[28:31]
	v_mfma_f32_16x16x32_bf16 v[16:19], v[150:153], v[232:235], v[16:19]
	v_mfma_f32_16x16x32_bf16 v[12:15], v[174:177], v[232:235], v[12:15]
	v_mfma_f32_16x16x32_bf16 v[56:59], v[178:181], v[194:197], v[56:59]
	v_mfma_f32_16x16x32_bf16 v[52:55], v[186:189], v[194:197], v[52:55]
	v_mfma_f32_16x16x32_bf16 v[40:43], v[178:181], v[212:215], v[40:43]
	v_mfma_f32_16x16x32_bf16 v[36:39], v[186:189], v[212:215], v[36:39]
	v_mfma_f32_16x16x32_bf16 v[24:27], v[178:181], v[220:223], v[24:27]
	v_mfma_f32_16x16x32_bf16 v[20:23], v[186:189], v[220:223], v[20:23]
	v_mfma_f32_16x16x32_bf16 v[8:11], v[178:181], v[228:231], v[8:11]
	v_mfma_f32_16x16x32_bf16 v[4:7], v[186:189], v[228:231], v[4:7]
	v_mfma_f32_16x16x32_bf16 v[56:59], v[182:185], v[198:201], v[56:59]
	v_mfma_f32_16x16x32_bf16 v[52:55], v[190:193], v[198:201], v[52:55]
	v_mfma_f32_16x16x32_bf16 v[40:43], v[182:185], v[216:219], v[40:43]
	v_mfma_f32_16x16x32_bf16 v[36:39], v[190:193], v[216:219], v[36:39]
	v_mfma_f32_16x16x32_bf16 v[24:27], v[182:185], v[224:227], v[24:27]
	v_mfma_f32_16x16x32_bf16 v[20:23], v[190:193], v[224:227], v[20:23]
	v_mfma_f32_16x16x32_bf16 v[8:11], v[182:185], v[232:235], v[8:11]
	v_mfma_f32_16x16x32_bf16 v[4:7], v[190:193], v[232:235], v[4:7]
	s_barrier
	s_add_i32 s67, s67, 2
	s_add_u32 s38, s38, 0x100
	s_addc_u32 s39, s39, 0
	s_add_u32 s37, s37, 0x100
	s_addc_u32 s66, s66, 0
	s_cmp_gt_u32 s67, 13
	s_cbranch_scc0 .LBB0_185
	s_and_b64 vcc, exec, s[18:19]
	s_cbranch_vccz .LBB0_188
	s_barrier

; #define PG8_WAIT_V(n) asm volatile("s_waitcnt vmcnt(" #n ")" ::: "memory")
; #define PG8_BAR __builtin_amdgcn_s_barrier()
; template <class Epi, class Sched, bool ALIGN_EPI = false, bool SP2 = false>
; __device__ __forceinline__ void gemm_phase(PG8_LAS unsigned char* lds, const Gemm g, const Sched& S, const Epi& E, const int tid) {
;     ...
;     PG8_WAIT_V(0);
;     if constexpr (!ALIGN_EPI) { if (wr == 0) PG8_BAR; }
;     PG8_BAR;
.LBB0_223:
	s_setprio 0
	s_waitcnt vmcnt(0)
	s_barrier

; #define PG8_STAGE(bufoff, gbase, voff) do { _Pragma("unroll") for (int _i = 0; _i < 2; ++_i) \
;         __builtin_amdgcn_global_load_lds((const unsigned*)((const char*)(gbase) + (voff)[_i]), (PG8_LAS unsigned*)(lds + (bufoff) + ldsw + _i * 8192), 16, 0, 0); } while (0)
; #define PG8_WAIT_V(n) asm volatile("s_waitcnt vmcnt(" #n ")" ::: "memory")
; #define PG8_BAR __builtin_amdgcn_s_barrier()
; template <class Epi, class Sched, bool ALIGN_EPI = false, bool SP2 = false>
; __device__ __forceinline__ void gemm_phase(PG8_LAS unsigned char* lds, const Gemm g, const Sched& S, const Epi& E, const int tid) {
;     ...
;         if (wr == 1) PG8_BAR;
;         PG8_WAIT_V(2); PG8_BAR;
;         PG8_STAGE(PG8_SB(1, 0), cB + kstep, voffB); PG8_STAGE(PG8_SA(1, 0), cA + kstep, voffA); PG8_STAGE(PG8_SB(1, 1), cB + hstepB + kstep, voffB);
;         PG8_WAIT_V(6); PG8_BAR;
;     } else {
;         PG8_STAGE(PG8_SB(0, 0), cB, voffB); PG8_STAGE(PG8_SA(0, 0), cA, voffA); PG8_STAGE(PG8_SB(0, 1), cB + hstepB, voffB); PG8_STAGE(PG8_SA(0, 1), cA + hstep, voffA);
;         if (wr == 1) PG8_BAR;
;         PG8_WAIT_V(4); PG8_BAR;
;         PG8_STAGE(PG8_SB(1, 0), cB + kstep, voffB); PG8_STAGE(PG8_SA(1, 0), cA + kstep, voffA); PG8_STAGE(PG8_SB(1, 1), cB + hstepB + kstep, voffB);
;         PG8_WAIT_V(6); PG8_BAR;
;     }
;     if constexpr (Epi::HAS_INIT) E.init_finish(acc, iw_);
.LBB0_610:
	v_lshlrev_b32_e32 v18, 1, v143
	v_lshlrev_b32_e32 v19, 2, v170
	s_and_b32 s7, s4, 3
	v_lshl_or_b32 v18, v170, 6, v18
	s_lshl_b32 s4, s38, 13
	v_and_b32_e32 v20, 32, v19
	s_add_i32 m0, s64, 0x18000
	v_lshl_add_u64 v[10:11], v[10:11], 0, s[52:53]
	s_lshl_b32 s92, s38, 6
	v_bitop3_b32 v21, v18, s4, v20 bitop3:0xde
	s_lshl_b32 s4, s7, 12
	s_waitcnt vmcnt(2)
	s_barrier
	global_load_lds_dwordx4 v[10:11], off
	v_lshl_add_u64 v[8:9], v[8:9], 0, s[52:53]
	s_add_i32 m0, s64, 0x1a000
	s_add_i32 s93, s64, 0x8000
	s_add_i32 s95, s64, 0xa000
	v_bitop3_b32 v174, s4, v18, v20 bitop3:0xf6
	global_load_lds_dwordx4 v[8:9], off
	v_lshl_add_u64 v[4:5], v[4:5], 0, s[52:53]
	s_mov_b32 m0, s93
	s_add_u32 s4, s12, 0x10080
	global_load_lds_dwordx4 v[4:5], off
	v_lshl_add_u64 v[4:5], v[6:7], 0, s[52:53]
	s_mov_b32 m0, s95
	s_addc_u32 s5, s13, 0
	global_load_lds_dwordx4 v[4:5], off
	s_add_i32 m0, s64, 0x1c000
	v_lshl_add_u64 v[4:5], s[4:5], 0, v[136:137]
	global_load_lds_dwordx4 v[4:5], off
	v_lshl_add_u64 v[4:5], s[4:5], 0, v[140:141]
	s_add_i32 m0, s64, 0x1e000
	s_cmpk_lt_u32 s3, 0x100
	global_load_lds_dwordx4 v[4:5], off
	v_and_b32_e32 v4, 7, v3
	v_subrev_co_u32_e64 v142, s[4:5], 5, v4
	v_lshlrev_b32_e32 v4, 14, v12
	v_and_b32_e32 v4, 0xffff8000, v4
	v_lshl_add_u32 v4, v13, 11, v4
	v_and_b32_e32 v5, 1, v12
	v_lshl_or_b32 v4, v5, 6, v4
	s_cselect_b64 s[36:37], -1, 0
	s_lshl_b32 s3, s38, 8
	v_lshl_add_u32 v144, v14, 1, v4
	v_lshlrev_b32_e32 v4, 14, v15
	s_add_i32 s3, s3, 0
	v_and_b32_e32 v4, 0xffff8000, v4
	s_waitcnt vmcnt(6)
	s_lshl_b32 s27, s55, 3
	s_add_i32 s3, s3, 0x20000
	v_lshl_add_u32 v4, v16, 11, v4
	v_and_b32_e32 v5, 1, v15
	s_cmp_eq_u64 s[16:17], 0
	v_lshl_or_b32 v4, v5, 6, v4
	v_add_u32_e32 v175, s3, v19
	s_cselect_b64 s[38:39], -1, 0
	v_lshl_or_b32 v176, s7, 6, v143
	v_mov_b32_e32 v145, v2
	v_lshl_add_u32 v146, v17, 1, v4
	v_mov_b32_e32 v147, v2
	s_mov_b32 s76, 0
	v_add_u32_e32 v177, 0, v21
	s_barrier
	v_readfirstlane_b32 s98, v0
	s_nop 3
	s_and_b32 s98, s98, 0x3ff
	s_lshr_b32 s98, s98, 6
	s_cmp_ge_u32 s98, 4
	s_cbranch_scc0 .Lprio_done1
	s_setprio 1
.Lprio_done1:
	s_branch .LBB0_613
.LBB0_611:
	s_mov_b64 s[6:7], 0

;     DI bool next(int i, Unit& u) const { const int L = i * 32 + rank; if (L >= ppg * nN) return false; u.pm = ppg * grp + (L % ppg); const int p0 = L / ppg, p1 = p0 + rot; u.pn = rev ? nN - 1 - p0 : (p1 >= nN ? p1 - nN : p1); return true; }
; #define PG8_STAGE(bufoff, gbase, voff) do { _Pragma("unroll") for (int _i = 0; _i < 2; ++_i) \
;         __builtin_amdgcn_global_load_lds((const unsigned*)((const char*)(gbase) + (voff)[_i]), (PG8_LAS unsigned*)(lds + (bufoff) + ldsw + _i * 8192), 16, 0, 0); } while (0)
; #define PG8_LDA(dst, b, h) do { _Pragma("unroll") for (int m = 0; m < 4; ++m) _Pragma("unroll") for (int k = 0; k < 2; ++k) dst[m][k] = *(const PG8_LAS bf16x8*)(lds + PG8_SA(b, h) + aoff + m * 2048 + k * 1024); } while (0)
; #define PG8_LDB(dst, b, h) do { _Pragma("unroll") for (int n = 0; n < 2; ++n) _Pragma("unroll") for (int k = 0; k < 2; ++k) dst[n][k] = *(const PG8_LAS bf16x8*)(lds + PG8_SB(b, h) + boff + n * 2048 + k * 1024); } while (0)
; #define PG8_WAIT_V(n) asm volatile("s_waitcnt vmcnt(" #n ")" ::: "memory")
; #define PG8_WAIT_L(n) asm volatile("s_waitcnt lgkmcnt(" #n ")" ::: "memory")
; template <class Epi, class Sched, bool ALIGN_EPI = false, bool SP2 = false>
; __device__ __forceinline__ void gemm_phase(PG8_LAS unsigned char* lds, const Gemm g, const Sched& S, const Epi& E, const int tid) {
;     ...
;         const bool has_next = S.next(ui + 1, nxt);
;         const char* nA = has_next ? (const char*)g.A + (size_t)nxt.pm * tstep : cA; const char* nB = has_next ? (const char*)g.Bt + (size_t)nxt.pn * tstep : cB;
;         for (int t = 0; t < nt; t += 2) {
;             const bool last = (t == nt - 2);
;             const char* a1 = cA + (size_t)(t + 1) * kstep;
;             const char* a2 = last ? nA : cA + (size_t)(t + 2) * kstep; const char* b2 = last ? nB : cB + (size_t)(t + 2) * kstep;
;             const char* a3 = a2 + kstep; const char* b3 = b2 + kstep;
;             if (last && has_next) S.a_ready(nxt);
;             if constexpr (SP2) {
;             PG8_LDB(B0, 0, 0); PG8_LDB(B1, 0, 1); PG8_SCHED; PG8_LDA(At, 0, 0); PG8_STAGE(PG8_SA(1, 1), a1 + hstep, voffA);
;             PG8_WAIT_V(8); PG8_WAIT_L(0); PG8_BAR; PG8_MMA(0, 0, At, B0); PG8_MMA(0, 1, At, B1); PG8_BAR; PG8_SCHED;
;             PG8_LDA(At, 0, 1); PG8_STAGE(PG8_SB(0, 0), b2, voffB); PG8_STAGE(PG8_SB(0, 1), b2 + hstepB, voffB); PG8_STAGE(PG8_SA(0, 0), a2, voffA);
.LBB0_616:
	s_add_u32 s12, s10, 0xfffc0080
	s_addc_u32 s13, s11, -1
	s_add_i32 s79, 0, 0x10000
	s_cmp_eq_u32 s67, 12
	s_cselect_b32 s41, s3, s13
	s_cselect_b32 s40, s7, s12
	s_cselect_b32 s13, s9, s66
	s_cselect_b32 s12, s42, s43
	s_cmp_eq_u32 s67, 12
	s_cselect_b32 s32, 1, 0
	s_andn2_b32 s32, s32, s82
	s_add_i32 s88, 0, 0x14000
	v_add_u32_e32 v160, s79, v174
	v_add_u32_e32 v186, s88, v174
	ds_read_b128 v[148:151], v160
	ds_read_b128 v[152:155], v160 offset:1024
	ds_read_b128 v[156:159], v160 offset:2048
	ds_read_b128 v[160:163], v160 offset:3072
	ds_read_b128 v[164:167], v186
	ds_read_b128 v[178:181], v186 offset:1024
	ds_read_b128 v[182:185], v186 offset:2048
	ds_read_b128 v[186:189], v186 offset:3072
	v_lshl_add_u64 v[232:233], s[10:11], 0, v[144:145]
	s_add_i32 m0, s64, 0xc000
	ds_read_b128 v[190:193], v177
	ds_read_b128 v[194:197], v177 offset:1024
	ds_read_b128 v[198:201], v177 offset:2048
	ds_read_b128 v[212:215], v177 offset:3072
	ds_read_b128 v[216:219], v177 offset:4096
	ds_read_b128 v[220:223], v177 offset:5120
	ds_read_b128 v[224:227], v177 offset:6144
	ds_read_b128 v[228:231], v177 offset:7168
	global_load_lds_dwordx4 v[232:233], off
	v_lshl_add_u64 v[232:233], s[10:11], 0, v[146:147]
	s_add_i32 m0, s64, 0xe000
	s_nop 0
	global_load_lds_dwordx4 v[232:233], off
	s_waitcnt vmcnt(8)
	s_waitcnt lgkmcnt(0)
	s_barrier
	s_waitcnt lgkmcnt(0)
	v_mfma_f32_16x16x32_bf16 v[128:131], v[148:151], v[190:193], v[128:131]
	v_mfma_f32_16x16x32_bf16 v[124:127], v[156:159], v[190:193], v[124:127]
	v_mfma_f32_16x16x32_bf16 v[112:115], v[148:151], v[198:201], v[112:115]
	v_mfma_f32_16x16x32_bf16 v[108:111], v[156:159], v[198:201], v[108:111]
	v_mfma_f32_16x16x32_bf16 v[96:99], v[148:151], v[216:219], v[96:99]
	v_mfma_f32_16x16x32_bf16 v[92:95], v[156:159], v[216:219], v[92:95]
	v_mfma_f32_16x16x32_bf16 v[80:83], v[148:151], v[224:227], v[80:83]
	v_mfma_f32_16x16x32_bf16 v[76:79], v[156:159], v[224:227], v[76:79]
	v_mfma_f32_16x16x32_bf16 v[128:131], v[152:155], v[194:197], v[128:131]
	v_mfma_f32_16x16x32_bf16 v[124:127], v[160:163], v[194:197], v[124:127]
	v_mfma_f32_16x16x32_bf16 v[112:115], v[152:155], v[212:215], v[112:115]
	v_mfma_f32_16x16x32_bf16 v[108:111], v[160:163], v[212:215], v[108:111]
	v_mfma_f32_16x16x32_bf16 v[96:99], v[152:155], v[220:223], v[96:99]
	v_mfma_f32_16x16x32_bf16 v[92:95], v[160:163], v[220:223], v[92:95]
	v_mfma_f32_16x16x32_bf16 v[80:83], v[152:155], v[228:231], v[80:83]
	v_mfma_f32_16x16x32_bf16 v[76:79], v[160:163], v[228:231], v[76:79]
	v_mfma_f32_16x16x32_bf16 v[120:123], v[164:167], v[190:193], v[120:123]
	v_mfma_f32_16x16x32_bf16 v[116:119], v[182:185], v[190:193], v[116:119]
	v_mfma_f32_16x16x32_bf16 v[104:107], v[164:167], v[198:201], v[104:107]
	v_mfma_f32_16x16x32_bf16 v[100:103], v[182:185], v[198:201], v[100:103]
	v_mfma_f32_16x16x32_bf16 v[88:91], v[164:167], v[216:219], v[88:91]
	v_mfma_f32_16x16x32_bf16 v[84:87], v[182:185], v[216:219], v[84:87]
	v_mfma_f32_16x16x32_bf16 v[72:75], v[164:167], v[224:227], v[72:75]
	v_mfma_f32_16x16x32_bf16 v[68:71], v[182:185], v[224:227], v[68:71]
	v_mfma_f32_16x16x32_bf16 v[120:123], v[178:181], v[194:197], v[120:123]
	v_mfma_f32_16x16x32_bf16 v[116:119], v[186:189], v[194:197], v[116:119]
	v_mfma_f32_16x16x32_bf16 v[104:107], v[178:181], v[212:215], v[104:107]
	v_mfma_f32_16x16x32_bf16 v[100:103], v[186:189], v[212:215], v[100:103]
	v_mfma_f32_16x16x32_bf16 v[88:91], v[178:181], v[220:223], v[88:91]
	v_mfma_f32_16x16x32_bf16 v[84:87], v[186:189], v[220:223], v[84:87]
	v_mfma_f32_16x16x32_bf16 v[72:75], v[178:181], v[228:231], v[72:75]
	v_mfma_f32_16x16x32_bf16 v[68:71], v[186:189], v[228:231], v[68:71]
	s_barrier
	s_add_i32 s79, s79, s63
	v_lshl_add_u64 v[232:233], s[12:13], 0, v[136:137]
	s_mov_b32 m0, s79
	ds_read_b128 v[190:193], v177 offset:16384
	ds_read_b128 v[194:197], v177 offset:17408
	ds_read_b128 v[198:201], v177 offset:18432
	ds_read_b128 v[212:215], v177 offset:19456
	ds_read_b128 v[216:219], v177 offset:20480
	ds_read_b128 v[220:223], v177 offset:21504
	ds_read_b128 v[224:227], v177 offset:22528
	ds_read_b128 v[228:231], v177 offset:23552
	s_cmp_lg_u32 s32, 0
	s_cbranch_scc1 .Lbt1_0
	global_load_lds_dwordx4 v[232:233], off

; #define PG8_STAGE(bufoff, gbase, voff) do { _Pragma("unroll") for (int _i = 0; _i < 2; ++_i) \
;         __builtin_amdgcn_global_load_lds((const unsigned*)((const char*)(gbase) + (voff)[_i]), (PG8_LAS unsigned*)(lds + (bufoff) + ldsw + _i * 8192), 16, 0, 0); } while (0)
; #define PG8_LDA(dst, b, h) do { _Pragma("unroll") for (int m = 0; m < 4; ++m) _Pragma("unroll") for (int k = 0; k < 2; ++k) dst[m][k] = *(const PG8_LAS bf16x8*)(lds + PG8_SA(b, h) + aoff + m * 2048 + k * 1024); } while (0)
; #define PG8_LDB(dst, b, h) do { _Pragma("unroll") for (int n = 0; n < 2; ++n) _Pragma("unroll") for (int k = 0; k < 2; ++k) dst[n][k] = *(const PG8_LAS bf16x8*)(lds + PG8_SB(b, h) + boff + n * 2048 + k * 1024); } while (0)
; #define PG8_MMA(ai, bj, At, Bt) do { __builtin_amdgcn_s_setprio(1); _Pragma("unroll") for (int m = 0; m < 4; ++m) _Pragma("unroll") for (int n = 0; n < 2; ++n) _Pragma("unroll") for (int k = 0; k < 2; ++k) \
;         acc[ai][bj][m][n] = __builtin_amdgcn_mfma_f32_16x16x32_bf16(Bt[n][k], At[m][k], acc[ai][bj][m][n], 0, 0, 0); __builtin_amdgcn_s_setprio(0); } while (0)
; #define PG8_WAIT_V(n) asm volatile("s_waitcnt vmcnt(" #n ")" ::: "memory")
; #define PG8_WAIT_L(n) asm volatile("s_waitcnt lgkmcnt(" #n ")" ::: "memory")
; #define PG8_BAR __builtin_amdgcn_s_barrier()
; #define PG8_SCHED __builtin_amdgcn_sched_barrier(0)
; template <class Epi, class Sched, bool ALIGN_EPI = false, bool SP2 = false>
; __device__ __forceinline__ void gemm_phase(PG8_LAS unsigned char* lds, const Gemm g, const Sched& S, const Epi& E, const int tid) {
;     ...
;             PG8_WAIT_V(8); PG8_WAIT_L(0); PG8_BAR; PG8_MMA(1, 0, At, B0); PG8_MMA(1, 1, At, B1); PG8_BAR; PG8_SCHED;
;             PG8_LDB(B0, 1, 0); PG8_LDB(B1, 1, 1); PG8_SCHED; PG8_LDA(At, 1, 0); PG8_STAGE(PG8_SA(0, 1), a2 + hstep, voffA);
.Lbw1_2:
	s_waitcnt lgkmcnt(0)
	s_barrier
	s_waitcnt lgkmcnt(0)
	v_mfma_f32_16x16x32_bf16 v[64:67], v[148:151], v[190:193], v[64:67]
	v_mfma_f32_16x16x32_bf16 v[60:63], v[156:159], v[190:193], v[60:63]
	v_mfma_f32_16x16x32_bf16 v[48:51], v[148:151], v[198:201], v[48:51]
	v_mfma_f32_16x16x32_bf16 v[44:47], v[156:159], v[198:201], v[44:47]
	v_mfma_f32_16x16x32_bf16 v[32:35], v[148:151], v[216:219], v[32:35]
	v_mfma_f32_16x16x32_bf16 v[28:31], v[156:159], v[216:219], v[28:31]
	v_mfma_f32_16x16x32_bf16 v[16:19], v[148:151], v[224:227], v[16:19]
	v_mfma_f32_16x16x32_bf16 v[12:15], v[156:159], v[224:227], v[12:15]
	v_mfma_f32_16x16x32_bf16 v[64:67], v[152:155], v[194:197], v[64:67]
	v_mfma_f32_16x16x32_bf16 v[60:63], v[160:163], v[194:197], v[60:63]
	v_mfma_f32_16x16x32_bf16 v[48:51], v[152:155], v[212:215], v[48:51]
	v_mfma_f32_16x16x32_bf16 v[44:47], v[160:163], v[212:215], v[44:47]
	v_mfma_f32_16x16x32_bf16 v[32:35], v[152:155], v[220:223], v[32:35]
	v_mfma_f32_16x16x32_bf16 v[28:31], v[160:163], v[220:223], v[28:31]
	v_mfma_f32_16x16x32_bf16 v[16:19], v[152:155], v[228:231], v[16:19]
	v_mfma_f32_16x16x32_bf16 v[12:15], v[160:163], v[228:231], v[12:15]
	v_mfma_f32_16x16x32_bf16 v[56:59], v[164:167], v[190:193], v[56:59]
	v_mfma_f32_16x16x32_bf16 v[52:55], v[182:185], v[190:193], v[52:55]
	v_mfma_f32_16x16x32_bf16 v[40:43], v[164:167], v[198:201], v[40:43]
	v_mfma_f32_16x16x32_bf16 v[36:39], v[182:185], v[198:201], v[36:39]
	v_mfma_f32_16x16x32_bf16 v[24:27], v[164:167], v[216:219], v[24:27]
	v_mfma_f32_16x16x32_bf16 v[20:23], v[182:185], v[216:219], v[20:23]
	v_mfma_f32_16x16x32_bf16 v[8:11], v[164:167], v[224:227], v[8:11]
	v_mfma_f32_16x16x32_bf16 v[4:7], v[182:185], v[224:227], v[4:7]
	v_mfma_f32_16x16x32_bf16 v[56:59], v[178:181], v[194:197], v[56:59]
	v_mfma_f32_16x16x32_bf16 v[52:55], v[186:189], v[194:197], v[52:55]
	v_mfma_f32_16x16x32_bf16 v[40:43], v[178:181], v[212:215], v[40:43]
	v_mfma_f32_16x16x32_bf16 v[36:39], v[186:189], v[212:215], v[36:39]
	v_mfma_f32_16x16x32_bf16 v[24:27], v[178:181], v[220:223], v[24:27]
	v_mfma_f32_16x16x32_bf16 v[20:23], v[186:189], v[220:223], v[20:23]
	v_mfma_f32_16x16x32_bf16 v[8:11], v[178:181], v[228:231], v[8:11]
	v_mfma_f32_16x16x32_bf16 v[4:7], v[186:189], v[228:231], v[4:7]
	s_barrier
	s_add_i32 s79, 0, 0x18000
	s_add_i32 s88, 0, 0x1c000
	v_add_u32_e32 v160, s79, v174
	v_add_u32_e32 v186, s88, v174
	ds_read_b128 v[148:151], v160
	ds_read_b128 v[152:155], v160 offset:1024
	ds_read_b128 v[156:159], v160 offset:2048
	ds_read_b128 v[160:163], v160 offset:3072
	ds_read_b128 v[164:167], v186
	ds_read_b128 v[178:181], v186 offset:1024
	ds_read_b128 v[182:185], v186 offset:2048
	ds_read_b128 v[186:189], v186 offset:3072
	s_add_u32 s40, s40, 0x40000
	s_addc_u32 s41, s41, 0
	s_mov_b32 m0, s86
	v_lshl_add_u64 v[240:241], s[40:41], 0, v[134:135]
	ds_read_b128 v[190:193], v177 offset:32768
	ds_read_b128 v[194:197], v177 offset:33792
	ds_read_b128 v[198:201], v177 offset:34816
	ds_read_b128 v[212:215], v177 offset:35840
	ds_read_b128 v[216:219], v177 offset:36864
	ds_read_b128 v[220:223], v177 offset:37888
	ds_read_b128 v[224:227], v177 offset:38912
	ds_read_b128 v[228:231], v177 offset:39936
	s_cmp_lg_u32 s32, 0
	s_cbranch_scc1 .Lbt1_6
	global_load_lds_dwordx4 v[240:241], off

; #define PG8_STAGE(bufoff, gbase, voff) do { _Pragma("unroll") for (int _i = 0; _i < 2; ++_i) \
;         __builtin_amdgcn_global_load_lds((const unsigned*)((const char*)(gbase) + (voff)[_i]), (PG8_LAS unsigned*)(lds + (bufoff) + ldsw + _i * 8192), 16, 0, 0); } while (0)
; #define PG8_LDA(dst, b, h) do { _Pragma("unroll") for (int m = 0; m < 4; ++m) _Pragma("unroll") for (int k = 0; k < 2; ++k) dst[m][k] = *(const PG8_LAS bf16x8*)(lds + PG8_SA(b, h) + aoff + m * 2048 + k * 1024); } while (0)
; #define PG8_MMA(ai, bj, At, Bt) do { __builtin_amdgcn_s_setprio(1); _Pragma("unroll") for (int m = 0; m < 4; ++m) _Pragma("unroll") for (int n = 0; n < 2; ++n) _Pragma("unroll") for (int k = 0; k < 2; ++k) \
;         acc[ai][bj][m][n] = __builtin_amdgcn_mfma_f32_16x16x32_bf16(Bt[n][k], At[m][k], acc[ai][bj][m][n], 0, 0, 0); __builtin_amdgcn_s_setprio(0); } while (0)
; #define PG8_WAIT_V(n) asm volatile("s_waitcnt vmcnt(" #n ")" ::: "memory")
; #define PG8_WAIT_L(n) asm volatile("s_waitcnt lgkmcnt(" #n ")" ::: "memory")
; #define PG8_BAR __builtin_amdgcn_s_barrier()
; #define PG8_SCHED __builtin_amdgcn_sched_barrier(0)
; template <class Epi, class Sched, bool ALIGN_EPI = false, bool SP2 = false>
; __device__ __forceinline__ void gemm_phase(PG8_LAS unsigned char* lds, const Gemm g, const Sched& S, const Epi& E, const int tid) {
;     ...
;             PG8_WAIT_V(8); PG8_WAIT_L(0); PG8_BAR; PG8_MMA(0, 0, At, B0); PG8_MMA(0, 1, At, B1); PG8_BAR; PG8_SCHED;
;             PG8_LDA(At, 1, 1); PG8_STAGE(PG8_SB(1, 0), b3, voffB); PG8_STAGE(PG8_SB(1, 1), b3 + hstepB, voffB); PG8_STAGE(PG8_SA(1, 0), a3, voffA);
.Lbw1_0:
	s_waitcnt lgkmcnt(0)
	s_barrier
	s_waitcnt lgkmcnt(0)
	v_mfma_f32_16x16x32_bf16 v[128:131], v[148:151], v[190:193], v[128:131]
	v_mfma_f32_16x16x32_bf16 v[124:127], v[156:159], v[190:193], v[124:127]
	v_mfma_f32_16x16x32_bf16 v[112:115], v[148:151], v[198:201], v[112:115]
	v_mfma_f32_16x16x32_bf16 v[108:111], v[156:159], v[198:201], v[108:111]
	v_mfma_f32_16x16x32_bf16 v[96:99], v[148:151], v[216:219], v[96:99]
	v_mfma_f32_16x16x32_bf16 v[92:95], v[156:159], v[216:219], v[92:95]
	v_mfma_f32_16x16x32_bf16 v[80:83], v[148:151], v[224:227], v[80:83]
	v_mfma_f32_16x16x32_bf16 v[76:79], v[156:159], v[224:227], v[76:79]
	v_mfma_f32_16x16x32_bf16 v[128:131], v[152:155], v[194:197], v[128:131]
	v_mfma_f32_16x16x32_bf16 v[124:127], v[160:163], v[194:197], v[124:127]
	v_mfma_f32_16x16x32_bf16 v[112:115], v[152:155], v[212:215], v[112:115]
	v_mfma_f32_16x16x32_bf16 v[108:111], v[160:163], v[212:215], v[108:111]
	v_mfma_f32_16x16x32_bf16 v[96:99], v[152:155], v[220:223], v[96:99]
	v_mfma_f32_16x16x32_bf16 v[92:95], v[160:163], v[220:223], v[92:95]
	v_mfma_f32_16x16x32_bf16 v[80:83], v[152:155], v[228:231], v[80:83]
	v_mfma_f32_16x16x32_bf16 v[76:79], v[160:163], v[228:231], v[76:79]
	v_mfma_f32_16x16x32_bf16 v[120:123], v[164:167], v[190:193], v[120:123]
	v_mfma_f32_16x16x32_bf16 v[116:119], v[182:185], v[190:193], v[116:119]
	v_mfma_f32_16x16x32_bf16 v[104:107], v[164:167], v[198:201], v[104:107]
	v_mfma_f32_16x16x32_bf16 v[100:103], v[182:185], v[198:201], v[100:103]
	v_mfma_f32_16x16x32_bf16 v[88:91], v[164:167], v[216:219], v[88:91]
	v_mfma_f32_16x16x32_bf16 v[84:87], v[182:185], v[216:219], v[84:87]
	v_mfma_f32_16x16x32_bf16 v[72:75], v[164:167], v[224:227], v[72:75]
	v_mfma_f32_16x16x32_bf16 v[68:71], v[182:185], v[224:227], v[68:71]
	v_mfma_f32_16x16x32_bf16 v[120:123], v[178:181], v[194:197], v[120:123]
	v_mfma_f32_16x16x32_bf16 v[116:119], v[186:189], v[194:197], v[116:119]
	v_mfma_f32_16x16x32_bf16 v[104:107], v[178:181], v[212:215], v[104:107]
	v_mfma_f32_16x16x32_bf16 v[100:103], v[186:189], v[212:215], v[100:103]
	v_mfma_f32_16x16x32_bf16 v[88:91], v[178:181], v[220:223], v[88:91]
	v_mfma_f32_16x16x32_bf16 v[84:87], v[186:189], v[220:223], v[84:87]
	v_mfma_f32_16x16x32_bf16 v[72:75], v[178:181], v[228:231], v[72:75]
	v_mfma_f32_16x16x32_bf16 v[68:71], v[186:189], v[228:231], v[68:71]
	s_barrier
	s_add_i32 s40, s79, s63
	v_lshl_add_u64 v[232:233], v[232:233], 0, s[52:53]
	s_mov_b32 m0, s40
	ds_read_b128 v[190:193], v177 offset:49152
	ds_read_b128 v[194:197], v177 offset:50176
	ds_read_b128 v[198:201], v177 offset:51200
	ds_read_b128 v[212:215], v177 offset:52224
	ds_read_b128 v[216:219], v177 offset:53248
	ds_read_b128 v[220:223], v177 offset:54272
	ds_read_b128 v[224:227], v177 offset:55296
	ds_read_b128 v[228:231], v177 offset:56320
	s_cmp_lg_u32 s32, 0
	s_cbranch_scc1 .Lbt1_8
	global_load_lds_dwordx4 v[232:233], off

; #define PG8_STAGE(bufoff, gbase, voff) do { _Pragma("unroll") for (int _i = 0; _i < 2; ++_i) \
;         __builtin_amdgcn_global_load_lds((const unsigned*)((const char*)(gbase) + (voff)[_i]), (PG8_LAS unsigned*)(lds + (bufoff) + ldsw + _i * 8192), 16, 0, 0); } while (0)
; #define PG8_LDA(dst, b, h) do { _Pragma("unroll") for (int m = 0; m < 4; ++m) _Pragma("unroll") for (int k = 0; k < 2; ++k) dst[m][k] = *(const PG8_LAS bf16x8*)(lds + PG8_SA(b, h) + aoff + m * 2048 + k * 1024); } while (0)
; #define PG8_MMA(ai, bj, At, Bt) do { __builtin_amdgcn_s_setprio(1); _Pragma("unroll") for (int m = 0; m < 4; ++m) _Pragma("unroll") for (int n = 0; n < 2; ++n) _Pragma("unroll") for (int k = 0; k < 2; ++k) \
;         acc[ai][bj][m][n] = __builtin_amdgcn_mfma_f32_16x16x32_bf16(Bt[n][k], At[m][k], acc[ai][bj][m][n], 0, 0, 0); __builtin_amdgcn_s_setprio(0); } while (0)
; #define PG8_WAIT_V(n) asm volatile("s_waitcnt vmcnt(" #n ")" ::: "memory")
; #define PG8_WAIT_L(n) asm volatile("s_waitcnt lgkmcnt(" #n ")" ::: "memory")
; #define PG8_BAR __builtin_amdgcn_s_barrier()
; #define PG8_SCHED __builtin_amdgcn_sched_barrier(0)
; template <class Epi, class Sched, bool ALIGN_EPI = false, bool SP2 = false>
; __device__ __forceinline__ void gemm_phase(PG8_LAS unsigned char* lds, const Gemm g, const Sched& S, const Epi& E, const int tid) {
;     ...
;         for (int t = 0; t < nt; t += 2) {
;             const bool last = (t == nt - 2);
;             const char* a1 = cA + (size_t)(t + 1) * kstep;
;             const char* a2 = last ? nA : cA + (size_t)(t + 2) * kstep; const char* b2 = last ? nB : cB + (size_t)(t + 2) * kstep;
;             const char* a3 = a2 + kstep; const char* b3 = b2 + kstep;
;     ...
;             PG8_LDA(At, 1, 1); PG8_STAGE(PG8_SB(1, 0), b3, voffB); PG8_STAGE(PG8_SB(1, 1), b3 + hstepB, voffB); PG8_STAGE(PG8_SA(1, 0), a3, voffA);
;             PG8_WAIT_V(8); PG8_WAIT_L(0); PG8_BAR; PG8_MMA(1, 0, At, B0); PG8_MMA(1, 1, At, B1); PG8_BAR; PG8_SCHED;
.Lbt1_13:
	s_waitcnt vmcnt(8)
	s_waitcnt lgkmcnt(0)
	s_barrier
	s_waitcnt lgkmcnt(0)
	v_mfma_f32_16x16x32_bf16 v[64:67], v[148:151], v[190:193], v[64:67]
	v_mfma_f32_16x16x32_bf16 v[60:63], v[156:159], v[190:193], v[60:63]
	v_mfma_f32_16x16x32_bf16 v[48:51], v[148:151], v[198:201], v[48:51]
	v_mfma_f32_16x16x32_bf16 v[44:47], v[156:159], v[198:201], v[44:47]
	v_mfma_f32_16x16x32_bf16 v[32:35], v[148:151], v[216:219], v[32:35]
	v_mfma_f32_16x16x32_bf16 v[28:31], v[156:159], v[216:219], v[28:31]
	v_mfma_f32_16x16x32_bf16 v[16:19], v[148:151], v[224:227], v[16:19]
	v_mfma_f32_16x16x32_bf16 v[12:15], v[156:159], v[224:227], v[12:15]
	v_mfma_f32_16x16x32_bf16 v[64:67], v[152:155], v[194:197], v[64:67]
	v_mfma_f32_16x16x32_bf16 v[60:63], v[160:163], v[194:197], v[60:63]
	v_mfma_f32_16x16x32_bf16 v[48:51], v[152:155], v[212:215], v[48:51]
	v_mfma_f32_16x16x32_bf16 v[44:47], v[160:163], v[212:215], v[44:47]
	v_mfma_f32_16x16x32_bf16 v[32:35], v[152:155], v[220:223], v[32:35]
	v_mfma_f32_16x16x32_bf16 v[28:31], v[160:163], v[220:223], v[28:31]
	v_mfma_f32_16x16x32_bf16 v[16:19], v[152:155], v[228:231], v[16:19]
	v_mfma_f32_16x16x32_bf16 v[12:15], v[160:163], v[228:231], v[12:15]
	v_mfma_f32_16x16x32_bf16 v[56:59], v[164:167], v[190:193], v[56:59]
	v_mfma_f32_16x16x32_bf16 v[52:55], v[182:185], v[190:193], v[52:55]
	v_mfma_f32_16x16x32_bf16 v[40:43], v[164:167], v[198:201], v[40:43]
	v_mfma_f32_16x16x32_bf16 v[36:39], v[182:185], v[198:201], v[36:39]
	v_mfma_f32_16x16x32_bf16 v[24:27], v[164:167], v[216:219], v[24:27]
	v_mfma_f32_16x16x32_bf16 v[20:23], v[182:185], v[216:219], v[20:23]
	v_mfma_f32_16x16x32_bf16 v[8:11], v[164:167], v[224:227], v[8:11]
	v_mfma_f32_16x16x32_bf16 v[4:7], v[182:185], v[224:227], v[4:7]
	v_mfma_f32_16x16x32_bf16 v[56:59], v[178:181], v[194:197], v[56:59]
	v_mfma_f32_16x16x32_bf16 v[52:55], v[186:189], v[194:197], v[52:55]
	v_mfma_f32_16x16x32_bf16 v[40:43], v[178:181], v[212:215], v[40:43]
	v_mfma_f32_16x16x32_bf16 v[36:39], v[186:189], v[212:215], v[36:39]
	v_mfma_f32_16x16x32_bf16 v[24:27], v[178:181], v[220:223], v[24:27]
	v_mfma_f32_16x16x32_bf16 v[20:23], v[186:189], v[220:223], v[20:23]
	v_mfma_f32_16x16x32_bf16 v[8:11], v[178:181], v[228:231], v[8:11]
	v_mfma_f32_16x16x32_bf16 v[4:7], v[186:189], v[228:231], v[4:7]
	s_barrier
	s_add_i32 s67, s67, 2
	s_add_u32 s10, s10, 0x100
	s_addc_u32 s11, s11, 0
	s_add_u32 s43, s43, 0x100
	s_addc_u32 s66, s66, 0
	s_cmp_gt_u32 s67, 13
	s_cbranch_scc0 .LBB0_616
	s_and_b64 vcc, exec, s[36:37]
	s_cbranch_vccz .LBB0_619
	s_barrier

; DI float bf_lo(unsigned u) { return __uint_as_float(u << 16); }
; DI float bf_hi(unsigned u) { return __uint_as_float(u & 0xffff0000u); }
; #define PG8_STAGE(bufoff, gbase, voff) do { _Pragma("unroll") for (int _i = 0; _i < 2; ++_i) \
;         __builtin_amdgcn_global_load_lds((const unsigned*)((const char*)(gbase) + (voff)[_i]), (PG8_LAS unsigned*)(lds + (bufoff) + ldsw + _i * 8192), 16, 0, 0); } while (0)
; #define PG8_WAIT_V(n) asm volatile("s_waitcnt vmcnt(" #n ")" ::: "memory")
; #define PG8_BAR __builtin_amdgcn_s_barrier()
;     DI void init_finish(f32x4 (&acc)[2][2][4][2], const u32x4 (&w)[R8::HAS_PRE ? 16 : 1]) const {
;         if constexpr (R8::HAS_PRE) {
; #pragma unroll
;             for (int ai = 0; ai < 2; ++ai)
; #pragma unroll
;                 for (int m = 0; m < 4; ++m)
; #pragma unroll
;                     for (int bj = 0; bj < 2; ++bj) { const u32x4 v = w[(ai * 4 + m) * 2 + bj];
;                         acc[ai][bj][m][0] = (f32x4){bf_lo(v.x), bf_hi(v.x), bf_lo(v.y), bf_hi(v.y)}; acc[ai][bj][m][1] = (f32x4){bf_lo(v.z), bf_hi(v.z), bf_lo(v.w), bf_hi(v.w)}; }
;         }
;     }
; template <class Epi, class Sched, bool ALIGN_EPI = false, bool SP2 = false>
; __device__ __forceinline__ void gemm_phase(PG8_LAS unsigned char* lds, const Gemm g, const Sched& S, const Epi& E, const int tid) {
;     ...
;     if constexpr (SP2) {
;         PG8_STAGE(PG8_SB(0, 0), cB, voffB); PG8_STAGE(PG8_SB(0, 1), cB + hstepB, voffB); PG8_STAGE(PG8_SA(0, 0), cA, voffA); PG8_STAGE(PG8_SA(0, 1), cA + hstep, voffA);
;         if (wr == 1) PG8_BAR;
;         PG8_WAIT_V(2); PG8_BAR;
;         PG8_STAGE(PG8_SB(1, 0), cB + kstep, voffB); PG8_STAGE(PG8_SA(1, 0), cA + kstep, voffA); PG8_STAGE(PG8_SB(1, 1), cB + hstepB + kstep, voffB);
;         PG8_WAIT_V(6); PG8_BAR;
;     } else {
;         PG8_STAGE(PG8_SB(0, 0), cB, voffB); PG8_STAGE(PG8_SA(0, 0), cA, voffA); PG8_STAGE(PG8_SB(0, 1), cB + hstepB, voffB); PG8_STAGE(PG8_SA(0, 1), cA + hstep, voffA);
;         if (wr == 1) PG8_BAR;
;         PG8_WAIT_V(4); PG8_BAR;
;         PG8_STAGE(PG8_SB(1, 0), cB + kstep, voffB); PG8_STAGE(PG8_SA(1, 0), cA + kstep, voffA); PG8_STAGE(PG8_SB(1, 1), cB + hstepB + kstep, voffB);
;         PG8_WAIT_V(6); PG8_BAR;
;     }
;     if constexpr (Epi::HAS_INIT) E.init_finish(acc, iw_);
.LBB0_973:
	v_or_b32_e32 v157, s15, v152
	v_lshlrev_b32_e32 v76, 6, v157
	v_lshlrev_b32_e32 v77, 4, v146
	s_movk_i32 s15, 0x3c0
	v_lshlrev_b32_e32 v78, 2, v157
	v_and_or_b32 v76, v76, s15, v77
	s_lshl_b32 s5, s5, 13
	v_and_b32_e32 v78, 32, v78
	v_bitop3_b32 v149, v76, s5, v78 bitop3:0xde
	v_lshl_or_b32 v76, v152, 6, v77
	v_lshlrev_b32_e32 v77, 2, v152
	s_add_i32 m0, s29, 0x18000
	v_lshl_add_u64 v[74:75], v[74:75], 0, s[52:53]
	s_lshl_b32 s4, s4, 12
	v_and_b32_e32 v77, 32, v77
	s_waitcnt vmcnt(2)
	s_barrier
	global_load_lds_dwordx4 v[74:75], off
	v_lshl_add_u64 v[72:73], v[72:73], 0, s[52:53]
	s_add_i32 m0, s29, 0x1a000
	s_add_i32 s64, s29, 0x8000
	s_add_i32 s65, s29, 0xa000
	v_bitop3_b32 v158, s4, v76, v77 bitop3:0xf6
	global_load_lds_dwordx4 v[72:73], off
	v_lshl_add_u64 v[68:69], v[68:69], 0, s[52:53]
	s_mov_b32 m0, s64
	s_add_u32 s4, s36, 0x10080
	global_load_lds_dwordx4 v[68:69], off
	v_lshl_add_u64 v[68:69], v[70:71], 0, s[52:53]
	s_mov_b32 m0, s65
	s_addc_u32 s5, s37, 0
	global_load_lds_dwordx4 v[68:69], off
	s_add_i32 m0, s29, 0x1c000
	v_lshl_add_u64 v[68:69], s[4:5], 0, v[136:137]
	global_load_lds_dwordx4 v[68:69], off
	v_lshl_add_u64 v[68:69], s[4:5], 0, v[140:141]
	s_add_i32 m0, s29, 0x1e000
	v_cmp_eq_u32_e64 s[4:5], 0, v146
	global_load_lds_dwordx4 v[68:69], off
	v_lshlrev_b32_e32 v146, 14, v142
	v_and_b32_e32 v146, 0xffff8000, v146
	v_lshl_add_u32 v143, v143, 11, v146
	v_and_b32_e32 v142, 1, v142
	v_lshl_or_b32 v142, v142, 6, v143
	v_lshl_add_u32 v142, v144, 1, v142
	v_lshlrev_b32_e32 v144, 14, v145
	v_and_b32_e32 v144, 0xffff8000, v144
	s_waitcnt vmcnt(6)
	v_lshl_add_u32 v144, v147, 11, v144
	v_and_b32_e32 v145, 1, v145
	s_cmpk_lt_u32 s14, 0x100
	v_lshl_or_b32 v144, v145, 6, v144
	s_waitcnt vmcnt(0)
	v_lshlrev_b32_e32 v120, 16, v64
	v_and_b32_e32 v121, 0xffff0000, v64
	v_lshlrev_b32_e32 v122, 16, v65
	v_and_b32_e32 v123, 0xffff0000, v65
	v_lshlrev_b32_e32 v128, 16, v66
	v_and_b32_e32 v129, 0xffff0000, v66
	v_lshlrev_b32_e32 v130, 16, v67
	v_and_b32_e32 v131, 0xffff0000, v67
	v_lshlrev_b32_e32 v116, 16, v56
	v_and_b32_e32 v117, 0xffff0000, v56
	v_lshlrev_b32_e32 v118, 16, v57
	v_and_b32_e32 v119, 0xffff0000, v57
	v_lshlrev_b32_e32 v124, 16, v58
	v_and_b32_e32 v125, 0xffff0000, v58
	v_lshlrev_b32_e32 v126, 16, v59
	v_and_b32_e32 v127, 0xffff0000, v59
	v_lshlrev_b32_e32 v100, 16, v60
	v_and_b32_e32 v101, 0xffff0000, v60
	v_lshlrev_b32_e32 v102, 16, v61
	v_and_b32_e32 v103, 0xffff0000, v61
	v_lshlrev_b32_e32 v108, 16, v62
	v_and_b32_e32 v109, 0xffff0000, v62
	v_lshlrev_b32_e32 v110, 16, v63
	v_and_b32_e32 v111, 0xffff0000, v63
	v_lshlrev_b32_e32 v104, 16, v48
	v_and_b32_e32 v105, 0xffff0000, v48
	v_lshlrev_b32_e32 v106, 16, v49
	v_and_b32_e32 v107, 0xffff0000, v49
	v_lshlrev_b32_e32 v112, 16, v50
	v_and_b32_e32 v113, 0xffff0000, v50
	v_lshlrev_b32_e32 v114, 16, v51
	v_and_b32_e32 v115, 0xffff0000, v51
	v_lshlrev_b32_e32 v84, 16, v52
	v_and_b32_e32 v85, 0xffff0000, v52
	v_lshlrev_b32_e32 v86, 16, v53
	v_and_b32_e32 v87, 0xffff0000, v53
	v_lshlrev_b32_e32 v92, 16, v54
	v_and_b32_e32 v93, 0xffff0000, v54
	v_lshlrev_b32_e32 v94, 16, v55
	v_and_b32_e32 v95, 0xffff0000, v55
	v_lshlrev_b32_e32 v88, 16, v40
	v_and_b32_e32 v89, 0xffff0000, v40
	v_lshlrev_b32_e32 v90, 16, v41
	v_and_b32_e32 v91, 0xffff0000, v41
	v_lshlrev_b32_e32 v96, 16, v42
	v_and_b32_e32 v97, 0xffff0000, v42
	v_lshlrev_b32_e32 v98, 16, v43
	v_and_b32_e32 v99, 0xffff0000, v43
	v_lshlrev_b32_e32 v68, 16, v44
	v_and_b32_e32 v69, 0xffff0000, v44
	v_lshlrev_b32_e32 v70, 16, v45
	v_and_b32_e32 v71, 0xffff0000, v45
	v_lshlrev_b32_e32 v76, 16, v46
	v_and_b32_e32 v77, 0xffff0000, v46
	v_lshlrev_b32_e32 v78, 16, v47
	v_and_b32_e32 v79, 0xffff0000, v47
	v_lshlrev_b32_e32 v72, 16, v36
	v_and_b32_e32 v73, 0xffff0000, v36
	v_lshlrev_b32_e32 v74, 16, v37
	v_and_b32_e32 v75, 0xffff0000, v37
	v_lshlrev_b32_e32 v80, 16, v38
	v_and_b32_e32 v81, 0xffff0000, v38
	v_lshlrev_b32_e32 v82, 16, v39
	v_and_b32_e32 v83, 0xffff0000, v39
	v_lshlrev_b32_e32 v52, 16, v32
	v_and_b32_e32 v53, 0xffff0000, v32
	v_lshlrev_b32_e32 v54, 16, v33
	v_and_b32_e32 v55, 0xffff0000, v33
	v_lshlrev_b32_e32 v60, 16, v34
	v_and_b32_e32 v61, 0xffff0000, v34
	v_lshlrev_b32_e32 v62, 16, v35
	v_and_b32_e32 v63, 0xffff0000, v35
	v_lshlrev_b32_e32 v56, 16, v28
	v_and_b32_e32 v57, 0xffff0000, v28
	v_lshlrev_b32_e32 v58, 16, v29
	v_and_b32_e32 v59, 0xffff0000, v29
	v_lshlrev_b32_e32 v64, 16, v30
	v_and_b32_e32 v65, 0xffff0000, v30
	v_lshlrev_b32_e32 v66, 16, v31
	v_and_b32_e32 v67, 0xffff0000, v31
	v_lshlrev_b32_e32 v36, 16, v24
	v_and_b32_e32 v37, 0xffff0000, v24
	v_lshlrev_b32_e32 v38, 16, v25
	v_and_b32_e32 v39, 0xffff0000, v25
	v_lshlrev_b32_e32 v44, 16, v26
	v_and_b32_e32 v45, 0xffff0000, v26
	v_lshlrev_b32_e32 v46, 16, v27
	v_and_b32_e32 v47, 0xffff0000, v27
	v_lshlrev_b32_e32 v40, 16, v20
	v_and_b32_e32 v41, 0xffff0000, v20
	v_lshlrev_b32_e32 v42, 16, v21
	v_and_b32_e32 v43, 0xffff0000, v21
	v_lshlrev_b32_e32 v48, 16, v22
	v_and_b32_e32 v49, 0xffff0000, v22
	v_lshlrev_b32_e32 v50, 16, v23
	v_and_b32_e32 v51, 0xffff0000, v23
	v_lshlrev_b32_e32 v20, 16, v12
	v_and_b32_e32 v21, 0xffff0000, v12
	v_lshlrev_b32_e32 v22, 16, v13
	v_and_b32_e32 v23, 0xffff0000, v13
	v_lshlrev_b32_e32 v28, 16, v14
	v_and_b32_e32 v29, 0xffff0000, v14
	v_lshlrev_b32_e32 v30, 16, v15
	v_and_b32_e32 v31, 0xffff0000, v15
	v_lshlrev_b32_e32 v24, 16, v4
	v_and_b32_e32 v25, 0xffff0000, v4
	v_lshlrev_b32_e32 v26, 16, v5
	v_and_b32_e32 v27, 0xffff0000, v5
	v_lshlrev_b32_e32 v32, 16, v6
	v_and_b32_e32 v33, 0xffff0000, v6
	v_lshlrev_b32_e32 v34, 16, v7
	v_and_b32_e32 v35, 0xffff0000, v7
	v_lshlrev_b32_e32 v4, 16, v8
	v_and_b32_e32 v5, 0xffff0000, v8
	v_lshlrev_b32_e32 v6, 16, v9
	v_and_b32_e32 v7, 0xffff0000, v9
	v_lshlrev_b32_e32 v12, 16, v10
	v_and_b32_e32 v13, 0xffff0000, v10
	v_lshlrev_b32_e32 v14, 16, v11
	v_and_b32_e32 v15, 0xffff0000, v11
	v_lshlrev_b32_e32 v8, 16, v16
	v_and_b32_e32 v9, 0xffff0000, v16
	v_lshlrev_b32_e32 v10, 16, v17
	v_and_b32_e32 v11, 0xffff0000, v17
	v_lshlrev_b32_e32 v16, 16, v18
	v_and_b32_e32 v17, 0xffff0000, v18
	v_lshlrev_b32_e32 v18, 16, v19
	v_and_b32_e32 v19, 0xffff0000, v19
	s_cselect_b64 s[14:15], -1, 0
	s_mov_b32 s66, 0
	s_lshl_b32 s67, s27, 3
	v_or_b32_e32 v159, s54, v156
	v_mov_b32_e32 v143, v2
	v_lshl_add_u32 v144, v148, 1, v144
	v_mov_b32_e32 v145, v2
	v_add_u32_e32 v160, 0, v149
	s_barrier
	v_readfirstlane_b32 s98, v0
	s_nop 3
	s_and_b32 s98, s98, 0x3ff
	s_lshr_b32 s98, s98, 6
	s_cmp_ge_u32 s98, 4
	s_cbranch_scc0 .Lprio_done2
	s_setprio 1
; DI float bf_lo(unsigned u) { return __uint_as_float(u << 16); }
; DI float bf_hi(unsigned u) { return __uint_as_float(u & 0xffff0000u); }
;     DI void init_finish(f32x4 (&acc)[2][2][4][2], const u32x4 (&w)[R8::HAS_PRE ? 16 : 1]) const {
;         if constexpr (R8::HAS_PRE) {
; #pragma unroll
;             for (int ai = 0; ai < 2; ++ai)
; #pragma unroll
;                 for (int m = 0; m < 4; ++m)
; #pragma unroll
;                     for (int bj = 0; bj < 2; ++bj) { const u32x4 v = w[(ai * 4 + m) * 2 + bj];
;                         acc[ai][bj][m][0] = (f32x4){bf_lo(v.x), bf_hi(v.x), bf_lo(v.y), bf_hi(v.y)}; acc[ai][bj][m][1] = (f32x4){bf_lo(v.z), bf_hi(v.z), bf_lo(v.w), bf_hi(v.w)}; }
;         }
;     }
;     DI void init(f32x4 (&acc)[2][2][4][2], const Unit& u, int wr, int wc, int fr, int fq) const { u32x4 w[R8::HAS_PRE ? 16 : 1]; init_issue(w, u, wr, wc, fr, fq); init_finish(acc, w); }
; template <class Epi, class Sched, bool ALIGN_EPI = false, bool SP2 = false>
; __device__ __forceinline__ void gemm_phase(PG8_LAS unsigned char* lds, const Gemm g, const Sched& S, const Epi& E, const int tid) {
;     ...
;         if constexpr (!Epi::AFTER_DRAIN) { E(acc, cur, wr, wc, fr, fq); S.done(cur); }
;         if (!has_next) break;
;         if constexpr (Epi::HAS_INIT) E.init(acc, nxt, wr, wc, fr, fq);
.Lprio_done2:
	s_branch .LBB0_976
.LBB0_974:
	s_waitcnt vmcnt(0)
	v_lshlrev_b32_e32 v120, 16, v66
	v_and_b32_e32 v121, 0xffff0000, v66
	v_lshlrev_b32_e32 v122, 16, v67
	v_and_b32_e32 v123, 0xffff0000, v67
	v_lshlrev_b32_e32 v128, 16, v68
	v_and_b32_e32 v129, 0xffff0000, v68
	v_lshlrev_b32_e32 v130, 16, v69
	v_and_b32_e32 v131, 0xffff0000, v69
	v_lshlrev_b32_e32 v116, 16, v58
	v_and_b32_e32 v117, 0xffff0000, v58
	v_lshlrev_b32_e32 v118, 16, v59
	v_and_b32_e32 v119, 0xffff0000, v59
	v_lshlrev_b32_e32 v124, 16, v60
	v_and_b32_e32 v125, 0xffff0000, v60
	v_lshlrev_b32_e32 v126, 16, v61
	v_and_b32_e32 v127, 0xffff0000, v61
	v_lshlrev_b32_e32 v100, 16, v62
	v_and_b32_e32 v101, 0xffff0000, v62
	v_lshlrev_b32_e32 v102, 16, v63
	v_and_b32_e32 v103, 0xffff0000, v63
	v_lshlrev_b32_e32 v108, 16, v64
	v_and_b32_e32 v109, 0xffff0000, v64
	v_lshlrev_b32_e32 v110, 16, v65
	v_and_b32_e32 v111, 0xffff0000, v65
	v_lshlrev_b32_e32 v104, 16, v50
	v_and_b32_e32 v105, 0xffff0000, v50
	v_lshlrev_b32_e32 v106, 16, v51
	v_and_b32_e32 v107, 0xffff0000, v51
	v_lshlrev_b32_e32 v112, 16, v52
	v_and_b32_e32 v113, 0xffff0000, v52
	v_lshlrev_b32_e32 v114, 16, v53
	v_and_b32_e32 v115, 0xffff0000, v53
	v_lshlrev_b32_e32 v84, 16, v54
	v_and_b32_e32 v85, 0xffff0000, v54
	v_lshlrev_b32_e32 v86, 16, v55
	v_and_b32_e32 v87, 0xffff0000, v55
	v_lshlrev_b32_e32 v92, 16, v56
	v_and_b32_e32 v93, 0xffff0000, v56
	v_lshlrev_b32_e32 v94, 16, v57
	v_and_b32_e32 v95, 0xffff0000, v57
	v_lshlrev_b32_e32 v88, 16, v42
	v_and_b32_e32 v89, 0xffff0000, v42
	v_lshlrev_b32_e32 v90, 16, v43
	v_and_b32_e32 v91, 0xffff0000, v43
	v_lshlrev_b32_e32 v96, 16, v44
	v_and_b32_e32 v97, 0xffff0000, v44
	v_lshlrev_b32_e32 v98, 16, v45
	v_and_b32_e32 v99, 0xffff0000, v45
	v_lshlrev_b32_e32 v68, 16, v46
	v_and_b32_e32 v69, 0xffff0000, v46
	v_lshlrev_b32_e32 v70, 16, v47
	v_and_b32_e32 v71, 0xffff0000, v47
	v_lshlrev_b32_e32 v76, 16, v48
	v_and_b32_e32 v77, 0xffff0000, v48
	v_lshlrev_b32_e32 v78, 16, v49
	v_and_b32_e32 v79, 0xffff0000, v49
	v_lshlrev_b32_e32 v72, 16, v34
	v_and_b32_e32 v73, 0xffff0000, v34
	v_lshlrev_b32_e32 v74, 16, v35
	v_and_b32_e32 v75, 0xffff0000, v35
	v_lshlrev_b32_e32 v80, 16, v36
	v_and_b32_e32 v81, 0xffff0000, v36
	v_lshlrev_b32_e32 v82, 16, v37
	v_and_b32_e32 v83, 0xffff0000, v37
	v_lshlrev_b32_e32 v52, 16, v38
	v_and_b32_e32 v53, 0xffff0000, v38
	v_lshlrev_b32_e32 v54, 16, v39
	v_and_b32_e32 v55, 0xffff0000, v39
	v_lshlrev_b32_e32 v60, 16, v40
	v_and_b32_e32 v61, 0xffff0000, v40
	v_lshlrev_b32_e32 v62, 16, v41
	v_and_b32_e32 v63, 0xffff0000, v41
	v_lshlrev_b32_e32 v56, 16, v26
	v_and_b32_e32 v57, 0xffff0000, v26
	v_lshlrev_b32_e32 v58, 16, v27
	v_and_b32_e32 v59, 0xffff0000, v27
	v_lshlrev_b32_e32 v64, 16, v28
	v_and_b32_e32 v65, 0xffff0000, v28
	v_lshlrev_b32_e32 v66, 16, v29
	v_and_b32_e32 v67, 0xffff0000, v29
	v_lshlrev_b32_e32 v36, 16, v30
	v_and_b32_e32 v37, 0xffff0000, v30
	v_lshlrev_b32_e32 v38, 16, v31
	v_and_b32_e32 v39, 0xffff0000, v31
	v_lshlrev_b32_e32 v44, 16, v32
	v_and_b32_e32 v45, 0xffff0000, v32
	v_lshlrev_b32_e32 v46, 16, v33
	v_and_b32_e32 v47, 0xffff0000, v33
	v_lshlrev_b32_e32 v40, 16, v12
	v_and_b32_e32 v41, 0xffff0000, v12
	v_lshlrev_b32_e32 v42, 16, v13
	v_and_b32_e32 v43, 0xffff0000, v13
	v_lshlrev_b32_e32 v48, 16, v14
	v_and_b32_e32 v49, 0xffff0000, v14
	v_lshlrev_b32_e32 v50, 16, v15
	v_and_b32_e32 v51, 0xffff0000, v15
	v_lshlrev_b32_e32 v20, 16, v22
	v_and_b32_e32 v21, 0xffff0000, v22
	v_lshlrev_b32_e32 v22, 16, v23
	v_and_b32_e32 v23, 0xffff0000, v23
	v_lshlrev_b32_e32 v28, 16, v24
	v_and_b32_e32 v29, 0xffff0000, v24
	v_lshlrev_b32_e32 v30, 16, v25
	v_and_b32_e32 v31, 0xffff0000, v25
	v_lshlrev_b32_e32 v24, 16, v4
	v_and_b32_e32 v25, 0xffff0000, v4
	v_lshlrev_b32_e32 v26, 16, v5
	v_and_b32_e32 v27, 0xffff0000, v5
	v_lshlrev_b32_e32 v32, 16, v6
	v_and_b32_e32 v33, 0xffff0000, v6
	v_lshlrev_b32_e32 v34, 16, v7
	v_and_b32_e32 v35, 0xffff0000, v7
	v_lshlrev_b32_e32 v4, 16, v8
	v_and_b32_e32 v5, 0xffff0000, v8
	v_lshlrev_b32_e32 v6, 16, v9
	v_and_b32_e32 v7, 0xffff0000, v9
	v_lshlrev_b32_e32 v12, 16, v10
	v_and_b32_e32 v13, 0xffff0000, v10
	v_lshlrev_b32_e32 v14, 16, v11
	v_and_b32_e32 v15, 0xffff0000, v11
	v_lshlrev_b32_e32 v8, 16, v16
	v_and_b32_e32 v9, 0xffff0000, v16
	v_lshlrev_b32_e32 v10, 16, v17
	v_and_b32_e32 v11, 0xffff0000, v17
	v_lshlrev_b32_e32 v16, 16, v18
	v_and_b32_e32 v17, 0xffff0000, v18
	v_lshlrev_b32_e32 v18, 16, v19
	v_and_b32_e32 v19, 0xffff0000, v19
	s_mov_b64 s[24:25], 0

;     DI bool next(int i, Unit& u) const { const int L = i * 32 + rank; if (L >= ppg * nN) return false; u.pm = ppg * grp + (L % ppg); const int p0 = L / ppg, p1 = p0 + rot; u.pn = rev ? nN - 1 - p0 : (p1 >= nN ? p1 - nN : p1); return true; }
; #define PG8_STAGE(bufoff, gbase, voff) do { _Pragma("unroll") for (int _i = 0; _i < 2; ++_i) \
;         __builtin_amdgcn_global_load_lds((const unsigned*)((const char*)(gbase) + (voff)[_i]), (PG8_LAS unsigned*)(lds + (bufoff) + ldsw + _i * 8192), 16, 0, 0); } while (0)
; #define PG8_LDA(dst, b, h) do { _Pragma("unroll") for (int m = 0; m < 4; ++m) _Pragma("unroll") for (int k = 0; k < 2; ++k) dst[m][k] = *(const PG8_LAS bf16x8*)(lds + PG8_SA(b, h) + aoff + m * 2048 + k * 1024); } while (0)
; #define PG8_LDB(dst, b, h) do { _Pragma("unroll") for (int n = 0; n < 2; ++n) _Pragma("unroll") for (int k = 0; k < 2; ++k) dst[n][k] = *(const PG8_LAS bf16x8*)(lds + PG8_SB(b, h) + boff + n * 2048 + k * 1024); } while (0)
; #define PG8_WAIT_V(n) asm volatile("s_waitcnt vmcnt(" #n ")" ::: "memory")
; #define PG8_WAIT_L(n) asm volatile("s_waitcnt lgkmcnt(" #n ")" ::: "memory")
; template <class Epi, class Sched, bool ALIGN_EPI = false, bool SP2 = false>
; __device__ __forceinline__ void gemm_phase(PG8_LAS unsigned char* lds, const Gemm g, const Sched& S, const Epi& E, const int tid) {
;     ...
;         const bool has_next = S.next(ui + 1, nxt);
;         const char* nA = has_next ? (const char*)g.A + (size_t)nxt.pm * tstep : cA; const char* nB = has_next ? (const char*)g.Bt + (size_t)nxt.pn * tstep : cB;
;         for (int t = 0; t < nt; t += 2) {
;             const bool last = (t == nt - 2);
;             const char* a1 = cA + (size_t)(t + 1) * kstep;
;             const char* a2 = last ? nA : cA + (size_t)(t + 2) * kstep; const char* b2 = last ? nB : cB + (size_t)(t + 2) * kstep;
;             const char* a3 = a2 + kstep; const char* b3 = b2 + kstep;
;             if (last && has_next) S.a_ready(nxt);
;             if constexpr (SP2) {
;             PG8_LDB(B0, 0, 0); PG8_LDB(B1, 0, 1); PG8_SCHED; PG8_LDA(At, 0, 0); PG8_STAGE(PG8_SA(1, 1), a1 + hstep, voffA);
;             PG8_WAIT_V(8); PG8_WAIT_L(0); PG8_BAR; PG8_MMA(0, 0, At, B0); PG8_MMA(0, 1, At, B1); PG8_BAR; PG8_SCHED;
;             PG8_LDA(At, 0, 1); PG8_STAGE(PG8_SB(0, 0), b2, voffB); PG8_STAGE(PG8_SB(0, 1), b2 + hstepB, voffB); PG8_STAGE(PG8_SA(0, 0), a2, voffA);
.LBB0_979:
	s_add_u32 s36, s38, 0xfffc0080
	s_addc_u32 s37, s39, -1
	s_add_i32 s81, 0, 0x10000
	s_cmp_eq_u32 s80, 12
	s_cselect_b32 s41, s19, s37
	s_cselect_b32 s40, s25, s36
	v_add_u32_e32 v150, s81, v158
	s_cselect_b32 s37, s17, s79
	s_cselect_b32 s36, s76, s78
	s_cmp_eq_u32 s80, 12
	s_cselect_b32 s32, 1, 0
	s_andn2_b32 s32, s32, s30
	s_add_i32 s84, 0, 0x14000
	ds_read_b128 v[146:149], v150
	ds_read_b128 v[162:165], v150 offset:1024
	ds_read_b128 v[170:173], v150 offset:2048
	ds_read_b128 v[174:177], v150 offset:3072
	v_add_u32_e32 v150, s84, v158
	ds_read_b128 v[178:181], v150
	ds_read_b128 v[182:185], v150 offset:1024
	ds_read_b128 v[186:189], v150 offset:2048
	ds_read_b128 v[190:193], v150 offset:3072
	v_lshl_add_u64 v[150:151], s[38:39], 0, v[142:143]
	s_add_i32 m0, s29, 0xc000
	ds_read_b128 v[194:197], v160
	ds_read_b128 v[198:201], v160 offset:1024
	ds_read_b128 v[212:215], v160 offset:2048
	ds_read_b128 v[216:219], v160 offset:3072
	ds_read_b128 v[220:223], v160 offset:4096
	ds_read_b128 v[224:227], v160 offset:5120
	ds_read_b128 v[228:231], v160 offset:6144
	ds_read_b128 v[232:235], v160 offset:7168
	global_load_lds_dwordx4 v[150:151], off
	v_lshl_add_u64 v[150:151], s[38:39], 0, v[144:145]
	s_add_i32 m0, s29, 0xe000
	s_nop 0
	global_load_lds_dwordx4 v[150:151], off
	s_waitcnt vmcnt(8)
	s_waitcnt lgkmcnt(0)
	s_barrier
	s_waitcnt lgkmcnt(0)
	v_mfma_f32_16x16x32_bf16 v[120:123], v[146:149], v[194:197], v[120:123]
	v_mfma_f32_16x16x32_bf16 v[128:131], v[170:173], v[194:197], v[128:131]
	v_mfma_f32_16x16x32_bf16 v[100:103], v[146:149], v[212:215], v[100:103]
	v_mfma_f32_16x16x32_bf16 v[108:111], v[170:173], v[212:215], v[108:111]
	v_mfma_f32_16x16x32_bf16 v[84:87], v[146:149], v[220:223], v[84:87]
	v_mfma_f32_16x16x32_bf16 v[92:95], v[170:173], v[220:223], v[92:95]
	v_mfma_f32_16x16x32_bf16 v[68:71], v[146:149], v[228:231], v[68:71]
	v_mfma_f32_16x16x32_bf16 v[76:79], v[170:173], v[228:231], v[76:79]
	v_mfma_f32_16x16x32_bf16 v[120:123], v[162:165], v[198:201], v[120:123]
	v_mfma_f32_16x16x32_bf16 v[128:131], v[174:177], v[198:201], v[128:131]
	v_mfma_f32_16x16x32_bf16 v[100:103], v[162:165], v[216:219], v[100:103]
	v_mfma_f32_16x16x32_bf16 v[108:111], v[174:177], v[216:219], v[108:111]
	v_mfma_f32_16x16x32_bf16 v[84:87], v[162:165], v[224:227], v[84:87]
	v_mfma_f32_16x16x32_bf16 v[92:95], v[174:177], v[224:227], v[92:95]
	v_mfma_f32_16x16x32_bf16 v[68:71], v[162:165], v[232:235], v[68:71]
	v_mfma_f32_16x16x32_bf16 v[76:79], v[174:177], v[232:235], v[76:79]
	v_mfma_f32_16x16x32_bf16 v[116:119], v[178:181], v[194:197], v[116:119]
	v_mfma_f32_16x16x32_bf16 v[124:127], v[186:189], v[194:197], v[124:127]
	v_mfma_f32_16x16x32_bf16 v[104:107], v[178:181], v[212:215], v[104:107]
	v_mfma_f32_16x16x32_bf16 v[112:115], v[186:189], v[212:215], v[112:115]
	v_mfma_f32_16x16x32_bf16 v[88:91], v[178:181], v[220:223], v[88:91]
	v_mfma_f32_16x16x32_bf16 v[96:99], v[186:189], v[220:223], v[96:99]
	v_mfma_f32_16x16x32_bf16 v[72:75], v[178:181], v[228:231], v[72:75]
	v_mfma_f32_16x16x32_bf16 v[80:83], v[186:189], v[228:231], v[80:83]
	v_mfma_f32_16x16x32_bf16 v[116:119], v[182:185], v[198:201], v[116:119]
	v_mfma_f32_16x16x32_bf16 v[124:127], v[190:193], v[198:201], v[124:127]
	v_mfma_f32_16x16x32_bf16 v[104:107], v[182:185], v[216:219], v[104:107]
	v_mfma_f32_16x16x32_bf16 v[112:115], v[190:193], v[216:219], v[112:115]
	v_mfma_f32_16x16x32_bf16 v[88:91], v[182:185], v[224:227], v[88:91]
	v_mfma_f32_16x16x32_bf16 v[96:99], v[190:193], v[224:227], v[96:99]
	v_mfma_f32_16x16x32_bf16 v[72:75], v[182:185], v[232:235], v[72:75]
	v_mfma_f32_16x16x32_bf16 v[80:83], v[190:193], v[232:235], v[80:83]
	s_barrier
	s_add_i32 s81, s81, s43
	v_lshl_add_u64 v[150:151], s[36:37], 0, v[136:137]
	s_mov_b32 m0, s81
	ds_read_b128 v[194:197], v160 offset:16384
	ds_read_b128 v[198:201], v160 offset:17408
	ds_read_b128 v[212:215], v160 offset:18432
	ds_read_b128 v[216:219], v160 offset:19456
	ds_read_b128 v[220:223], v160 offset:20480
	ds_read_b128 v[224:227], v160 offset:21504
	ds_read_b128 v[228:231], v160 offset:22528
	ds_read_b128 v[232:235], v160 offset:23552
	s_cmp_lg_u32 s32, 0
	s_cbranch_scc1 .Lbt2_0
	global_load_lds_dwordx4 v[150:151], off

; #define PG8_STAGE(bufoff, gbase, voff) do { _Pragma("unroll") for (int _i = 0; _i < 2; ++_i) \
;         __builtin_amdgcn_global_load_lds((const unsigned*)((const char*)(gbase) + (voff)[_i]), (PG8_LAS unsigned*)(lds + (bufoff) + ldsw + _i * 8192), 16, 0, 0); } while (0)
; #define PG8_LDA(dst, b, h) do { _Pragma("unroll") for (int m = 0; m < 4; ++m) _Pragma("unroll") for (int k = 0; k < 2; ++k) dst[m][k] = *(const PG8_LAS bf16x8*)(lds + PG8_SA(b, h) + aoff + m * 2048 + k * 1024); } while (0)
; #define PG8_LDB(dst, b, h) do { _Pragma("unroll") for (int n = 0; n < 2; ++n) _Pragma("unroll") for (int k = 0; k < 2; ++k) dst[n][k] = *(const PG8_LAS bf16x8*)(lds + PG8_SB(b, h) + boff + n * 2048 + k * 1024); } while (0)
; #define PG8_MMA(ai, bj, At, Bt) do { __builtin_amdgcn_s_setprio(1); _Pragma("unroll") for (int m = 0; m < 4; ++m) _Pragma("unroll") for (int n = 0; n < 2; ++n) _Pragma("unroll") for (int k = 0; k < 2; ++k) \
;         acc[ai][bj][m][n] = __builtin_amdgcn_mfma_f32_16x16x32_bf16(Bt[n][k], At[m][k], acc[ai][bj][m][n], 0, 0, 0); __builtin_amdgcn_s_setprio(0); } while (0)
; #define PG8_WAIT_V(n) asm volatile("s_waitcnt vmcnt(" #n ")" ::: "memory")
; #define PG8_WAIT_L(n) asm volatile("s_waitcnt lgkmcnt(" #n ")" ::: "memory")
; #define PG8_BAR __builtin_amdgcn_s_barrier()
; #define PG8_SCHED __builtin_amdgcn_sched_barrier(0)
; template <class Epi, class Sched, bool ALIGN_EPI = false, bool SP2 = false>
; __device__ __forceinline__ void gemm_phase(PG8_LAS unsigned char* lds, const Gemm g, const Sched& S, const Epi& E, const int tid) {
;     ...
;             PG8_WAIT_V(8); PG8_WAIT_L(0); PG8_BAR; PG8_MMA(1, 0, At, B0); PG8_MMA(1, 1, At, B1); PG8_BAR; PG8_SCHED;
;             PG8_LDB(B0, 1, 0); PG8_LDB(B1, 1, 1); PG8_SCHED; PG8_LDA(At, 1, 0); PG8_STAGE(PG8_SA(0, 1), a2 + hstep, voffA);
;             PG8_WAIT_V(8); PG8_WAIT_L(0); PG8_BAR; PG8_MMA(0, 0, At, B0); PG8_MMA(0, 1, At, B1); PG8_BAR; PG8_SCHED;
.Lbw2_2:
	s_waitcnt lgkmcnt(0)
	s_barrier
	s_waitcnt lgkmcnt(0)
	v_mfma_f32_16x16x32_bf16 v[52:55], v[146:149], v[194:197], v[52:55]
	v_mfma_f32_16x16x32_bf16 v[60:63], v[170:173], v[194:197], v[60:63]
	v_mfma_f32_16x16x32_bf16 v[36:39], v[146:149], v[212:215], v[36:39]
	v_mfma_f32_16x16x32_bf16 v[44:47], v[170:173], v[212:215], v[44:47]
	v_mfma_f32_16x16x32_bf16 v[20:23], v[146:149], v[220:223], v[20:23]
	v_mfma_f32_16x16x32_bf16 v[28:31], v[170:173], v[220:223], v[28:31]
	v_mfma_f32_16x16x32_bf16 v[4:7], v[146:149], v[228:231], v[4:7]
	v_mfma_f32_16x16x32_bf16 v[12:15], v[170:173], v[228:231], v[12:15]
	v_mfma_f32_16x16x32_bf16 v[52:55], v[162:165], v[198:201], v[52:55]
	v_mfma_f32_16x16x32_bf16 v[60:63], v[174:177], v[198:201], v[60:63]
	v_mfma_f32_16x16x32_bf16 v[36:39], v[162:165], v[216:219], v[36:39]
	v_mfma_f32_16x16x32_bf16 v[44:47], v[174:177], v[216:219], v[44:47]
	v_mfma_f32_16x16x32_bf16 v[20:23], v[162:165], v[224:227], v[20:23]
	v_mfma_f32_16x16x32_bf16 v[28:31], v[174:177], v[224:227], v[28:31]
	v_mfma_f32_16x16x32_bf16 v[4:7], v[162:165], v[232:235], v[4:7]
	v_mfma_f32_16x16x32_bf16 v[12:15], v[174:177], v[232:235], v[12:15]
	v_mfma_f32_16x16x32_bf16 v[56:59], v[178:181], v[194:197], v[56:59]
	v_mfma_f32_16x16x32_bf16 v[64:67], v[186:189], v[194:197], v[64:67]
	v_mfma_f32_16x16x32_bf16 v[40:43], v[178:181], v[212:215], v[40:43]
	v_mfma_f32_16x16x32_bf16 v[48:51], v[186:189], v[212:215], v[48:51]
	v_mfma_f32_16x16x32_bf16 v[24:27], v[178:181], v[220:223], v[24:27]
	v_mfma_f32_16x16x32_bf16 v[32:35], v[186:189], v[220:223], v[32:35]
	v_mfma_f32_16x16x32_bf16 v[8:11], v[178:181], v[228:231], v[8:11]
	v_mfma_f32_16x16x32_bf16 v[16:19], v[186:189], v[228:231], v[16:19]
	v_mfma_f32_16x16x32_bf16 v[56:59], v[182:185], v[198:201], v[56:59]
	v_mfma_f32_16x16x32_bf16 v[64:67], v[190:193], v[198:201], v[64:67]
	v_mfma_f32_16x16x32_bf16 v[40:43], v[182:185], v[216:219], v[40:43]
	v_mfma_f32_16x16x32_bf16 v[48:51], v[190:193], v[216:219], v[48:51]
	v_mfma_f32_16x16x32_bf16 v[24:27], v[182:185], v[224:227], v[24:27]
	v_mfma_f32_16x16x32_bf16 v[32:35], v[190:193], v[224:227], v[32:35]
	v_mfma_f32_16x16x32_bf16 v[8:11], v[182:185], v[232:235], v[8:11]
	v_mfma_f32_16x16x32_bf16 v[16:19], v[190:193], v[232:235], v[16:19]
	s_barrier
	s_add_i32 s81, 0, 0x18000
	v_add_u32_e32 v161, s81, v158
	s_add_i32 s82, 0, 0x1c000
	ds_read_b128 v[146:149], v161
	ds_read_b128 v[162:165], v161 offset:1024
	ds_read_b128 v[170:173], v161 offset:2048
	ds_read_b128 v[174:177], v161 offset:3072
	v_add_u32_e32 v161, s82, v158
	ds_read_b128 v[178:181], v161
	ds_read_b128 v[182:185], v161 offset:1024
	ds_read_b128 v[186:189], v161 offset:2048
	ds_read_b128 v[190:193], v161 offset:3072
	s_add_u32 s40, s40, 0x40000
	s_addc_u32 s41, s41, 0
	s_mov_b32 m0, s62
	v_lshl_add_u64 v[240:241], s[40:41], 0, v[134:135]
	ds_read_b128 v[194:197], v160 offset:32768
	ds_read_b128 v[198:201], v160 offset:33792
	ds_read_b128 v[212:215], v160 offset:34816
	ds_read_b128 v[216:219], v160 offset:35840
	ds_read_b128 v[220:223], v160 offset:36864
	ds_read_b128 v[224:227], v160 offset:37888
	ds_read_b128 v[228:231], v160 offset:38912
	ds_read_b128 v[232:235], v160 offset:39936
	s_cmp_lg_u32 s32, 0
	s_cbranch_scc1 .Lbt2_6
	global_load_lds_dwordx4 v[240:241], off

; #define PG8_STAGE(bufoff, gbase, voff) do { _Pragma("unroll") for (int _i = 0; _i < 2; ++_i) \
;         __builtin_amdgcn_global_load_lds((const unsigned*)((const char*)(gbase) + (voff)[_i]), (PG8_LAS unsigned*)(lds + (bufoff) + ldsw + _i * 8192), 16, 0, 0); } while (0)
; #define PG8_LDA(dst, b, h) do { _Pragma("unroll") for (int m = 0; m < 4; ++m) _Pragma("unroll") for (int k = 0; k < 2; ++k) dst[m][k] = *(const PG8_LAS bf16x8*)(lds + PG8_SA(b, h) + aoff + m * 2048 + k * 1024); } while (0)
; #define PG8_MMA(ai, bj, At, Bt) do { __builtin_amdgcn_s_setprio(1); _Pragma("unroll") for (int m = 0; m < 4; ++m) _Pragma("unroll") for (int n = 0; n < 2; ++n) _Pragma("unroll") for (int k = 0; k < 2; ++k) \
;         acc[ai][bj][m][n] = __builtin_amdgcn_mfma_f32_16x16x32_bf16(Bt[n][k], At[m][k], acc[ai][bj][m][n], 0, 0, 0); __builtin_amdgcn_s_setprio(0); } while (0)
; #define PG8_WAIT_V(n) asm volatile("s_waitcnt vmcnt(" #n ")" ::: "memory")
; #define PG8_WAIT_L(n) asm volatile("s_waitcnt lgkmcnt(" #n ")" ::: "memory")
; #define PG8_BAR __builtin_amdgcn_s_barrier()
; #define PG8_SCHED __builtin_amdgcn_sched_barrier(0)
; template <class Epi, class Sched, bool ALIGN_EPI = false, bool SP2 = false>
; __device__ __forceinline__ void gemm_phase(PG8_LAS unsigned char* lds, const Gemm g, const Sched& S, const Epi& E, const int tid) {
;     ...
;             PG8_WAIT_V(8); PG8_WAIT_L(0); PG8_BAR; PG8_MMA(0, 0, At, B0); PG8_MMA(0, 1, At, B1); PG8_BAR; PG8_SCHED;
;             PG8_LDA(At, 1, 1); PG8_STAGE(PG8_SB(1, 0), b3, voffB); PG8_STAGE(PG8_SB(1, 1), b3 + hstepB, voffB); PG8_STAGE(PG8_SA(1, 0), a3, voffA);
.Lbw2_0:
	s_waitcnt lgkmcnt(0)
	s_barrier
	s_waitcnt lgkmcnt(0)
	v_mfma_f32_16x16x32_bf16 v[120:123], v[146:149], v[194:197], v[120:123]
	v_mfma_f32_16x16x32_bf16 v[128:131], v[170:173], v[194:197], v[128:131]
	v_mfma_f32_16x16x32_bf16 v[100:103], v[146:149], v[212:215], v[100:103]
	v_mfma_f32_16x16x32_bf16 v[108:111], v[170:173], v[212:215], v[108:111]
	v_mfma_f32_16x16x32_bf16 v[84:87], v[146:149], v[220:223], v[84:87]
	v_mfma_f32_16x16x32_bf16 v[92:95], v[170:173], v[220:223], v[92:95]
	v_mfma_f32_16x16x32_bf16 v[68:71], v[146:149], v[228:231], v[68:71]
	v_mfma_f32_16x16x32_bf16 v[76:79], v[170:173], v[228:231], v[76:79]
	v_mfma_f32_16x16x32_bf16 v[120:123], v[162:165], v[198:201], v[120:123]
	v_mfma_f32_16x16x32_bf16 v[128:131], v[174:177], v[198:201], v[128:131]
	v_mfma_f32_16x16x32_bf16 v[100:103], v[162:165], v[216:219], v[100:103]
	v_mfma_f32_16x16x32_bf16 v[108:111], v[174:177], v[216:219], v[108:111]
	v_mfma_f32_16x16x32_bf16 v[84:87], v[162:165], v[224:227], v[84:87]
	v_mfma_f32_16x16x32_bf16 v[92:95], v[174:177], v[224:227], v[92:95]
	v_mfma_f32_16x16x32_bf16 v[68:71], v[162:165], v[232:235], v[68:71]
	v_mfma_f32_16x16x32_bf16 v[76:79], v[174:177], v[232:235], v[76:79]
	v_mfma_f32_16x16x32_bf16 v[116:119], v[178:181], v[194:197], v[116:119]
	v_mfma_f32_16x16x32_bf16 v[124:127], v[186:189], v[194:197], v[124:127]
	v_mfma_f32_16x16x32_bf16 v[104:107], v[178:181], v[212:215], v[104:107]
	v_mfma_f32_16x16x32_bf16 v[112:115], v[186:189], v[212:215], v[112:115]
	v_mfma_f32_16x16x32_bf16 v[88:91], v[178:181], v[220:223], v[88:91]
	v_mfma_f32_16x16x32_bf16 v[96:99], v[186:189], v[220:223], v[96:99]
	v_mfma_f32_16x16x32_bf16 v[72:75], v[178:181], v[228:231], v[72:75]
	v_mfma_f32_16x16x32_bf16 v[80:83], v[186:189], v[228:231], v[80:83]
	v_mfma_f32_16x16x32_bf16 v[116:119], v[182:185], v[198:201], v[116:119]
	v_mfma_f32_16x16x32_bf16 v[124:127], v[190:193], v[198:201], v[124:127]
	v_mfma_f32_16x16x32_bf16 v[104:107], v[182:185], v[216:219], v[104:107]
	v_mfma_f32_16x16x32_bf16 v[112:115], v[190:193], v[216:219], v[112:115]
	v_mfma_f32_16x16x32_bf16 v[88:91], v[182:185], v[224:227], v[88:91]
	v_mfma_f32_16x16x32_bf16 v[96:99], v[190:193], v[224:227], v[96:99]
	v_mfma_f32_16x16x32_bf16 v[72:75], v[182:185], v[232:235], v[72:75]
	v_mfma_f32_16x16x32_bf16 v[80:83], v[190:193], v[232:235], v[80:83]
	s_barrier
	s_add_i32 s40, s81, s43
	v_lshl_add_u64 v[150:151], v[150:151], 0, s[52:53]
	s_mov_b32 m0, s40
	ds_read_b128 v[194:197], v160 offset:49152
	ds_read_b128 v[198:201], v160 offset:50176
	ds_read_b128 v[212:215], v160 offset:51200
	ds_read_b128 v[216:219], v160 offset:52224
	ds_read_b128 v[220:223], v160 offset:53248
	ds_read_b128 v[224:227], v160 offset:54272
	ds_read_b128 v[228:231], v160 offset:55296
	ds_read_b128 v[232:235], v160 offset:56320
	s_cmp_lg_u32 s32, 0
	s_cbranch_scc1 .Lbt2_8
	global_load_lds_dwordx4 v[150:151], off

; #define PG8_STAGE(bufoff, gbase, voff) do { _Pragma("unroll") for (int _i = 0; _i < 2; ++_i) \
;         __builtin_amdgcn_global_load_lds((const unsigned*)((const char*)(gbase) + (voff)[_i]), (PG8_LAS unsigned*)(lds + (bufoff) + ldsw + _i * 8192), 16, 0, 0); } while (0)
; #define PG8_LDA(dst, b, h) do { _Pragma("unroll") for (int m = 0; m < 4; ++m) _Pragma("unroll") for (int k = 0; k < 2; ++k) dst[m][k] = *(const PG8_LAS bf16x8*)(lds + PG8_SA(b, h) + aoff + m * 2048 + k * 1024); } while (0)
; #define PG8_MMA(ai, bj, At, Bt) do { __builtin_amdgcn_s_setprio(1); _Pragma("unroll") for (int m = 0; m < 4; ++m) _Pragma("unroll") for (int n = 0; n < 2; ++n) _Pragma("unroll") for (int k = 0; k < 2; ++k) \
;         acc[ai][bj][m][n] = __builtin_amdgcn_mfma_f32_16x16x32_bf16(Bt[n][k], At[m][k], acc[ai][bj][m][n], 0, 0, 0); __builtin_amdgcn_s_setprio(0); } while (0)
; #define PG8_WAIT_V(n) asm volatile("s_waitcnt vmcnt(" #n ")" ::: "memory")
; #define PG8_WAIT_L(n) asm volatile("s_waitcnt lgkmcnt(" #n ")" ::: "memory")
; #define PG8_BAR __builtin_amdgcn_s_barrier()
; #define PG8_SCHED __builtin_amdgcn_sched_barrier(0)
; template <class Epi, class Sched, bool ALIGN_EPI = false, bool SP2 = false>
; __device__ __forceinline__ void gemm_phase(PG8_LAS unsigned char* lds, const Gemm g, const Sched& S, const Epi& E, const int tid) {
;     ...
;         for (int t = 0; t < nt; t += 2) {
;             const bool last = (t == nt - 2);
;             const char* a1 = cA + (size_t)(t + 1) * kstep;
;             const char* a2 = last ? nA : cA + (size_t)(t + 2) * kstep; const char* b2 = last ? nB : cB + (size_t)(t + 2) * kstep;
;             const char* a3 = a2 + kstep; const char* b3 = b2 + kstep;
;     ...
;             PG8_LDA(At, 1, 1); PG8_STAGE(PG8_SB(1, 0), b3, voffB); PG8_STAGE(PG8_SB(1, 1), b3 + hstepB, voffB); PG8_STAGE(PG8_SA(1, 0), a3, voffA);
;             PG8_WAIT_V(8); PG8_WAIT_L(0); PG8_BAR; PG8_MMA(1, 0, At, B0); PG8_MMA(1, 1, At, B1); PG8_BAR; PG8_SCHED;
.Lbt2_13:
	s_waitcnt vmcnt(8)
	s_waitcnt lgkmcnt(0)
	s_barrier
	s_waitcnt lgkmcnt(0)
	v_mfma_f32_16x16x32_bf16 v[52:55], v[146:149], v[194:197], v[52:55]
	v_mfma_f32_16x16x32_bf16 v[60:63], v[170:173], v[194:197], v[60:63]
	v_mfma_f32_16x16x32_bf16 v[36:39], v[146:149], v[212:215], v[36:39]
	v_mfma_f32_16x16x32_bf16 v[44:47], v[170:173], v[212:215], v[44:47]
	v_mfma_f32_16x16x32_bf16 v[20:23], v[146:149], v[220:223], v[20:23]
	v_mfma_f32_16x16x32_bf16 v[28:31], v[170:173], v[220:223], v[28:31]
	v_mfma_f32_16x16x32_bf16 v[4:7], v[146:149], v[228:231], v[4:7]
	v_mfma_f32_16x16x32_bf16 v[12:15], v[170:173], v[228:231], v[12:15]
	v_mfma_f32_16x16x32_bf16 v[52:55], v[162:165], v[198:201], v[52:55]
	v_mfma_f32_16x16x32_bf16 v[60:63], v[174:177], v[198:201], v[60:63]
	v_mfma_f32_16x16x32_bf16 v[36:39], v[162:165], v[216:219], v[36:39]
	v_mfma_f32_16x16x32_bf16 v[44:47], v[174:177], v[216:219], v[44:47]
	v_mfma_f32_16x16x32_bf16 v[20:23], v[162:165], v[224:227], v[20:23]
	v_mfma_f32_16x16x32_bf16 v[28:31], v[174:177], v[224:227], v[28:31]
	v_mfma_f32_16x16x32_bf16 v[4:7], v[162:165], v[232:235], v[4:7]
	v_mfma_f32_16x16x32_bf16 v[12:15], v[174:177], v[232:235], v[12:15]
	v_mfma_f32_16x16x32_bf16 v[56:59], v[178:181], v[194:197], v[56:59]
	v_mfma_f32_16x16x32_bf16 v[64:67], v[186:189], v[194:197], v[64:67]
	v_mfma_f32_16x16x32_bf16 v[40:43], v[178:181], v[212:215], v[40:43]
	v_mfma_f32_16x16x32_bf16 v[48:51], v[186:189], v[212:215], v[48:51]
	v_mfma_f32_16x16x32_bf16 v[24:27], v[178:181], v[220:223], v[24:27]
	v_mfma_f32_16x16x32_bf16 v[32:35], v[186:189], v[220:223], v[32:35]
	v_mfma_f32_16x16x32_bf16 v[8:11], v[178:181], v[228:231], v[8:11]
	v_mfma_f32_16x16x32_bf16 v[16:19], v[186:189], v[228:231], v[16:19]
	v_mfma_f32_16x16x32_bf16 v[56:59], v[182:185], v[198:201], v[56:59]
	v_mfma_f32_16x16x32_bf16 v[64:67], v[190:193], v[198:201], v[64:67]
	v_mfma_f32_16x16x32_bf16 v[40:43], v[182:185], v[216:219], v[40:43]
	v_mfma_f32_16x16x32_bf16 v[48:51], v[190:193], v[216:219], v[48:51]
	v_mfma_f32_16x16x32_bf16 v[24:27], v[182:185], v[224:227], v[24:27]
	v_mfma_f32_16x16x32_bf16 v[32:35], v[190:193], v[224:227], v[32:35]
	v_mfma_f32_16x16x32_bf16 v[8:11], v[182:185], v[232:235], v[8:11]
	v_mfma_f32_16x16x32_bf16 v[16:19], v[190:193], v[232:235], v[16:19]
	s_barrier
	s_add_i32 s80, s80, 2
	s_add_u32 s38, s38, 0x100
	s_addc_u32 s39, s39, 0
	s_add_u32 s78, s78, 0x100
	s_addc_u32 s79, s79, 0
	s_cmp_gt_u32 s80, 13
	s_cbranch_scc0 .LBB0_979
	s_and_b64 vcc, exec, s[14:15]
	s_cbranch_vccz .LBB0_982
	s_barrier

; #define PG8_WAIT_V(n) asm volatile("s_waitcnt vmcnt(" #n ")" ::: "memory")
; #define PG8_BAR __builtin_amdgcn_s_barrier()
; template <class Epi, class Sched, bool ALIGN_EPI = false, bool SP2 = false>
; __device__ __forceinline__ void gemm_phase(PG8_LAS unsigned char* lds, const Gemm g, const Sched& S, const Epi& E, const int tid) {
;     ...
;     PG8_WAIT_V(0);
;     if constexpr (!ALIGN_EPI) { if (wr == 0) PG8_BAR; }
;     PG8_BAR;
.LBB0_1017:
	s_setprio 0
	s_waitcnt vmcnt(0)
	s_mov_b64 s[54:55], 0x200
	s_barrier

; #define PG8_STAGE(bufoff, gbase, voff) do { _Pragma("unroll") for (int _i = 0; _i < 2; ++_i) \
;         __builtin_amdgcn_global_load_lds((const unsigned*)((const char*)(gbase) + (voff)[_i]), (PG8_LAS unsigned*)(lds + (bufoff) + ldsw + _i * 8192), 16, 0, 0); } while (0)
; #define PG8_WAIT_V(n) asm volatile("s_waitcnt vmcnt(" #n ")" ::: "memory")
; #define PG8_BAR __builtin_amdgcn_s_barrier()
;     DI void row8x2(int row, int col, f32x4 a0, f32x4 a1, f32x4 b0, f32x4 b1, float r, bool hi) const {
;     ...
;         const int cc = col + (hi ? 32 : 0);
;         *(u32x4*)(O + (size_t)(row - (hi ? 8 : 0)) * ldc + cc) = pa;
;         *(u32x4*)(O + (size_t)(row + (hi ? 0 : 8)) * ldc + cc) = pb;
; template <class Epi, class Sched, bool ALIGN_EPI = false, bool SP2 = false>
; __device__ __forceinline__ void gemm_phase(PG8_LAS unsigned char* lds, const Gemm g, const Sched& S, const Epi& E, const int tid) {
;     ...
;         PG8_STAGE(PG8_SB(1, 0), cB + kstep, voffB); PG8_STAGE(PG8_SA(1, 0), cA + kstep, voffA); PG8_STAGE(PG8_SB(1, 1), cB + hstepB + kstep, voffB);
;         PG8_WAIT_V(6); PG8_BAR;
;     } else {
;         PG8_STAGE(PG8_SB(0, 0), cB, voffB); PG8_STAGE(PG8_SA(0, 0), cA, voffA); PG8_STAGE(PG8_SB(0, 1), cB + hstepB, voffB); PG8_STAGE(PG8_SA(0, 1), cA + hstep, voffA);
;         if (wr == 1) PG8_BAR;
;         PG8_WAIT_V(4); PG8_BAR;
;         PG8_STAGE(PG8_SB(1, 0), cB + kstep, voffB); PG8_STAGE(PG8_SA(1, 0), cA + kstep, voffA); PG8_STAGE(PG8_SB(1, 1), cB + hstepB + kstep, voffB);
;         PG8_WAIT_V(6); PG8_BAR;
;     }
;     if constexpr (Epi::HAS_INIT) E.init_finish(acc, iw_);
.LBB0_1102:
	v_lshlrev_b32_e32 v18, 1, v151
	v_lshlrev_b32_e32 v19, 2, v152
	s_and_b32 s21, s19, 3
	v_lshl_or_b32 v18, v152, 6, v18
	s_lshl_b32 s19, s20, 13
	v_and_b32_e32 v20, 32, v19
	s_add_i32 m0, s37, 0x18000
	v_lshl_add_u64 v[10:11], v[10:11], 0, s[52:53]
	v_bitop3_b32 v21, v18, s19, v20 bitop3:0xde
	s_lshl_b32 s19, s21, 12
	s_waitcnt vmcnt(2)
	s_barrier
	global_load_lds_dwordx4 v[10:11], off
	v_lshl_add_u64 v[8:9], v[8:9], 0, s[52:53]
	s_add_i32 m0, s37, 0x1a000
	s_add_i32 s67, s37, 0x8000
	s_add_i32 s76, s37, 0xa000
	global_load_lds_dwordx4 v[8:9], off
	v_lshl_add_u64 v[4:5], v[4:5], 0, s[52:53]
	s_mov_b32 m0, s67
	s_add_u32 s22, s42, 0x10080
	global_load_lds_dwordx4 v[4:5], off
	v_lshl_add_u64 v[4:5], v[6:7], 0, s[52:53]
	s_mov_b32 m0, s76
	s_addc_u32 s23, s43, 0
	global_load_lds_dwordx4 v[4:5], off
	s_add_i32 m0, s37, 0x1c000
	v_lshl_add_u64 v[4:5], s[22:23], 0, v[138:139]
	global_load_lds_dwordx4 v[4:5], off
	v_lshl_add_u64 v[4:5], s[22:23], 0, v[134:135]
	s_add_i32 m0, s37, 0x1e000
	s_cmpk_lt_u32 s18, 0x100
	global_load_lds_dwordx4 v[4:5], off
	v_cmp_lt_u32_e32 vcc, 7, v152
	v_bitop3_b32 v157, s19, v18, v20 bitop3:0xf6
	s_cselect_b64 s[18:19], -1, 0
	s_lshl_b32 s21, s21, 6
	v_cndmask_b32_e64 v4, 0, 32, vcc
	v_or3_b32 v161, s21, v4, v151
	v_lshlrev_b32_e32 v4, 14, v12
	v_and_b32_e32 v4, 0xffff8000, v4
	v_lshl_add_u32 v4, v13, 11, v4
	v_and_b32_e32 v5, 1, v12
	v_lshl_or_b32 v4, v5, 6, v4
	v_lshl_add_u32 v142, v14, 1, v4
	v_lshlrev_b32_e32 v4, 14, v15
	v_lshl_or_b32 v156, s20, 6, v152
	s_lshl_b32 s20, s20, 8
	v_and_b32_e32 v4, 0xffff8000, v4
	s_waitcnt vmcnt(6)
	s_add_i32 s20, s20, 0
	v_lshl_add_u32 v4, v16, 11, v4
	v_and_b32_e32 v5, 1, v15
	s_add_i32 s20, s20, 0x20000
	v_lshl_or_b32 v4, v5, 6, v4
	s_mov_b32 s78, 0
	v_cndmask_b32_e64 v158, 0, -8, vcc
	v_cndmask_b32_e64 v159, 8, 0, vcc
	v_add_u32_e32 v160, s20, v19
	v_mov_b32_e32 v143, v2
	v_lshl_add_u32 v144, v17, 1, v4
	v_mov_b32_e32 v145, v2
	v_add_u32_e32 v162, 0, v21
	s_barrier
	v_readfirstlane_b32 s98, v0
	s_nop 3
	s_and_b32 s98, s98, 0x3ff
	s_lshr_b32 s98, s98, 6
	s_cmp_ge_u32 s98, 4
	s_cbranch_scc0 .Lprio_done3
	s_setprio 1
.Lprio_done3:
	s_branch .LBB0_1105
.LBB0_1103:
	s_mov_b64 s[28:29], 0

;     DI bool next(int i, Unit& u) const { const int L = i * 32 + rank; if (L >= ppg * nN) return false; u.pm = ppg * grp + (L % ppg); const int p0 = L / ppg, p1 = p0 + rot; u.pn = rev ? nN - 1 - p0 : (p1 >= nN ? p1 - nN : p1); return true; }
; #define PG8_STAGE(bufoff, gbase, voff) do { _Pragma("unroll") for (int _i = 0; _i < 2; ++_i) \
;         __builtin_amdgcn_global_load_lds((const unsigned*)((const char*)(gbase) + (voff)[_i]), (PG8_LAS unsigned*)(lds + (bufoff) + ldsw + _i * 8192), 16, 0, 0); } while (0)
; #define PG8_LDA(dst, b, h) do { _Pragma("unroll") for (int m = 0; m < 4; ++m) _Pragma("unroll") for (int k = 0; k < 2; ++k) dst[m][k] = *(const PG8_LAS bf16x8*)(lds + PG8_SA(b, h) + aoff + m * 2048 + k * 1024); } while (0)
; #define PG8_LDB(dst, b, h) do { _Pragma("unroll") for (int n = 0; n < 2; ++n) _Pragma("unroll") for (int k = 0; k < 2; ++k) dst[n][k] = *(const PG8_LAS bf16x8*)(lds + PG8_SB(b, h) + boff + n * 2048 + k * 1024); } while (0)
; #define PG8_WAIT_V(n) asm volatile("s_waitcnt vmcnt(" #n ")" ::: "memory")
; #define PG8_WAIT_L(n) asm volatile("s_waitcnt lgkmcnt(" #n ")" ::: "memory")
; template <class Epi, class Sched, bool ALIGN_EPI = false, bool SP2 = false>
; __device__ __forceinline__ void gemm_phase(PG8_LAS unsigned char* lds, const Gemm g, const Sched& S, const Epi& E, const int tid) {
;     ...
;         const bool has_next = S.next(ui + 1, nxt);
;         const char* nA = has_next ? (const char*)g.A + (size_t)nxt.pm * tstep : cA; const char* nB = has_next ? (const char*)g.Bt + (size_t)nxt.pn * tstep : cB;
;         for (int t = 0; t < nt; t += 2) {
;             const bool last = (t == nt - 2);
;             const char* a1 = cA + (size_t)(t + 1) * kstep;
;             const char* a2 = last ? nA : cA + (size_t)(t + 2) * kstep; const char* b2 = last ? nB : cB + (size_t)(t + 2) * kstep;
;             const char* a3 = a2 + kstep; const char* b3 = b2 + kstep;
;             if (last && has_next) S.a_ready(nxt);
;             if constexpr (SP2) {
;             PG8_LDB(B0, 0, 0); PG8_LDB(B1, 0, 1); PG8_SCHED; PG8_LDA(At, 0, 0); PG8_STAGE(PG8_SA(1, 1), a1 + hstep, voffA);
;             PG8_WAIT_V(8); PG8_WAIT_L(0); PG8_BAR; PG8_MMA(0, 0, At, B0); PG8_MMA(0, 1, At, B1); PG8_BAR; PG8_SCHED;
;             PG8_LDA(At, 0, 1); PG8_STAGE(PG8_SB(0, 0), b2, voffB); PG8_STAGE(PG8_SB(0, 1), b2 + hstepB, voffB); PG8_STAGE(PG8_SA(0, 0), a2, voffA);
.LBB0_1108:
	s_add_u32 s42, s40, 0xfffc0080
	s_addc_u32 s43, s41, -1
	s_add_i32 s84, 0, 0x10000
	s_cmp_eq_u32 s83, 12
	s_cselect_b32 s55, s23, s43
	s_cselect_b32 s54, s79, s42
	v_add_u32_e32 v163, s84, v157
	s_cselect_b32 s43, s21, s82
	s_cselect_b32 s42, s80, s81
	s_cmp_eq_u32 s83, 12
	s_cselect_b32 s32, 1, 0
	s_andn2_b32 s32, s32, s28
	s_add_i32 s86, 0, 0x14000
	ds_read_b128 v[146:149], v163
	ds_read_b128 v[164:167], v163 offset:1024
	ds_read_b128 v[170:173], v163 offset:2048
	ds_read_b128 v[174:177], v163 offset:3072
	v_add_u32_e32 v163, s86, v157
	ds_read_b128 v[178:181], v163
	ds_read_b128 v[182:185], v163 offset:1024
	ds_read_b128 v[186:189], v163 offset:2048
	ds_read_b128 v[190:193], v163 offset:3072
	v_lshl_add_u64 v[236:237], s[40:41], 0, v[142:143]
	s_add_i32 m0, s37, 0xc000
	ds_read_b128 v[194:197], v162
	ds_read_b128 v[198:201], v162 offset:1024
	ds_read_b128 v[212:215], v162 offset:2048
	ds_read_b128 v[216:219], v162 offset:3072
	ds_read_b128 v[220:223], v162 offset:4096
	ds_read_b128 v[224:227], v162 offset:5120
	ds_read_b128 v[228:231], v162 offset:6144
	ds_read_b128 v[232:235], v162 offset:7168
	global_load_lds_dwordx4 v[236:237], off
	v_lshl_add_u64 v[236:237], s[40:41], 0, v[144:145]
	s_add_i32 m0, s37, 0xe000
	s_nop 0
	global_load_lds_dwordx4 v[236:237], off
	s_waitcnt vmcnt(8)
	s_waitcnt lgkmcnt(0)
	s_barrier
	s_waitcnt lgkmcnt(0)
	v_mfma_f32_16x16x32_bf16 v[128:131], v[146:149], v[194:197], v[128:131]
	v_mfma_f32_16x16x32_bf16 v[124:127], v[170:173], v[194:197], v[124:127]
	v_mfma_f32_16x16x32_bf16 v[112:115], v[146:149], v[212:215], v[112:115]
	v_mfma_f32_16x16x32_bf16 v[108:111], v[170:173], v[212:215], v[108:111]
	v_mfma_f32_16x16x32_bf16 v[96:99], v[146:149], v[220:223], v[96:99]
	v_mfma_f32_16x16x32_bf16 v[92:95], v[170:173], v[220:223], v[92:95]
	v_mfma_f32_16x16x32_bf16 v[80:83], v[146:149], v[228:231], v[80:83]
	v_mfma_f32_16x16x32_bf16 v[76:79], v[170:173], v[228:231], v[76:79]
	v_mfma_f32_16x16x32_bf16 v[128:131], v[164:167], v[198:201], v[128:131]
	v_mfma_f32_16x16x32_bf16 v[124:127], v[174:177], v[198:201], v[124:127]
	v_mfma_f32_16x16x32_bf16 v[112:115], v[164:167], v[216:219], v[112:115]
	v_mfma_f32_16x16x32_bf16 v[108:111], v[174:177], v[216:219], v[108:111]
	v_mfma_f32_16x16x32_bf16 v[96:99], v[164:167], v[224:227], v[96:99]
	v_mfma_f32_16x16x32_bf16 v[92:95], v[174:177], v[224:227], v[92:95]
	v_mfma_f32_16x16x32_bf16 v[80:83], v[164:167], v[232:235], v[80:83]
	v_mfma_f32_16x16x32_bf16 v[76:79], v[174:177], v[232:235], v[76:79]
	v_mfma_f32_16x16x32_bf16 v[120:123], v[178:181], v[194:197], v[120:123]
	v_mfma_f32_16x16x32_bf16 v[116:119], v[186:189], v[194:197], v[116:119]
	v_mfma_f32_16x16x32_bf16 v[104:107], v[178:181], v[212:215], v[104:107]
	v_mfma_f32_16x16x32_bf16 v[100:103], v[186:189], v[212:215], v[100:103]
	v_mfma_f32_16x16x32_bf16 v[88:91], v[178:181], v[220:223], v[88:91]
	v_mfma_f32_16x16x32_bf16 v[84:87], v[186:189], v[220:223], v[84:87]
	v_mfma_f32_16x16x32_bf16 v[72:75], v[178:181], v[228:231], v[72:75]
	v_mfma_f32_16x16x32_bf16 v[68:71], v[186:189], v[228:231], v[68:71]
	v_mfma_f32_16x16x32_bf16 v[120:123], v[182:185], v[198:201], v[120:123]
	v_mfma_f32_16x16x32_bf16 v[116:119], v[190:193], v[198:201], v[116:119]
	v_mfma_f32_16x16x32_bf16 v[104:107], v[182:185], v[216:219], v[104:107]
	v_mfma_f32_16x16x32_bf16 v[100:103], v[190:193], v[216:219], v[100:103]
	v_mfma_f32_16x16x32_bf16 v[88:91], v[182:185], v[224:227], v[88:91]
	v_mfma_f32_16x16x32_bf16 v[84:87], v[190:193], v[224:227], v[84:87]
	v_mfma_f32_16x16x32_bf16 v[72:75], v[182:185], v[232:235], v[72:75]
	v_mfma_f32_16x16x32_bf16 v[68:71], v[190:193], v[232:235], v[68:71]
	s_barrier
	s_add_i32 s84, s84, s63
	v_lshl_add_u64 v[236:237], s[42:43], 0, v[138:139]
	s_mov_b32 m0, s84
	ds_read_b128 v[194:197], v162 offset:16384
	ds_read_b128 v[198:201], v162 offset:17408
	ds_read_b128 v[212:215], v162 offset:18432
	ds_read_b128 v[216:219], v162 offset:19456
	ds_read_b128 v[220:223], v162 offset:20480
	ds_read_b128 v[224:227], v162 offset:21504
	ds_read_b128 v[228:231], v162 offset:22528
	ds_read_b128 v[232:235], v162 offset:23552
	s_cmp_lg_u32 s32, 0
	s_cbranch_scc1 .Lbt3_0
	global_load_lds_dwordx4 v[236:237], off

; #define PG8_STAGE(bufoff, gbase, voff) do { _Pragma("unroll") for (int _i = 0; _i < 2; ++_i) \
;         __builtin_amdgcn_global_load_lds((const unsigned*)((const char*)(gbase) + (voff)[_i]), (PG8_LAS unsigned*)(lds + (bufoff) + ldsw + _i * 8192), 16, 0, 0); } while (0)
; #define PG8_LDA(dst, b, h) do { _Pragma("unroll") for (int m = 0; m < 4; ++m) _Pragma("unroll") for (int k = 0; k < 2; ++k) dst[m][k] = *(const PG8_LAS bf16x8*)(lds + PG8_SA(b, h) + aoff + m * 2048 + k * 1024); } while (0)
; #define PG8_LDB(dst, b, h) do { _Pragma("unroll") for (int n = 0; n < 2; ++n) _Pragma("unroll") for (int k = 0; k < 2; ++k) dst[n][k] = *(const PG8_LAS bf16x8*)(lds + PG8_SB(b, h) + boff + n * 2048 + k * 1024); } while (0)
; #define PG8_MMA(ai, bj, At, Bt) do { __builtin_amdgcn_s_setprio(1); _Pragma("unroll") for (int m = 0; m < 4; ++m) _Pragma("unroll") for (int n = 0; n < 2; ++n) _Pragma("unroll") for (int k = 0; k < 2; ++k) \
;         acc[ai][bj][m][n] = __builtin_amdgcn_mfma_f32_16x16x32_bf16(Bt[n][k], At[m][k], acc[ai][bj][m][n], 0, 0, 0); __builtin_amdgcn_s_setprio(0); } while (0)
; #define PG8_WAIT_V(n) asm volatile("s_waitcnt vmcnt(" #n ")" ::: "memory")
; #define PG8_WAIT_L(n) asm volatile("s_waitcnt lgkmcnt(" #n ")" ::: "memory")
; #define PG8_BAR __builtin_amdgcn_s_barrier()
; #define PG8_SCHED __builtin_amdgcn_sched_barrier(0)
; template <class Epi, class Sched, bool ALIGN_EPI = false, bool SP2 = false>
; __device__ __forceinline__ void gemm_phase(PG8_LAS unsigned char* lds, const Gemm g, const Sched& S, const Epi& E, const int tid) {
;     ...
;             PG8_WAIT_V(8); PG8_WAIT_L(0); PG8_BAR; PG8_MMA(1, 0, At, B0); PG8_MMA(1, 1, At, B1); PG8_BAR; PG8_SCHED;
;             PG8_LDB(B0, 1, 0); PG8_LDB(B1, 1, 1); PG8_SCHED; PG8_LDA(At, 1, 0); PG8_STAGE(PG8_SA(0, 1), a2 + hstep, voffA);
;             PG8_WAIT_V(8); PG8_WAIT_L(0); PG8_BAR; PG8_MMA(0, 0, At, B0); PG8_MMA(0, 1, At, B1); PG8_BAR; PG8_SCHED;
.Lbw3_2:
	s_waitcnt lgkmcnt(0)
	s_barrier
	s_waitcnt lgkmcnt(0)
	v_mfma_f32_16x16x32_bf16 v[64:67], v[146:149], v[194:197], v[64:67]
	v_mfma_f32_16x16x32_bf16 v[60:63], v[170:173], v[194:197], v[60:63]
	v_mfma_f32_16x16x32_bf16 v[48:51], v[146:149], v[212:215], v[48:51]
	v_mfma_f32_16x16x32_bf16 v[44:47], v[170:173], v[212:215], v[44:47]
	v_mfma_f32_16x16x32_bf16 v[32:35], v[146:149], v[220:223], v[32:35]
	v_mfma_f32_16x16x32_bf16 v[28:31], v[170:173], v[220:223], v[28:31]
	v_mfma_f32_16x16x32_bf16 v[16:19], v[146:149], v[228:231], v[16:19]
	v_mfma_f32_16x16x32_bf16 v[12:15], v[170:173], v[228:231], v[12:15]
	v_mfma_f32_16x16x32_bf16 v[64:67], v[164:167], v[198:201], v[64:67]
	v_mfma_f32_16x16x32_bf16 v[60:63], v[174:177], v[198:201], v[60:63]
	v_mfma_f32_16x16x32_bf16 v[48:51], v[164:167], v[216:219], v[48:51]
	v_mfma_f32_16x16x32_bf16 v[44:47], v[174:177], v[216:219], v[44:47]
	v_mfma_f32_16x16x32_bf16 v[32:35], v[164:167], v[224:227], v[32:35]
	v_mfma_f32_16x16x32_bf16 v[28:31], v[174:177], v[224:227], v[28:31]
	v_mfma_f32_16x16x32_bf16 v[16:19], v[164:167], v[232:235], v[16:19]
	v_mfma_f32_16x16x32_bf16 v[12:15], v[174:177], v[232:235], v[12:15]
	v_mfma_f32_16x16x32_bf16 v[56:59], v[178:181], v[194:197], v[56:59]
	v_mfma_f32_16x16x32_bf16 v[52:55], v[186:189], v[194:197], v[52:55]
	v_mfma_f32_16x16x32_bf16 v[40:43], v[178:181], v[212:215], v[40:43]
	v_mfma_f32_16x16x32_bf16 v[36:39], v[186:189], v[212:215], v[36:39]
	v_mfma_f32_16x16x32_bf16 v[24:27], v[178:181], v[220:223], v[24:27]
	v_mfma_f32_16x16x32_bf16 v[20:23], v[186:189], v[220:223], v[20:23]
	v_mfma_f32_16x16x32_bf16 v[8:11], v[178:181], v[228:231], v[8:11]
	v_mfma_f32_16x16x32_bf16 v[4:7], v[186:189], v[228:231], v[4:7]
	v_mfma_f32_16x16x32_bf16 v[56:59], v[182:185], v[198:201], v[56:59]
	v_mfma_f32_16x16x32_bf16 v[52:55], v[190:193], v[198:201], v[52:55]
	v_mfma_f32_16x16x32_bf16 v[40:43], v[182:185], v[216:219], v[40:43]
	v_mfma_f32_16x16x32_bf16 v[36:39], v[190:193], v[216:219], v[36:39]
	v_mfma_f32_16x16x32_bf16 v[24:27], v[182:185], v[224:227], v[24:27]
	v_mfma_f32_16x16x32_bf16 v[20:23], v[190:193], v[224:227], v[20:23]
	v_mfma_f32_16x16x32_bf16 v[8:11], v[182:185], v[232:235], v[8:11]
	v_mfma_f32_16x16x32_bf16 v[4:7], v[190:193], v[232:235], v[4:7]
	s_barrier
	s_add_i32 s84, 0, 0x18000
	v_add_u32_e32 v163, s84, v157
	s_add_i32 s85, 0, 0x1c000
	ds_read_b128 v[146:149], v163
	ds_read_b128 v[164:167], v163 offset:1024
	ds_read_b128 v[170:173], v163 offset:2048
	ds_read_b128 v[174:177], v163 offset:3072
	v_add_u32_e32 v163, s85, v157
	ds_read_b128 v[178:181], v163
	ds_read_b128 v[182:185], v163 offset:1024
	ds_read_b128 v[186:189], v163 offset:2048
	ds_read_b128 v[190:193], v163 offset:3072
	s_add_u32 s54, s54, 0x40000
	s_addc_u32 s55, s55, 0
	s_mov_b32 m0, s65
	v_lshl_add_u64 v[244:245], s[54:55], 0, v[140:141]
	ds_read_b128 v[194:197], v162 offset:32768
	ds_read_b128 v[198:201], v162 offset:33792
	ds_read_b128 v[212:215], v162 offset:34816
	ds_read_b128 v[216:219], v162 offset:35840
	ds_read_b128 v[220:223], v162 offset:36864
	ds_read_b128 v[224:227], v162 offset:37888
	ds_read_b128 v[228:231], v162 offset:38912
	ds_read_b128 v[232:235], v162 offset:39936
	s_cmp_lg_u32 s32, 0
	s_cbranch_scc1 .Lbt3_6
	global_load_lds_dwordx4 v[244:245], off

; #define PG8_STAGE(bufoff, gbase, voff) do { _Pragma("unroll") for (int _i = 0; _i < 2; ++_i) \
;         __builtin_amdgcn_global_load_lds((const unsigned*)((const char*)(gbase) + (voff)[_i]), (PG8_LAS unsigned*)(lds + (bufoff) + ldsw + _i * 8192), 16, 0, 0); } while (0)
; #define PG8_LDA(dst, b, h) do { _Pragma("unroll") for (int m = 0; m < 4; ++m) _Pragma("unroll") for (int k = 0; k < 2; ++k) dst[m][k] = *(const PG8_LAS bf16x8*)(lds + PG8_SA(b, h) + aoff + m * 2048 + k * 1024); } while (0)
; #define PG8_MMA(ai, bj, At, Bt) do { __builtin_amdgcn_s_setprio(1); _Pragma("unroll") for (int m = 0; m < 4; ++m) _Pragma("unroll") for (int n = 0; n < 2; ++n) _Pragma("unroll") for (int k = 0; k < 2; ++k) \
;         acc[ai][bj][m][n] = __builtin_amdgcn_mfma_f32_16x16x32_bf16(Bt[n][k], At[m][k], acc[ai][bj][m][n], 0, 0, 0); __builtin_amdgcn_s_setprio(0); } while (0)
; #define PG8_WAIT_V(n) asm volatile("s_waitcnt vmcnt(" #n ")" ::: "memory")
; #define PG8_WAIT_L(n) asm volatile("s_waitcnt lgkmcnt(" #n ")" ::: "memory")
; #define PG8_BAR __builtin_amdgcn_s_barrier()
; #define PG8_SCHED __builtin_amdgcn_sched_barrier(0)
; template <class Epi, class Sched, bool ALIGN_EPI = false, bool SP2 = false>
; __device__ __forceinline__ void gemm_phase(PG8_LAS unsigned char* lds, const Gemm g, const Sched& S, const Epi& E, const int tid) {
;     ...
;             PG8_WAIT_V(8); PG8_WAIT_L(0); PG8_BAR; PG8_MMA(0, 0, At, B0); PG8_MMA(0, 1, At, B1); PG8_BAR; PG8_SCHED;
;             PG8_LDA(At, 1, 1); PG8_STAGE(PG8_SB(1, 0), b3, voffB); PG8_STAGE(PG8_SB(1, 1), b3 + hstepB, voffB); PG8_STAGE(PG8_SA(1, 0), a3, voffA);
.Lbw3_0:
	s_waitcnt lgkmcnt(0)
	s_barrier
	s_waitcnt lgkmcnt(0)
	v_mfma_f32_16x16x32_bf16 v[128:131], v[146:149], v[194:197], v[128:131]
	v_mfma_f32_16x16x32_bf16 v[124:127], v[170:173], v[194:197], v[124:127]
	v_mfma_f32_16x16x32_bf16 v[112:115], v[146:149], v[212:215], v[112:115]
	v_mfma_f32_16x16x32_bf16 v[108:111], v[170:173], v[212:215], v[108:111]
	v_mfma_f32_16x16x32_bf16 v[96:99], v[146:149], v[220:223], v[96:99]
	v_mfma_f32_16x16x32_bf16 v[92:95], v[170:173], v[220:223], v[92:95]
	v_mfma_f32_16x16x32_bf16 v[80:83], v[146:149], v[228:231], v[80:83]
	v_mfma_f32_16x16x32_bf16 v[76:79], v[170:173], v[228:231], v[76:79]
	v_mfma_f32_16x16x32_bf16 v[128:131], v[164:167], v[198:201], v[128:131]
	v_mfma_f32_16x16x32_bf16 v[124:127], v[174:177], v[198:201], v[124:127]
	v_mfma_f32_16x16x32_bf16 v[112:115], v[164:167], v[216:219], v[112:115]
	v_mfma_f32_16x16x32_bf16 v[108:111], v[174:177], v[216:219], v[108:111]
	v_mfma_f32_16x16x32_bf16 v[96:99], v[164:167], v[224:227], v[96:99]
	v_mfma_f32_16x16x32_bf16 v[92:95], v[174:177], v[224:227], v[92:95]
	v_mfma_f32_16x16x32_bf16 v[80:83], v[164:167], v[232:235], v[80:83]
	v_mfma_f32_16x16x32_bf16 v[76:79], v[174:177], v[232:235], v[76:79]
	v_mfma_f32_16x16x32_bf16 v[120:123], v[178:181], v[194:197], v[120:123]
	v_mfma_f32_16x16x32_bf16 v[116:119], v[186:189], v[194:197], v[116:119]
	v_mfma_f32_16x16x32_bf16 v[104:107], v[178:181], v[212:215], v[104:107]
	v_mfma_f32_16x16x32_bf16 v[100:103], v[186:189], v[212:215], v[100:103]
	v_mfma_f32_16x16x32_bf16 v[88:91], v[178:181], v[220:223], v[88:91]
	v_mfma_f32_16x16x32_bf16 v[84:87], v[186:189], v[220:223], v[84:87]
	v_mfma_f32_16x16x32_bf16 v[72:75], v[178:181], v[228:231], v[72:75]
	v_mfma_f32_16x16x32_bf16 v[68:71], v[186:189], v[228:231], v[68:71]
	v_mfma_f32_16x16x32_bf16 v[120:123], v[182:185], v[198:201], v[120:123]
	v_mfma_f32_16x16x32_bf16 v[116:119], v[190:193], v[198:201], v[116:119]
	v_mfma_f32_16x16x32_bf16 v[104:107], v[182:185], v[216:219], v[104:107]
	v_mfma_f32_16x16x32_bf16 v[100:103], v[190:193], v[216:219], v[100:103]
	v_mfma_f32_16x16x32_bf16 v[88:91], v[182:185], v[224:227], v[88:91]
	v_mfma_f32_16x16x32_bf16 v[84:87], v[190:193], v[224:227], v[84:87]
	v_mfma_f32_16x16x32_bf16 v[72:75], v[182:185], v[232:235], v[72:75]
	v_mfma_f32_16x16x32_bf16 v[68:71], v[190:193], v[232:235], v[68:71]
	s_barrier
	s_add_i32 s54, s84, s63
	v_lshl_add_u64 v[236:237], v[236:237], 0, s[52:53]
	s_mov_b32 m0, s54
	ds_read_b128 v[194:197], v162 offset:49152
	ds_read_b128 v[198:201], v162 offset:50176
	ds_read_b128 v[212:215], v162 offset:51200
	ds_read_b128 v[216:219], v162 offset:52224
	ds_read_b128 v[220:223], v162 offset:53248
	ds_read_b128 v[224:227], v162 offset:54272
	ds_read_b128 v[228:231], v162 offset:55296
	ds_read_b128 v[232:235], v162 offset:56320
	s_cmp_lg_u32 s32, 0
	s_cbranch_scc1 .Lbt3_8
	global_load_lds_dwordx4 v[236:237], off

; #define PG8_STAGE(bufoff, gbase, voff) do { _Pragma("unroll") for (int _i = 0; _i < 2; ++_i) \
;         __builtin_amdgcn_global_load_lds((const unsigned*)((const char*)(gbase) + (voff)[_i]), (PG8_LAS unsigned*)(lds + (bufoff) + ldsw + _i * 8192), 16, 0, 0); } while (0)
; #define PG8_LDA(dst, b, h) do { _Pragma("unroll") for (int m = 0; m < 4; ++m) _Pragma("unroll") for (int k = 0; k < 2; ++k) dst[m][k] = *(const PG8_LAS bf16x8*)(lds + PG8_SA(b, h) + aoff + m * 2048 + k * 1024); } while (0)
; #define PG8_MMA(ai, bj, At, Bt) do { __builtin_amdgcn_s_setprio(1); _Pragma("unroll") for (int m = 0; m < 4; ++m) _Pragma("unroll") for (int n = 0; n < 2; ++n) _Pragma("unroll") for (int k = 0; k < 2; ++k) \
;         acc[ai][bj][m][n] = __builtin_amdgcn_mfma_f32_16x16x32_bf16(Bt[n][k], At[m][k], acc[ai][bj][m][n], 0, 0, 0); __builtin_amdgcn_s_setprio(0); } while (0)
; #define PG8_WAIT_V(n) asm volatile("s_waitcnt vmcnt(" #n ")" ::: "memory")
; #define PG8_WAIT_L(n) asm volatile("s_waitcnt lgkmcnt(" #n ")" ::: "memory")
; #define PG8_BAR __builtin_amdgcn_s_barrier()
; #define PG8_SCHED __builtin_amdgcn_sched_barrier(0)
; template <class Epi, class Sched, bool ALIGN_EPI = false, bool SP2 = false>
; __device__ __forceinline__ void gemm_phase(PG8_LAS unsigned char* lds, const Gemm g, const Sched& S, const Epi& E, const int tid) {
;     ...
;         for (int t = 0; t < nt; t += 2) {
;             const bool last = (t == nt - 2);
;             const char* a1 = cA + (size_t)(t + 1) * kstep;
;             const char* a2 = last ? nA : cA + (size_t)(t + 2) * kstep; const char* b2 = last ? nB : cB + (size_t)(t + 2) * kstep;
;             const char* a3 = a2 + kstep; const char* b3 = b2 + kstep;
;     ...
;             PG8_LDA(At, 1, 1); PG8_STAGE(PG8_SB(1, 0), b3, voffB); PG8_STAGE(PG8_SB(1, 1), b3 + hstepB, voffB); PG8_STAGE(PG8_SA(1, 0), a3, voffA);
;             PG8_WAIT_V(8); PG8_WAIT_L(0); PG8_BAR; PG8_MMA(1, 0, At, B0); PG8_MMA(1, 1, At, B1); PG8_BAR; PG8_SCHED;
.Lbt3_13:
	s_waitcnt vmcnt(8)
	s_waitcnt lgkmcnt(0)
	s_barrier
	s_waitcnt lgkmcnt(0)
	v_mfma_f32_16x16x32_bf16 v[64:67], v[146:149], v[194:197], v[64:67]
	v_mfma_f32_16x16x32_bf16 v[60:63], v[170:173], v[194:197], v[60:63]
	v_mfma_f32_16x16x32_bf16 v[48:51], v[146:149], v[212:215], v[48:51]
	v_mfma_f32_16x16x32_bf16 v[44:47], v[170:173], v[212:215], v[44:47]
	v_mfma_f32_16x16x32_bf16 v[32:35], v[146:149], v[220:223], v[32:35]
	v_mfma_f32_16x16x32_bf16 v[28:31], v[170:173], v[220:223], v[28:31]
	v_mfma_f32_16x16x32_bf16 v[16:19], v[146:149], v[228:231], v[16:19]
	v_mfma_f32_16x16x32_bf16 v[12:15], v[170:173], v[228:231], v[12:15]
	v_mfma_f32_16x16x32_bf16 v[64:67], v[164:167], v[198:201], v[64:67]
	v_mfma_f32_16x16x32_bf16 v[60:63], v[174:177], v[198:201], v[60:63]
	v_mfma_f32_16x16x32_bf16 v[48:51], v[164:167], v[216:219], v[48:51]
	v_mfma_f32_16x16x32_bf16 v[44:47], v[174:177], v[216:219], v[44:47]
	v_mfma_f32_16x16x32_bf16 v[32:35], v[164:167], v[224:227], v[32:35]
	v_mfma_f32_16x16x32_bf16 v[28:31], v[174:177], v[224:227], v[28:31]
	v_mfma_f32_16x16x32_bf16 v[16:19], v[164:167], v[232:235], v[16:19]
	v_mfma_f32_16x16x32_bf16 v[12:15], v[174:177], v[232:235], v[12:15]
	v_mfma_f32_16x16x32_bf16 v[56:59], v[178:181], v[194:197], v[56:59]
	v_mfma_f32_16x16x32_bf16 v[52:55], v[186:189], v[194:197], v[52:55]
	v_mfma_f32_16x16x32_bf16 v[40:43], v[178:181], v[212:215], v[40:43]
	v_mfma_f32_16x16x32_bf16 v[36:39], v[186:189], v[212:215], v[36:39]
	v_mfma_f32_16x16x32_bf16 v[24:27], v[178:181], v[220:223], v[24:27]
	v_mfma_f32_16x16x32_bf16 v[20:23], v[186:189], v[220:223], v[20:23]
	v_mfma_f32_16x16x32_bf16 v[8:11], v[178:181], v[228:231], v[8:11]
	v_mfma_f32_16x16x32_bf16 v[4:7], v[186:189], v[228:231], v[4:7]
	v_mfma_f32_16x16x32_bf16 v[56:59], v[182:185], v[198:201], v[56:59]
	v_mfma_f32_16x16x32_bf16 v[52:55], v[190:193], v[198:201], v[52:55]
	v_mfma_f32_16x16x32_bf16 v[40:43], v[182:185], v[216:219], v[40:43]
	v_mfma_f32_16x16x32_bf16 v[36:39], v[190:193], v[216:219], v[36:39]
	v_mfma_f32_16x16x32_bf16 v[24:27], v[182:185], v[224:227], v[24:27]
	v_mfma_f32_16x16x32_bf16 v[20:23], v[190:193], v[224:227], v[20:23]
	v_mfma_f32_16x16x32_bf16 v[8:11], v[182:185], v[232:235], v[8:11]
	v_mfma_f32_16x16x32_bf16 v[4:7], v[190:193], v[232:235], v[4:7]
	s_barrier
	s_add_i32 s83, s83, 2
	s_add_u32 s40, s40, 0x100
	s_addc_u32 s41, s41, 0
	s_add_u32 s81, s81, 0x100
	s_addc_u32 s82, s82, 0
	s_cmp_gt_u32 s83, 13
	s_cbranch_scc0 .LBB0_1108
	s_and_b64 vcc, exec, s[18:19]
	s_cbranch_vccz .LBB0_1111
	s_barrier

; DI float bf_lo(unsigned u) { return __uint_as_float(u << 16); }
; DI float bf_hi(unsigned u) { return __uint_as_float(u & 0xffff0000u); }
; #define PG8_STAGE(bufoff, gbase, voff) do { _Pragma("unroll") for (int _i = 0; _i < 2; ++_i) \
;         __builtin_amdgcn_global_load_lds((const unsigned*)((const char*)(gbase) + (voff)[_i]), (PG8_LAS unsigned*)(lds + (bufoff) + ldsw + _i * 8192), 16, 0, 0); } while (0)
; #define PG8_WAIT_V(n) asm volatile("s_waitcnt vmcnt(" #n ")" ::: "memory")
; #define PG8_BAR __builtin_amdgcn_s_barrier()
;     DI void init_finish(f32x4 (&acc)[2][2][4][2], const u32x4 (&w)[R8::HAS_PRE ? 16 : 1]) const {
;         if constexpr (R8::HAS_PRE) {
; #pragma unroll
;             for (int ai = 0; ai < 2; ++ai)
; #pragma unroll
;                 for (int m = 0; m < 4; ++m)
; #pragma unroll
;                     for (int bj = 0; bj < 2; ++bj) { const u32x4 v = w[(ai * 4 + m) * 2 + bj];
;                         acc[ai][bj][m][0] = (f32x4){bf_lo(v.x), bf_hi(v.x), bf_lo(v.y), bf_hi(v.y)}; acc[ai][bj][m][1] = (f32x4){bf_lo(v.z), bf_hi(v.z), bf_lo(v.w), bf_hi(v.w)}; }
;         }
;     }
; template <class Epi, class Sched, bool ALIGN_EPI = false, bool SP2 = false>
; __device__ __forceinline__ void gemm_phase(PG8_LAS unsigned char* lds, const Gemm g, const Sched& S, const Epi& E, const int tid) {
;     ...
;     if constexpr (SP2) {
;         PG8_STAGE(PG8_SB(0, 0), cB, voffB); PG8_STAGE(PG8_SB(0, 1), cB + hstepB, voffB); PG8_STAGE(PG8_SA(0, 0), cA, voffA); PG8_STAGE(PG8_SA(0, 1), cA + hstep, voffA);
;         if (wr == 1) PG8_BAR;
;         PG8_WAIT_V(2); PG8_BAR;
;         PG8_STAGE(PG8_SB(1, 0), cB + kstep, voffB); PG8_STAGE(PG8_SA(1, 0), cA + kstep, voffA); PG8_STAGE(PG8_SB(1, 1), cB + hstepB + kstep, voffB);
;         PG8_WAIT_V(6); PG8_BAR;
;     } else {
;         PG8_STAGE(PG8_SB(0, 0), cB, voffB); PG8_STAGE(PG8_SA(0, 0), cA, voffA); PG8_STAGE(PG8_SB(0, 1), cB + hstepB, voffB); PG8_STAGE(PG8_SA(0, 1), cA + hstep, voffA);
;         if (wr == 1) PG8_BAR;
;         PG8_WAIT_V(4); PG8_BAR;
;         PG8_STAGE(PG8_SB(1, 0), cB + kstep, voffB); PG8_STAGE(PG8_SA(1, 0), cA + kstep, voffA); PG8_STAGE(PG8_SB(1, 1), cB + hstepB + kstep, voffB);
;         PG8_WAIT_V(6); PG8_BAR;
;     }
;     if constexpr (Epi::HAS_INIT) E.init_finish(acc, iw_);
.LBB0_1260:
	v_or_b32_e32 v157, s17, v152
	v_lshlrev_b32_e32 v76, 6, v157
	v_lshlrev_b32_e32 v77, 4, v146
	s_movk_i32 s17, 0x3c0
	v_lshlrev_b32_e32 v78, 2, v157
	v_and_or_b32 v76, v76, s17, v77
	s_lshl_b32 s5, s5, 13
	v_and_b32_e32 v78, 32, v78
	v_bitop3_b32 v149, v76, s5, v78 bitop3:0xde
	v_lshl_or_b32 v76, v152, 6, v77
	v_lshlrev_b32_e32 v77, 2, v152
	s_add_i32 m0, s31, 0x18000
	v_lshl_add_u64 v[74:75], v[74:75], 0, s[52:53]
	s_lshl_b32 s4, s4, 12
	v_and_b32_e32 v77, 32, v77
	s_waitcnt vmcnt(2)
	s_barrier
	global_load_lds_dwordx4 v[74:75], off
	v_lshl_add_u64 v[72:73], v[72:73], 0, s[52:53]
	s_add_i32 m0, s31, 0x1a000
	s_add_i32 s66, s31, 0x8000
	s_add_i32 s67, s31, 0xa000
	v_bitop3_b32 v158, v76, s4, v77 bitop3:0xde
	global_load_lds_dwordx4 v[72:73], off
	v_lshl_add_u64 v[68:69], v[68:69], 0, s[52:53]
	s_mov_b32 m0, s66
	s_add_u32 s4, s38, 0x10080
	global_load_lds_dwordx4 v[68:69], off
	v_lshl_add_u64 v[68:69], v[70:71], 0, s[52:53]
	s_mov_b32 m0, s67
	s_addc_u32 s5, s39, 0
	global_load_lds_dwordx4 v[68:69], off
	s_add_i32 m0, s31, 0x1c000
	v_lshl_add_u64 v[68:69], s[4:5], 0, v[136:137]
	global_load_lds_dwordx4 v[68:69], off
	v_lshl_add_u64 v[68:69], s[4:5], 0, v[140:141]
	s_add_i32 m0, s31, 0x1e000
	v_cmp_eq_u32_e64 s[4:5], 0, v146
	global_load_lds_dwordx4 v[68:69], off
	v_lshlrev_b32_e32 v146, 14, v142
	v_and_b32_e32 v146, 0xffff8000, v146
	v_lshl_add_u32 v143, v143, 11, v146
	v_and_b32_e32 v142, 1, v142
	v_lshl_or_b32 v142, v142, 6, v143
	v_lshl_add_u32 v142, v144, 1, v142
	v_lshlrev_b32_e32 v144, 14, v145
	v_and_b32_e32 v144, 0xffff8000, v144
	s_waitcnt vmcnt(6)
	v_lshl_add_u32 v144, v147, 11, v144
	v_and_b32_e32 v145, 1, v145
	s_cmpk_lt_u32 s16, 0x100
	v_lshl_or_b32 v144, v145, 6, v144
	s_waitcnt vmcnt(0)
	v_lshlrev_b32_e32 v120, 16, v64
	v_and_b32_e32 v121, 0xffff0000, v64
	v_lshlrev_b32_e32 v122, 16, v65
	v_and_b32_e32 v123, 0xffff0000, v65
	v_lshlrev_b32_e32 v128, 16, v66
	v_and_b32_e32 v129, 0xffff0000, v66
	v_lshlrev_b32_e32 v130, 16, v67
	v_and_b32_e32 v131, 0xffff0000, v67
	v_lshlrev_b32_e32 v116, 16, v56
	v_and_b32_e32 v117, 0xffff0000, v56
	v_lshlrev_b32_e32 v118, 16, v57
	v_and_b32_e32 v119, 0xffff0000, v57
	v_lshlrev_b32_e32 v124, 16, v58
	v_and_b32_e32 v125, 0xffff0000, v58
	v_lshlrev_b32_e32 v126, 16, v59
	v_and_b32_e32 v127, 0xffff0000, v59
	v_lshlrev_b32_e32 v100, 16, v60
	v_and_b32_e32 v101, 0xffff0000, v60
	v_lshlrev_b32_e32 v102, 16, v61
	v_and_b32_e32 v103, 0xffff0000, v61
	v_lshlrev_b32_e32 v108, 16, v62
	v_and_b32_e32 v109, 0xffff0000, v62
	v_lshlrev_b32_e32 v110, 16, v63
	v_and_b32_e32 v111, 0xffff0000, v63
	v_lshlrev_b32_e32 v104, 16, v48
	v_and_b32_e32 v105, 0xffff0000, v48
	v_lshlrev_b32_e32 v106, 16, v49
	v_and_b32_e32 v107, 0xffff0000, v49
	v_lshlrev_b32_e32 v112, 16, v50
	v_and_b32_e32 v113, 0xffff0000, v50
	v_lshlrev_b32_e32 v114, 16, v51
	v_and_b32_e32 v115, 0xffff0000, v51
	v_lshlrev_b32_e32 v84, 16, v52
	v_and_b32_e32 v85, 0xffff0000, v52
	v_lshlrev_b32_e32 v86, 16, v53
	v_and_b32_e32 v87, 0xffff0000, v53
	v_lshlrev_b32_e32 v92, 16, v54
	v_and_b32_e32 v93, 0xffff0000, v54
	v_lshlrev_b32_e32 v94, 16, v55
	v_and_b32_e32 v95, 0xffff0000, v55
	v_lshlrev_b32_e32 v88, 16, v40
	v_and_b32_e32 v89, 0xffff0000, v40
	v_lshlrev_b32_e32 v90, 16, v41
	v_and_b32_e32 v91, 0xffff0000, v41
	v_lshlrev_b32_e32 v96, 16, v42
	v_and_b32_e32 v97, 0xffff0000, v42
	v_lshlrev_b32_e32 v98, 16, v43
	v_and_b32_e32 v99, 0xffff0000, v43
	v_lshlrev_b32_e32 v68, 16, v44
	v_and_b32_e32 v69, 0xffff0000, v44
	v_lshlrev_b32_e32 v70, 16, v45
	v_and_b32_e32 v71, 0xffff0000, v45
	v_lshlrev_b32_e32 v76, 16, v46
	v_and_b32_e32 v77, 0xffff0000, v46
	v_lshlrev_b32_e32 v78, 16, v47
	v_and_b32_e32 v79, 0xffff0000, v47
	v_lshlrev_b32_e32 v72, 16, v36
	v_and_b32_e32 v73, 0xffff0000, v36
	v_lshlrev_b32_e32 v74, 16, v37
	v_and_b32_e32 v75, 0xffff0000, v37
	v_lshlrev_b32_e32 v80, 16, v38
	v_and_b32_e32 v81, 0xffff0000, v38
	v_lshlrev_b32_e32 v82, 16, v39
	v_and_b32_e32 v83, 0xffff0000, v39
	v_lshlrev_b32_e32 v52, 16, v32
	v_and_b32_e32 v53, 0xffff0000, v32
	v_lshlrev_b32_e32 v54, 16, v33
	v_and_b32_e32 v55, 0xffff0000, v33
	v_lshlrev_b32_e32 v60, 16, v34
	v_and_b32_e32 v61, 0xffff0000, v34
	v_lshlrev_b32_e32 v62, 16, v35
	v_and_b32_e32 v63, 0xffff0000, v35
	v_lshlrev_b32_e32 v56, 16, v28
	v_and_b32_e32 v57, 0xffff0000, v28
	v_lshlrev_b32_e32 v58, 16, v29
	v_and_b32_e32 v59, 0xffff0000, v29
	v_lshlrev_b32_e32 v64, 16, v30
	v_and_b32_e32 v65, 0xffff0000, v30
	v_lshlrev_b32_e32 v66, 16, v31
	v_and_b32_e32 v67, 0xffff0000, v31
	v_lshlrev_b32_e32 v36, 16, v24
	v_and_b32_e32 v37, 0xffff0000, v24
	v_lshlrev_b32_e32 v38, 16, v25
	v_and_b32_e32 v39, 0xffff0000, v25
	v_lshlrev_b32_e32 v44, 16, v26
	v_and_b32_e32 v45, 0xffff0000, v26
	v_lshlrev_b32_e32 v46, 16, v27
	v_and_b32_e32 v47, 0xffff0000, v27
	v_lshlrev_b32_e32 v40, 16, v20
	v_and_b32_e32 v41, 0xffff0000, v20
	v_lshlrev_b32_e32 v42, 16, v21
	v_and_b32_e32 v43, 0xffff0000, v21
	v_lshlrev_b32_e32 v48, 16, v22
	v_and_b32_e32 v49, 0xffff0000, v22
	v_lshlrev_b32_e32 v50, 16, v23
	v_and_b32_e32 v51, 0xffff0000, v23
	v_lshlrev_b32_e32 v20, 16, v12
	v_and_b32_e32 v21, 0xffff0000, v12
	v_lshlrev_b32_e32 v22, 16, v13
	v_and_b32_e32 v23, 0xffff0000, v13
	v_lshlrev_b32_e32 v28, 16, v14
	v_and_b32_e32 v29, 0xffff0000, v14
	v_lshlrev_b32_e32 v30, 16, v15
	v_and_b32_e32 v31, 0xffff0000, v15
	v_lshlrev_b32_e32 v24, 16, v4
	v_and_b32_e32 v25, 0xffff0000, v4
	v_lshlrev_b32_e32 v26, 16, v5
	v_and_b32_e32 v27, 0xffff0000, v5
	v_lshlrev_b32_e32 v32, 16, v6
	v_and_b32_e32 v33, 0xffff0000, v6
	v_lshlrev_b32_e32 v34, 16, v7
	v_and_b32_e32 v35, 0xffff0000, v7
	v_lshlrev_b32_e32 v4, 16, v8
	v_and_b32_e32 v5, 0xffff0000, v8
	v_lshlrev_b32_e32 v6, 16, v9
	v_and_b32_e32 v7, 0xffff0000, v9
	v_lshlrev_b32_e32 v12, 16, v10
	v_and_b32_e32 v13, 0xffff0000, v10
	v_lshlrev_b32_e32 v14, 16, v11
	v_and_b32_e32 v15, 0xffff0000, v11
	v_lshlrev_b32_e32 v8, 16, v16
	v_and_b32_e32 v9, 0xffff0000, v16
	v_lshlrev_b32_e32 v10, 16, v17
	v_and_b32_e32 v11, 0xffff0000, v17
	v_lshlrev_b32_e32 v16, 16, v18
	v_and_b32_e32 v17, 0xffff0000, v18
	v_lshlrev_b32_e32 v18, 16, v19
	v_and_b32_e32 v19, 0xffff0000, v19
	s_cselect_b64 s[16:17], -1, 0
	s_mov_b32 s76, 0
	s_lshl_b32 s78, s27, 3
	v_or_b32_e32 v159, s62, v156
	v_mov_b32_e32 v143, v2
	v_lshl_add_u32 v144, v148, 1, v144
	v_mov_b32_e32 v145, v2
	v_add_u32_e32 v160, 0, v149
	s_barrier
	v_readfirstlane_b32 s98, v0
	s_nop 3
	s_and_b32 s98, s98, 0x3ff
	s_lshr_b32 s98, s98, 6
	s_cmp_ge_u32 s98, 4
	s_cbranch_scc0 .Lprio_done4
	s_setprio 1
; DI float bf_lo(unsigned u) { return __uint_as_float(u << 16); }
; DI float bf_hi(unsigned u) { return __uint_as_float(u & 0xffff0000u); }
;     DI void init_finish(f32x4 (&acc)[2][2][4][2], const u32x4 (&w)[R8::HAS_PRE ? 16 : 1]) const {
;         if constexpr (R8::HAS_PRE) {
; #pragma unroll
;             for (int ai = 0; ai < 2; ++ai)
; #pragma unroll
;                 for (int m = 0; m < 4; ++m)
; #pragma unroll
;                     for (int bj = 0; bj < 2; ++bj) { const u32x4 v = w[(ai * 4 + m) * 2 + bj];
;                         acc[ai][bj][m][0] = (f32x4){bf_lo(v.x), bf_hi(v.x), bf_lo(v.y), bf_hi(v.y)}; acc[ai][bj][m][1] = (f32x4){bf_lo(v.z), bf_hi(v.z), bf_lo(v.w), bf_hi(v.w)}; }
;         }
;     }
;     DI void init(f32x4 (&acc)[2][2][4][2], const Unit& u, int wr, int wc, int fr, int fq) const { u32x4 w[R8::HAS_PRE ? 16 : 1]; init_issue(w, u, wr, wc, fr, fq); init_finish(acc, w); }
; template <class Epi, class Sched, bool ALIGN_EPI = false, bool SP2 = false>
; __device__ __forceinline__ void gemm_phase(PG8_LAS unsigned char* lds, const Gemm g, const Sched& S, const Epi& E, const int tid) {
;     ...
;         if constexpr (!Epi::AFTER_DRAIN) { E(acc, cur, wr, wc, fr, fq); S.done(cur); }
;         if (!has_next) break;
;         if constexpr (Epi::HAS_INIT) E.init(acc, nxt, wr, wc, fr, fq);
.Lprio_done4:
	s_branch .LBB0_1263
.LBB0_1261:
	s_waitcnt vmcnt(0)
	v_lshlrev_b32_e32 v120, 16, v66
	v_and_b32_e32 v121, 0xffff0000, v66
	v_lshlrev_b32_e32 v122, 16, v67
	v_and_b32_e32 v123, 0xffff0000, v67
	v_lshlrev_b32_e32 v128, 16, v68
	v_and_b32_e32 v129, 0xffff0000, v68
	v_lshlrev_b32_e32 v130, 16, v69
	v_and_b32_e32 v131, 0xffff0000, v69
	v_lshlrev_b32_e32 v116, 16, v58
	v_and_b32_e32 v117, 0xffff0000, v58
	v_lshlrev_b32_e32 v118, 16, v59
	v_and_b32_e32 v119, 0xffff0000, v59
	v_lshlrev_b32_e32 v124, 16, v60
	v_and_b32_e32 v125, 0xffff0000, v60
	v_lshlrev_b32_e32 v126, 16, v61
	v_and_b32_e32 v127, 0xffff0000, v61
	v_lshlrev_b32_e32 v100, 16, v62
	v_and_b32_e32 v101, 0xffff0000, v62
	v_lshlrev_b32_e32 v102, 16, v63
	v_and_b32_e32 v103, 0xffff0000, v63
	v_lshlrev_b32_e32 v108, 16, v64
	v_and_b32_e32 v109, 0xffff0000, v64
	v_lshlrev_b32_e32 v110, 16, v65
	v_and_b32_e32 v111, 0xffff0000, v65
	v_lshlrev_b32_e32 v104, 16, v50
	v_and_b32_e32 v105, 0xffff0000, v50
	v_lshlrev_b32_e32 v106, 16, v51
	v_and_b32_e32 v107, 0xffff0000, v51
	v_lshlrev_b32_e32 v112, 16, v52
	v_and_b32_e32 v113, 0xffff0000, v52
	v_lshlrev_b32_e32 v114, 16, v53
	v_and_b32_e32 v115, 0xffff0000, v53
	v_lshlrev_b32_e32 v84, 16, v54
	v_and_b32_e32 v85, 0xffff0000, v54
	v_lshlrev_b32_e32 v86, 16, v55
	v_and_b32_e32 v87, 0xffff0000, v55
	v_lshlrev_b32_e32 v92, 16, v56
	v_and_b32_e32 v93, 0xffff0000, v56
	v_lshlrev_b32_e32 v94, 16, v57
	v_and_b32_e32 v95, 0xffff0000, v57
	v_lshlrev_b32_e32 v88, 16, v42
	v_and_b32_e32 v89, 0xffff0000, v42
	v_lshlrev_b32_e32 v90, 16, v43
	v_and_b32_e32 v91, 0xffff0000, v43
	v_lshlrev_b32_e32 v96, 16, v44
	v_and_b32_e32 v97, 0xffff0000, v44
	v_lshlrev_b32_e32 v98, 16, v45
	v_and_b32_e32 v99, 0xffff0000, v45
	v_lshlrev_b32_e32 v68, 16, v46
	v_and_b32_e32 v69, 0xffff0000, v46
	v_lshlrev_b32_e32 v70, 16, v47
	v_and_b32_e32 v71, 0xffff0000, v47
	v_lshlrev_b32_e32 v76, 16, v48
	v_and_b32_e32 v77, 0xffff0000, v48
	v_lshlrev_b32_e32 v78, 16, v49
	v_and_b32_e32 v79, 0xffff0000, v49
	v_lshlrev_b32_e32 v72, 16, v34
	v_and_b32_e32 v73, 0xffff0000, v34
	v_lshlrev_b32_e32 v74, 16, v35
	v_and_b32_e32 v75, 0xffff0000, v35
	v_lshlrev_b32_e32 v80, 16, v36
	v_and_b32_e32 v81, 0xffff0000, v36
	v_lshlrev_b32_e32 v82, 16, v37
	v_and_b32_e32 v83, 0xffff0000, v37
	v_lshlrev_b32_e32 v52, 16, v38
	v_and_b32_e32 v53, 0xffff0000, v38
	v_lshlrev_b32_e32 v54, 16, v39
	v_and_b32_e32 v55, 0xffff0000, v39
	v_lshlrev_b32_e32 v60, 16, v40
	v_and_b32_e32 v61, 0xffff0000, v40
	v_lshlrev_b32_e32 v62, 16, v41
	v_and_b32_e32 v63, 0xffff0000, v41
	v_lshlrev_b32_e32 v56, 16, v26
	v_and_b32_e32 v57, 0xffff0000, v26
	v_lshlrev_b32_e32 v58, 16, v27
	v_and_b32_e32 v59, 0xffff0000, v27
	v_lshlrev_b32_e32 v64, 16, v28
	v_and_b32_e32 v65, 0xffff0000, v28
	v_lshlrev_b32_e32 v66, 16, v29
	v_and_b32_e32 v67, 0xffff0000, v29
	v_lshlrev_b32_e32 v36, 16, v30
	v_and_b32_e32 v37, 0xffff0000, v30
	v_lshlrev_b32_e32 v38, 16, v31
	v_and_b32_e32 v39, 0xffff0000, v31
	v_lshlrev_b32_e32 v44, 16, v32
	v_and_b32_e32 v45, 0xffff0000, v32
	v_lshlrev_b32_e32 v46, 16, v33
	v_and_b32_e32 v47, 0xffff0000, v33
	v_lshlrev_b32_e32 v40, 16, v12
	v_and_b32_e32 v41, 0xffff0000, v12
	v_lshlrev_b32_e32 v42, 16, v13
	v_and_b32_e32 v43, 0xffff0000, v13
	v_lshlrev_b32_e32 v48, 16, v14
	v_and_b32_e32 v49, 0xffff0000, v14
	v_lshlrev_b32_e32 v50, 16, v15
	v_and_b32_e32 v51, 0xffff0000, v15
	v_lshlrev_b32_e32 v20, 16, v22
	v_and_b32_e32 v21, 0xffff0000, v22
	v_lshlrev_b32_e32 v22, 16, v23
	v_and_b32_e32 v23, 0xffff0000, v23
	v_lshlrev_b32_e32 v28, 16, v24
	v_and_b32_e32 v29, 0xffff0000, v24
	v_lshlrev_b32_e32 v30, 16, v25
	v_and_b32_e32 v31, 0xffff0000, v25
	v_lshlrev_b32_e32 v24, 16, v4
	v_and_b32_e32 v25, 0xffff0000, v4
	v_lshlrev_b32_e32 v26, 16, v5
	v_and_b32_e32 v27, 0xffff0000, v5
	v_lshlrev_b32_e32 v32, 16, v6
	v_and_b32_e32 v33, 0xffff0000, v6
	v_lshlrev_b32_e32 v34, 16, v7
	v_and_b32_e32 v35, 0xffff0000, v7
	v_lshlrev_b32_e32 v4, 16, v8
	v_and_b32_e32 v5, 0xffff0000, v8
	v_lshlrev_b32_e32 v6, 16, v9
	v_and_b32_e32 v7, 0xffff0000, v9
	v_lshlrev_b32_e32 v12, 16, v10
	v_and_b32_e32 v13, 0xffff0000, v10
	v_lshlrev_b32_e32 v14, 16, v11
	v_and_b32_e32 v15, 0xffff0000, v11
	v_lshlrev_b32_e32 v8, 16, v16
	v_and_b32_e32 v9, 0xffff0000, v16
	v_lshlrev_b32_e32 v10, 16, v17
	v_and_b32_e32 v11, 0xffff0000, v17
	v_lshlrev_b32_e32 v16, 16, v18
	v_and_b32_e32 v17, 0xffff0000, v18
	v_lshlrev_b32_e32 v18, 16, v19
	v_and_b32_e32 v19, 0xffff0000, v19
	s_mov_b64 s[28:29], 0

;     DI bool next(int i, Unit& u) const { const int L = i * 32 + rank; if (L >= ppg * nN) return false; u.pm = ppg * grp + (L % ppg); const int p0 = L / ppg, p1 = p0 + rot; u.pn = rev ? nN - 1 - p0 : (p1 >= nN ? p1 - nN : p1); return true; }
; #define PG8_STAGE(bufoff, gbase, voff) do { _Pragma("unroll") for (int _i = 0; _i < 2; ++_i) \
;         __builtin_amdgcn_global_load_lds((const unsigned*)((const char*)(gbase) + (voff)[_i]), (PG8_LAS unsigned*)(lds + (bufoff) + ldsw + _i * 8192), 16, 0, 0); } while (0)
; #define PG8_LDA(dst, b, h) do { _Pragma("unroll") for (int m = 0; m < 4; ++m) _Pragma("unroll") for (int k = 0; k < 2; ++k) dst[m][k] = *(const PG8_LAS bf16x8*)(lds + PG8_SA(b, h) + aoff + m * 2048 + k * 1024); } while (0)
; #define PG8_LDB(dst, b, h) do { _Pragma("unroll") for (int n = 0; n < 2; ++n) _Pragma("unroll") for (int k = 0; k < 2; ++k) dst[n][k] = *(const PG8_LAS bf16x8*)(lds + PG8_SB(b, h) + boff + n * 2048 + k * 1024); } while (0)
; #define PG8_WAIT_V(n) asm volatile("s_waitcnt vmcnt(" #n ")" ::: "memory")
; #define PG8_WAIT_L(n) asm volatile("s_waitcnt lgkmcnt(" #n ")" ::: "memory")
; template <class Epi, class Sched, bool ALIGN_EPI = false, bool SP2 = false>
; __device__ __forceinline__ void gemm_phase(PG8_LAS unsigned char* lds, const Gemm g, const Sched& S, const Epi& E, const int tid) {
;     ...
;         const bool has_next = S.next(ui + 1, nxt);
;         const char* nA = has_next ? (const char*)g.A + (size_t)nxt.pm * tstep : cA; const char* nB = has_next ? (const char*)g.Bt + (size_t)nxt.pn * tstep : cB;
;         for (int t = 0; t < nt; t += 2) {
;             const bool last = (t == nt - 2);
;             const char* a1 = cA + (size_t)(t + 1) * kstep;
;             const char* a2 = last ? nA : cA + (size_t)(t + 2) * kstep; const char* b2 = last ? nB : cB + (size_t)(t + 2) * kstep;
;             const char* a3 = a2 + kstep; const char* b3 = b2 + kstep;
;             if (last && has_next) S.a_ready(nxt);
;             if constexpr (SP2) {
;             PG8_LDB(B0, 0, 0); PG8_LDB(B1, 0, 1); PG8_SCHED; PG8_LDA(At, 0, 0); PG8_STAGE(PG8_SA(1, 1), a1 + hstep, voffA);
;             PG8_WAIT_V(8); PG8_WAIT_L(0); PG8_BAR; PG8_MMA(0, 0, At, B0); PG8_MMA(0, 1, At, B1); PG8_BAR; PG8_SCHED;
;             PG8_LDA(At, 0, 1); PG8_STAGE(PG8_SB(0, 0), b2, voffB); PG8_STAGE(PG8_SB(0, 1), b2 + hstepB, voffB); PG8_STAGE(PG8_SA(0, 0), a2, voffA);
.LBB0_1266:
	s_add_u32 s38, s40, 0xfffc0080
	s_addc_u32 s39, s41, -1
	s_add_i32 s83, 0, 0x10000
	s_cmp_eq_u32 s82, 12
	s_cselect_b32 s43, s21, s39
	s_cselect_b32 s42, s29, s38
	v_add_u32_e32 v150, s83, v158
	s_cselect_b32 s39, s19, s81
	s_cselect_b32 s38, s79, s80
	s_cmp_eq_u32 s82, 12
	s_cselect_b32 s32, 1, 0
	s_andn2_b32 s32, s32, s36
	s_add_i32 s86, 0, 0x14000
	ds_read_b128 v[146:149], v150
	ds_read_b128 v[162:165], v150 offset:1024
	ds_read_b128 v[170:173], v150 offset:2048
	ds_read_b128 v[174:177], v150 offset:3072
	v_add_u32_e32 v150, s86, v158
	ds_read_b128 v[178:181], v150
	ds_read_b128 v[182:185], v150 offset:1024
	ds_read_b128 v[186:189], v150 offset:2048
	ds_read_b128 v[190:193], v150 offset:3072
	v_lshl_add_u64 v[150:151], s[40:41], 0, v[142:143]
	s_add_i32 m0, s31, 0xc000
	ds_read_b128 v[194:197], v160
	ds_read_b128 v[198:201], v160 offset:1024
	ds_read_b128 v[212:215], v160 offset:2048
	ds_read_b128 v[216:219], v160 offset:3072
	ds_read_b128 v[220:223], v160 offset:4096
	ds_read_b128 v[224:227], v160 offset:5120
	ds_read_b128 v[228:231], v160 offset:6144
	ds_read_b128 v[232:235], v160 offset:7168
	global_load_lds_dwordx4 v[150:151], off
	v_lshl_add_u64 v[150:151], s[40:41], 0, v[144:145]
	s_add_i32 m0, s31, 0xe000
	s_nop 0
	global_load_lds_dwordx4 v[150:151], off
	s_waitcnt vmcnt(8)
	s_waitcnt lgkmcnt(0)
	s_barrier
	s_waitcnt lgkmcnt(0)
	v_mfma_f32_16x16x32_bf16 v[120:123], v[146:149], v[194:197], v[120:123]
	v_mfma_f32_16x16x32_bf16 v[128:131], v[170:173], v[194:197], v[128:131]
	v_mfma_f32_16x16x32_bf16 v[100:103], v[146:149], v[212:215], v[100:103]
	v_mfma_f32_16x16x32_bf16 v[108:111], v[170:173], v[212:215], v[108:111]
	v_mfma_f32_16x16x32_bf16 v[84:87], v[146:149], v[220:223], v[84:87]
	v_mfma_f32_16x16x32_bf16 v[92:95], v[170:173], v[220:223], v[92:95]
	v_mfma_f32_16x16x32_bf16 v[68:71], v[146:149], v[228:231], v[68:71]
	v_mfma_f32_16x16x32_bf16 v[76:79], v[170:173], v[228:231], v[76:79]
	v_mfma_f32_16x16x32_bf16 v[120:123], v[162:165], v[198:201], v[120:123]
	v_mfma_f32_16x16x32_bf16 v[128:131], v[174:177], v[198:201], v[128:131]
	v_mfma_f32_16x16x32_bf16 v[100:103], v[162:165], v[216:219], v[100:103]
	v_mfma_f32_16x16x32_bf16 v[108:111], v[174:177], v[216:219], v[108:111]
	v_mfma_f32_16x16x32_bf16 v[84:87], v[162:165], v[224:227], v[84:87]
	v_mfma_f32_16x16x32_bf16 v[92:95], v[174:177], v[224:227], v[92:95]
	v_mfma_f32_16x16x32_bf16 v[68:71], v[162:165], v[232:235], v[68:71]
	v_mfma_f32_16x16x32_bf16 v[76:79], v[174:177], v[232:235], v[76:79]
	v_mfma_f32_16x16x32_bf16 v[116:119], v[178:181], v[194:197], v[116:119]
	v_mfma_f32_16x16x32_bf16 v[124:127], v[186:189], v[194:197], v[124:127]
	v_mfma_f32_16x16x32_bf16 v[104:107], v[178:181], v[212:215], v[104:107]
	v_mfma_f32_16x16x32_bf16 v[112:115], v[186:189], v[212:215], v[112:115]
	v_mfma_f32_16x16x32_bf16 v[88:91], v[178:181], v[220:223], v[88:91]
	v_mfma_f32_16x16x32_bf16 v[96:99], v[186:189], v[220:223], v[96:99]
	v_mfma_f32_16x16x32_bf16 v[72:75], v[178:181], v[228:231], v[72:75]
	v_mfma_f32_16x16x32_bf16 v[80:83], v[186:189], v[228:231], v[80:83]
	v_mfma_f32_16x16x32_bf16 v[116:119], v[182:185], v[198:201], v[116:119]
	v_mfma_f32_16x16x32_bf16 v[124:127], v[190:193], v[198:201], v[124:127]
	v_mfma_f32_16x16x32_bf16 v[104:107], v[182:185], v[216:219], v[104:107]
	v_mfma_f32_16x16x32_bf16 v[112:115], v[190:193], v[216:219], v[112:115]
	v_mfma_f32_16x16x32_bf16 v[88:91], v[182:185], v[224:227], v[88:91]
	v_mfma_f32_16x16x32_bf16 v[96:99], v[190:193], v[224:227], v[96:99]
	v_mfma_f32_16x16x32_bf16 v[72:75], v[182:185], v[232:235], v[72:75]
	v_mfma_f32_16x16x32_bf16 v[80:83], v[190:193], v[232:235], v[80:83]
	s_barrier
	s_add_i32 s83, s83, s55
	v_lshl_add_u64 v[150:151], s[38:39], 0, v[136:137]
	s_mov_b32 m0, s83
	ds_read_b128 v[194:197], v160 offset:16384
	ds_read_b128 v[198:201], v160 offset:17408
	ds_read_b128 v[212:215], v160 offset:18432
	ds_read_b128 v[216:219], v160 offset:19456
	ds_read_b128 v[220:223], v160 offset:20480
	ds_read_b128 v[224:227], v160 offset:21504
	ds_read_b128 v[228:231], v160 offset:22528
	ds_read_b128 v[232:235], v160 offset:23552
	s_cmp_lg_u32 s32, 0
	s_cbranch_scc1 .Lbt4_0
	global_load_lds_dwordx4 v[150:151], off

; #define PG8_STAGE(bufoff, gbase, voff) do { _Pragma("unroll") for (int _i = 0; _i < 2; ++_i) \
;         __builtin_amdgcn_global_load_lds((const unsigned*)((const char*)(gbase) + (voff)[_i]), (PG8_LAS unsigned*)(lds + (bufoff) + ldsw + _i * 8192), 16, 0, 0); } while (0)
; #define PG8_LDA(dst, b, h) do { _Pragma("unroll") for (int m = 0; m < 4; ++m) _Pragma("unroll") for (int k = 0; k < 2; ++k) dst[m][k] = *(const PG8_LAS bf16x8*)(lds + PG8_SA(b, h) + aoff + m * 2048 + k * 1024); } while (0)
; #define PG8_LDB(dst, b, h) do { _Pragma("unroll") for (int n = 0; n < 2; ++n) _Pragma("unroll") for (int k = 0; k < 2; ++k) dst[n][k] = *(const PG8_LAS bf16x8*)(lds + PG8_SB(b, h) + boff + n * 2048 + k * 1024); } while (0)
; #define PG8_MMA(ai, bj, At, Bt) do { __builtin_amdgcn_s_setprio(1); _Pragma("unroll") for (int m = 0; m < 4; ++m) _Pragma("unroll") for (int n = 0; n < 2; ++n) _Pragma("unroll") for (int k = 0; k < 2; ++k) \
;         acc[ai][bj][m][n] = __builtin_amdgcn_mfma_f32_16x16x32_bf16(Bt[n][k], At[m][k], acc[ai][bj][m][n], 0, 0, 0); __builtin_amdgcn_s_setprio(0); } while (0)
; #define PG8_WAIT_V(n) asm volatile("s_waitcnt vmcnt(" #n ")" ::: "memory")
; #define PG8_WAIT_L(n) asm volatile("s_waitcnt lgkmcnt(" #n ")" ::: "memory")
; #define PG8_BAR __builtin_amdgcn_s_barrier()
; #define PG8_SCHED __builtin_amdgcn_sched_barrier(0)
; template <class Epi, class Sched, bool ALIGN_EPI = false, bool SP2 = false>
; __device__ __forceinline__ void gemm_phase(PG8_LAS unsigned char* lds, const Gemm g, const Sched& S, const Epi& E, const int tid) {
;     ...
;             PG8_WAIT_V(8); PG8_WAIT_L(0); PG8_BAR; PG8_MMA(1, 0, At, B0); PG8_MMA(1, 1, At, B1); PG8_BAR; PG8_SCHED;
;             PG8_LDB(B0, 1, 0); PG8_LDB(B1, 1, 1); PG8_SCHED; PG8_LDA(At, 1, 0); PG8_STAGE(PG8_SA(0, 1), a2 + hstep, voffA);
;             PG8_WAIT_V(8); PG8_WAIT_L(0); PG8_BAR; PG8_MMA(0, 0, At, B0); PG8_MMA(0, 1, At, B1); PG8_BAR; PG8_SCHED;
.Lbw4_2:
	s_waitcnt lgkmcnt(0)
	s_barrier
	s_waitcnt lgkmcnt(0)
	v_mfma_f32_16x16x32_bf16 v[52:55], v[146:149], v[194:197], v[52:55]
	v_mfma_f32_16x16x32_bf16 v[60:63], v[170:173], v[194:197], v[60:63]
	v_mfma_f32_16x16x32_bf16 v[36:39], v[146:149], v[212:215], v[36:39]
	v_mfma_f32_16x16x32_bf16 v[44:47], v[170:173], v[212:215], v[44:47]
	v_mfma_f32_16x16x32_bf16 v[20:23], v[146:149], v[220:223], v[20:23]
	v_mfma_f32_16x16x32_bf16 v[28:31], v[170:173], v[220:223], v[28:31]
	v_mfma_f32_16x16x32_bf16 v[4:7], v[146:149], v[228:231], v[4:7]
	v_mfma_f32_16x16x32_bf16 v[12:15], v[170:173], v[228:231], v[12:15]
	v_mfma_f32_16x16x32_bf16 v[52:55], v[162:165], v[198:201], v[52:55]
	v_mfma_f32_16x16x32_bf16 v[60:63], v[174:177], v[198:201], v[60:63]
	v_mfma_f32_16x16x32_bf16 v[36:39], v[162:165], v[216:219], v[36:39]
	v_mfma_f32_16x16x32_bf16 v[44:47], v[174:177], v[216:219], v[44:47]
	v_mfma_f32_16x16x32_bf16 v[20:23], v[162:165], v[224:227], v[20:23]
	v_mfma_f32_16x16x32_bf16 v[28:31], v[174:177], v[224:227], v[28:31]
	v_mfma_f32_16x16x32_bf16 v[4:7], v[162:165], v[232:235], v[4:7]
	v_mfma_f32_16x16x32_bf16 v[12:15], v[174:177], v[232:235], v[12:15]
	v_mfma_f32_16x16x32_bf16 v[56:59], v[178:181], v[194:197], v[56:59]
	v_mfma_f32_16x16x32_bf16 v[64:67], v[186:189], v[194:197], v[64:67]
	v_mfma_f32_16x16x32_bf16 v[40:43], v[178:181], v[212:215], v[40:43]
	v_mfma_f32_16x16x32_bf16 v[48:51], v[186:189], v[212:215], v[48:51]
	v_mfma_f32_16x16x32_bf16 v[24:27], v[178:181], v[220:223], v[24:27]
	v_mfma_f32_16x16x32_bf16 v[32:35], v[186:189], v[220:223], v[32:35]
	v_mfma_f32_16x16x32_bf16 v[8:11], v[178:181], v[228:231], v[8:11]
	v_mfma_f32_16x16x32_bf16 v[16:19], v[186:189], v[228:231], v[16:19]
	v_mfma_f32_16x16x32_bf16 v[56:59], v[182:185], v[198:201], v[56:59]
	v_mfma_f32_16x16x32_bf16 v[64:67], v[190:193], v[198:201], v[64:67]
	v_mfma_f32_16x16x32_bf16 v[40:43], v[182:185], v[216:219], v[40:43]
	v_mfma_f32_16x16x32_bf16 v[48:51], v[190:193], v[216:219], v[48:51]
	v_mfma_f32_16x16x32_bf16 v[24:27], v[182:185], v[224:227], v[24:27]
	v_mfma_f32_16x16x32_bf16 v[32:35], v[190:193], v[224:227], v[32:35]
	v_mfma_f32_16x16x32_bf16 v[8:11], v[182:185], v[232:235], v[8:11]
	v_mfma_f32_16x16x32_bf16 v[16:19], v[190:193], v[232:235], v[16:19]
	s_barrier
	s_add_i32 s83, 0, 0x18000
	v_add_u32_e32 v161, s83, v158
	s_add_i32 s84, 0, 0x1c000
	ds_read_b128 v[146:149], v161
	ds_read_b128 v[162:165], v161 offset:1024
	ds_read_b128 v[170:173], v161 offset:2048
	ds_read_b128 v[174:177], v161 offset:3072
	v_add_u32_e32 v161, s84, v158
	ds_read_b128 v[178:181], v161
	ds_read_b128 v[182:185], v161 offset:1024
	ds_read_b128 v[186:189], v161 offset:2048
	ds_read_b128 v[190:193], v161 offset:3072
	s_add_u32 s42, s42, 0x40000
	s_addc_u32 s43, s43, 0
	s_mov_b32 m0, s64
	v_lshl_add_u64 v[240:241], s[42:43], 0, v[134:135]
	ds_read_b128 v[194:197], v160 offset:32768
	ds_read_b128 v[198:201], v160 offset:33792
	ds_read_b128 v[212:215], v160 offset:34816
	ds_read_b128 v[216:219], v160 offset:35840
	ds_read_b128 v[220:223], v160 offset:36864
	ds_read_b128 v[224:227], v160 offset:37888
	ds_read_b128 v[228:231], v160 offset:38912
	ds_read_b128 v[232:235], v160 offset:39936
	s_cmp_lg_u32 s32, 0
	s_cbranch_scc1 .Lbt4_6
	global_load_lds_dwordx4 v[240:241], off

; #define PG8_STAGE(bufoff, gbase, voff) do { _Pragma("unroll") for (int _i = 0; _i < 2; ++_i) \
;         __builtin_amdgcn_global_load_lds((const unsigned*)((const char*)(gbase) + (voff)[_i]), (PG8_LAS unsigned*)(lds + (bufoff) + ldsw + _i * 8192), 16, 0, 0); } while (0)
; #define PG8_LDA(dst, b, h) do { _Pragma("unroll") for (int m = 0; m < 4; ++m) _Pragma("unroll") for (int k = 0; k < 2; ++k) dst[m][k] = *(const PG8_LAS bf16x8*)(lds + PG8_SA(b, h) + aoff + m * 2048 + k * 1024); } while (0)
; #define PG8_MMA(ai, bj, At, Bt) do { __builtin_amdgcn_s_setprio(1); _Pragma("unroll") for (int m = 0; m < 4; ++m) _Pragma("unroll") for (int n = 0; n < 2; ++n) _Pragma("unroll") for (int k = 0; k < 2; ++k) \
;         acc[ai][bj][m][n] = __builtin_amdgcn_mfma_f32_16x16x32_bf16(Bt[n][k], At[m][k], acc[ai][bj][m][n], 0, 0, 0); __builtin_amdgcn_s_setprio(0); } while (0)
; #define PG8_WAIT_V(n) asm volatile("s_waitcnt vmcnt(" #n ")" ::: "memory")
; #define PG8_WAIT_L(n) asm volatile("s_waitcnt lgkmcnt(" #n ")" ::: "memory")
; #define PG8_BAR __builtin_amdgcn_s_barrier()
; #define PG8_SCHED __builtin_amdgcn_sched_barrier(0)
; template <class Epi, class Sched, bool ALIGN_EPI = false, bool SP2 = false>
; __device__ __forceinline__ void gemm_phase(PG8_LAS unsigned char* lds, const Gemm g, const Sched& S, const Epi& E, const int tid) {
;     ...
;             PG8_WAIT_V(8); PG8_WAIT_L(0); PG8_BAR; PG8_MMA(0, 0, At, B0); PG8_MMA(0, 1, At, B1); PG8_BAR; PG8_SCHED;
;             PG8_LDA(At, 1, 1); PG8_STAGE(PG8_SB(1, 0), b3, voffB); PG8_STAGE(PG8_SB(1, 1), b3 + hstepB, voffB); PG8_STAGE(PG8_SA(1, 0), a3, voffA);
.Lbw4_0:
	s_waitcnt lgkmcnt(0)
	s_barrier
	s_waitcnt lgkmcnt(0)
	v_mfma_f32_16x16x32_bf16 v[120:123], v[146:149], v[194:197], v[120:123]
	v_mfma_f32_16x16x32_bf16 v[128:131], v[170:173], v[194:197], v[128:131]
	v_mfma_f32_16x16x32_bf16 v[100:103], v[146:149], v[212:215], v[100:103]
	v_mfma_f32_16x16x32_bf16 v[108:111], v[170:173], v[212:215], v[108:111]
	v_mfma_f32_16x16x32_bf16 v[84:87], v[146:149], v[220:223], v[84:87]
	v_mfma_f32_16x16x32_bf16 v[92:95], v[170:173], v[220:223], v[92:95]
	v_mfma_f32_16x16x32_bf16 v[68:71], v[146:149], v[228:231], v[68:71]
	v_mfma_f32_16x16x32_bf16 v[76:79], v[170:173], v[228:231], v[76:79]
	v_mfma_f32_16x16x32_bf16 v[120:123], v[162:165], v[198:201], v[120:123]
	v_mfma_f32_16x16x32_bf16 v[128:131], v[174:177], v[198:201], v[128:131]
	v_mfma_f32_16x16x32_bf16 v[100:103], v[162:165], v[216:219], v[100:103]
	v_mfma_f32_16x16x32_bf16 v[108:111], v[174:177], v[216:219], v[108:111]
	v_mfma_f32_16x16x32_bf16 v[84:87], v[162:165], v[224:227], v[84:87]
	v_mfma_f32_16x16x32_bf16 v[92:95], v[174:177], v[224:227], v[92:95]
	v_mfma_f32_16x16x32_bf16 v[68:71], v[162:165], v[232:235], v[68:71]
	v_mfma_f32_16x16x32_bf16 v[76:79], v[174:177], v[232:235], v[76:79]
	v_mfma_f32_16x16x32_bf16 v[116:119], v[178:181], v[194:197], v[116:119]
	v_mfma_f32_16x16x32_bf16 v[124:127], v[186:189], v[194:197], v[124:127]
	v_mfma_f32_16x16x32_bf16 v[104:107], v[178:181], v[212:215], v[104:107]
	v_mfma_f32_16x16x32_bf16 v[112:115], v[186:189], v[212:215], v[112:115]
	v_mfma_f32_16x16x32_bf16 v[88:91], v[178:181], v[220:223], v[88:91]
	v_mfma_f32_16x16x32_bf16 v[96:99], v[186:189], v[220:223], v[96:99]
	v_mfma_f32_16x16x32_bf16 v[72:75], v[178:181], v[228:231], v[72:75]
	v_mfma_f32_16x16x32_bf16 v[80:83], v[186:189], v[228:231], v[80:83]
	v_mfma_f32_16x16x32_bf16 v[116:119], v[182:185], v[198:201], v[116:119]
	v_mfma_f32_16x16x32_bf16 v[124:127], v[190:193], v[198:201], v[124:127]
	v_mfma_f32_16x16x32_bf16 v[104:107], v[182:185], v[216:219], v[104:107]
	v_mfma_f32_16x16x32_bf16 v[112:115], v[190:193], v[216:219], v[112:115]
	v_mfma_f32_16x16x32_bf16 v[88:91], v[182:185], v[224:227], v[88:91]
	v_mfma_f32_16x16x32_bf16 v[96:99], v[190:193], v[224:227], v[96:99]
	v_mfma_f32_16x16x32_bf16 v[72:75], v[182:185], v[232:235], v[72:75]
	v_mfma_f32_16x16x32_bf16 v[80:83], v[190:193], v[232:235], v[80:83]
	s_barrier
	s_add_i32 s42, s83, s55
	v_lshl_add_u64 v[150:151], v[150:151], 0, s[52:53]
	s_mov_b32 m0, s42
	ds_read_b128 v[194:197], v160 offset:49152
	ds_read_b128 v[198:201], v160 offset:50176
	ds_read_b128 v[212:215], v160 offset:51200
	ds_read_b128 v[216:219], v160 offset:52224
	ds_read_b128 v[220:223], v160 offset:53248
	ds_read_b128 v[224:227], v160 offset:54272
	ds_read_b128 v[228:231], v160 offset:55296
	ds_read_b128 v[232:235], v160 offset:56320
	s_cmp_lg_u32 s32, 0
	s_cbranch_scc1 .Lbt4_8
	global_load_lds_dwordx4 v[150:151], off

; #define PG8_STAGE(bufoff, gbase, voff) do { _Pragma("unroll") for (int _i = 0; _i < 2; ++_i) \
;         __builtin_amdgcn_global_load_lds((const unsigned*)((const char*)(gbase) + (voff)[_i]), (PG8_LAS unsigned*)(lds + (bufoff) + ldsw + _i * 8192), 16, 0, 0); } while (0)
; #define PG8_LDA(dst, b, h) do { _Pragma("unroll") for (int m = 0; m < 4; ++m) _Pragma("unroll") for (int k = 0; k < 2; ++k) dst[m][k] = *(const PG8_LAS bf16x8*)(lds + PG8_SA(b, h) + aoff + m * 2048 + k * 1024); } while (0)
; #define PG8_MMA(ai, bj, At, Bt) do { __builtin_amdgcn_s_setprio(1); _Pragma("unroll") for (int m = 0; m < 4; ++m) _Pragma("unroll") for (int n = 0; n < 2; ++n) _Pragma("unroll") for (int k = 0; k < 2; ++k) \
;         acc[ai][bj][m][n] = __builtin_amdgcn_mfma_f32_16x16x32_bf16(Bt[n][k], At[m][k], acc[ai][bj][m][n], 0, 0, 0); __builtin_amdgcn_s_setprio(0); } while (0)
; #define PG8_WAIT_V(n) asm volatile("s_waitcnt vmcnt(" #n ")" ::: "memory")
; #define PG8_WAIT_L(n) asm volatile("s_waitcnt lgkmcnt(" #n ")" ::: "memory")
; #define PG8_BAR __builtin_amdgcn_s_barrier()
; #define PG8_SCHED __builtin_amdgcn_sched_barrier(0)
; template <class Epi, class Sched, bool ALIGN_EPI = false, bool SP2 = false>
; __device__ __forceinline__ void gemm_phase(PG8_LAS unsigned char* lds, const Gemm g, const Sched& S, const Epi& E, const int tid) {
;     ...
;         for (int t = 0; t < nt; t += 2) {
;             const bool last = (t == nt - 2);
;             const char* a1 = cA + (size_t)(t + 1) * kstep;
;             const char* a2 = last ? nA : cA + (size_t)(t + 2) * kstep; const char* b2 = last ? nB : cB + (size_t)(t + 2) * kstep;
;             const char* a3 = a2 + kstep; const char* b3 = b2 + kstep;
;     ...
;             PG8_LDA(At, 1, 1); PG8_STAGE(PG8_SB(1, 0), b3, voffB); PG8_STAGE(PG8_SB(1, 1), b3 + hstepB, voffB); PG8_STAGE(PG8_SA(1, 0), a3, voffA);
;             PG8_WAIT_V(8); PG8_WAIT_L(0); PG8_BAR; PG8_MMA(1, 0, At, B0); PG8_MMA(1, 1, At, B1); PG8_BAR; PG8_SCHED;
.Lbt4_13:
	s_waitcnt vmcnt(8)
	s_waitcnt lgkmcnt(0)
	s_barrier
	s_waitcnt lgkmcnt(0)
	v_mfma_f32_16x16x32_bf16 v[52:55], v[146:149], v[194:197], v[52:55]
	v_mfma_f32_16x16x32_bf16 v[60:63], v[170:173], v[194:197], v[60:63]
	v_mfma_f32_16x16x32_bf16 v[36:39], v[146:149], v[212:215], v[36:39]
	v_mfma_f32_16x16x32_bf16 v[44:47], v[170:173], v[212:215], v[44:47]
	v_mfma_f32_16x16x32_bf16 v[20:23], v[146:149], v[220:223], v[20:23]
	v_mfma_f32_16x16x32_bf16 v[28:31], v[170:173], v[220:223], v[28:31]
	v_mfma_f32_16x16x32_bf16 v[4:7], v[146:149], v[228:231], v[4:7]
	v_mfma_f32_16x16x32_bf16 v[12:15], v[170:173], v[228:231], v[12:15]
	v_mfma_f32_16x16x32_bf16 v[52:55], v[162:165], v[198:201], v[52:55]
	v_mfma_f32_16x16x32_bf16 v[60:63], v[174:177], v[198:201], v[60:63]
	v_mfma_f32_16x16x32_bf16 v[36:39], v[162:165], v[216:219], v[36:39]
	v_mfma_f32_16x16x32_bf16 v[44:47], v[174:177], v[216:219], v[44:47]
	v_mfma_f32_16x16x32_bf16 v[20:23], v[162:165], v[224:227], v[20:23]
	v_mfma_f32_16x16x32_bf16 v[28:31], v[174:177], v[224:227], v[28:31]
	v_mfma_f32_16x16x32_bf16 v[4:7], v[162:165], v[232:235], v[4:7]
	v_mfma_f32_16x16x32_bf16 v[12:15], v[174:177], v[232:235], v[12:15]
	v_mfma_f32_16x16x32_bf16 v[56:59], v[178:181], v[194:197], v[56:59]
	v_mfma_f32_16x16x32_bf16 v[64:67], v[186:189], v[194:197], v[64:67]
	v_mfma_f32_16x16x32_bf16 v[40:43], v[178:181], v[212:215], v[40:43]
	v_mfma_f32_16x16x32_bf16 v[48:51], v[186:189], v[212:215], v[48:51]
	v_mfma_f32_16x16x32_bf16 v[24:27], v[178:181], v[220:223], v[24:27]
	v_mfma_f32_16x16x32_bf16 v[32:35], v[186:189], v[220:223], v[32:35]
	v_mfma_f32_16x16x32_bf16 v[8:11], v[178:181], v[228:231], v[8:11]
	v_mfma_f32_16x16x32_bf16 v[16:19], v[186:189], v[228:231], v[16:19]
	v_mfma_f32_16x16x32_bf16 v[56:59], v[182:185], v[198:201], v[56:59]
	v_mfma_f32_16x16x32_bf16 v[64:67], v[190:193], v[198:201], v[64:67]
	v_mfma_f32_16x16x32_bf16 v[40:43], v[182:185], v[216:219], v[40:43]
	v_mfma_f32_16x16x32_bf16 v[48:51], v[190:193], v[216:219], v[48:51]
	v_mfma_f32_16x16x32_bf16 v[24:27], v[182:185], v[224:227], v[24:27]
	v_mfma_f32_16x16x32_bf16 v[32:35], v[190:193], v[224:227], v[32:35]
	v_mfma_f32_16x16x32_bf16 v[8:11], v[182:185], v[232:235], v[8:11]
	v_mfma_f32_16x16x32_bf16 v[16:19], v[190:193], v[232:235], v[16:19]
	s_barrier
	s_add_i32 s82, s82, 2
	s_add_u32 s40, s40, 0x100
	s_addc_u32 s41, s41, 0
	s_add_u32 s80, s80, 0x100
	s_addc_u32 s81, s81, 0
	s_cmp_gt_u32 s82, 13
	s_cbranch_scc0 .LBB0_1266
	s_and_b64 vcc, exec, s[16:17]
	s_cbranch_vccz .LBB0_1269
	s_barrier

; #define PG8_STAGE(bufoff, gbase, voff) do { _Pragma("unroll") for (int _i = 0; _i < 2; ++_i) \
;         __builtin_amdgcn_global_load_lds((const unsigned*)((const char*)(gbase) + (voff)[_i]), (PG8_LAS unsigned*)(lds + (bufoff) + ldsw + _i * 8192), 16, 0, 0); } while (0)
; #define PG8_WAIT_V(n) asm volatile("s_waitcnt vmcnt(" #n ")" ::: "memory")
; #define PG8_BAR __builtin_amdgcn_s_barrier()
;     DI void row8x2(int row, int col, f32x4 a0, f32x4 a1, f32x4 b0, f32x4 b1, float r, bool hi) const {
;     ...
;         const int cc = col + (hi ? 32 : 0);
;         *(u32x4*)(O + (size_t)(row - (hi ? 8 : 0)) * ldc + cc) = pa;
;         *(u32x4*)(O + (size_t)(row + (hi ? 0 : 8)) * ldc + cc) = pb;
; template <class Epi, class Sched, bool ALIGN_EPI = false, bool SP2 = false>
; __device__ __forceinline__ void gemm_phase(PG8_LAS unsigned char* lds, const Gemm g, const Sched& S, const Epi& E, const int tid) {
;     ...
;         PG8_STAGE(PG8_SB(1, 0), cB + kstep, voffB); PG8_STAGE(PG8_SA(1, 0), cA + kstep, voffA); PG8_STAGE(PG8_SB(1, 1), cB + hstepB + kstep, voffB);
;         PG8_WAIT_V(6); PG8_BAR;
;     } else {
;         PG8_STAGE(PG8_SB(0, 0), cB, voffB); PG8_STAGE(PG8_SA(0, 0), cA, voffA); PG8_STAGE(PG8_SB(0, 1), cB + hstepB, voffB); PG8_STAGE(PG8_SA(0, 1), cA + hstep, voffA);
;         if (wr == 1) PG8_BAR;
;         PG8_WAIT_V(4); PG8_BAR;
;         PG8_STAGE(PG8_SB(1, 0), cB + kstep, voffB); PG8_STAGE(PG8_SA(1, 0), cA + kstep, voffA); PG8_STAGE(PG8_SB(1, 1), cB + hstepB + kstep, voffB);
;         PG8_WAIT_V(6); PG8_BAR;
;     }
;     if constexpr (Epi::HAS_INIT) E.init_finish(acc, iw_);
.LBB0_1374:
	v_lshlrev_b32_e32 v18, 1, v3
	v_lshlrev_b32_e32 v19, 2, v153
	s_and_b32 s17, s15, 3
	v_lshl_or_b32 v18, v153, 6, v18
	s_lshl_b32 s15, s16, 13
	v_and_b32_e32 v20, 32, v19
	s_add_i32 m0, s29, 0x18000
	v_lshl_add_u64 v[10:11], v[10:11], 0, s[52:53]
	v_bitop3_b32 v21, v18, s15, v20 bitop3:0xde
	s_lshl_b32 s15, s17, 12
	s_waitcnt vmcnt(2)
	s_barrier
	global_load_lds_dwordx4 v[10:11], off
	v_lshl_add_u64 v[8:9], v[8:9], 0, s[52:53]
	s_add_i32 m0, s29, 0x1a000
	s_add_i32 s63, s29, 0x8000
	s_add_i32 s64, s29, 0xa000
	global_load_lds_dwordx4 v[8:9], off
	v_lshl_add_u64 v[4:5], v[4:5], 0, s[52:53]
	s_mov_b32 m0, s63
	s_add_u32 s18, s36, 0x10080
	global_load_lds_dwordx4 v[4:5], off
	v_lshl_add_u64 v[4:5], v[6:7], 0, s[52:53]
	s_mov_b32 m0, s64
	s_addc_u32 s19, s37, 0
	global_load_lds_dwordx4 v[4:5], off
	s_add_i32 m0, s29, 0x1c000
	v_lshl_add_u64 v[4:5], s[18:19], 0, v[138:139]
	global_load_lds_dwordx4 v[4:5], off
	v_lshl_add_u64 v[4:5], s[18:19], 0, v[134:135]
	s_add_i32 m0, s29, 0x1e000
	s_cmpk_lt_u32 s14, 0x100
	global_load_lds_dwordx4 v[4:5], off
	v_cmp_lt_u32_e32 vcc, 7, v153
	v_bitop3_b32 v158, s15, v18, v20 bitop3:0xf6
	s_cselect_b64 s[14:15], -1, 0
	s_lshl_b32 s17, s17, 6
	v_cndmask_b32_e64 v4, 0, 32, vcc
	v_or3_b32 v162, s17, v4, v3
	v_lshlrev_b32_e32 v4, 14, v12
	v_and_b32_e32 v4, 0xffff8000, v4
	v_lshl_add_u32 v4, v13, 11, v4
	v_and_b32_e32 v5, 1, v12
	v_lshl_or_b32 v4, v5, 6, v4
	v_lshl_add_u32 v142, v14, 1, v4
	v_lshlrev_b32_e32 v4, 14, v15
	v_lshl_or_b32 v157, s16, 6, v153
	s_lshl_b32 s16, s16, 8
	v_and_b32_e32 v4, 0xffff8000, v4
	s_waitcnt vmcnt(6)
	s_add_i32 s16, s16, 0
	v_lshl_add_u32 v4, v16, 11, v4
	v_and_b32_e32 v5, 1, v15
	s_add_i32 s16, s16, 0x20000
	v_lshl_or_b32 v4, v5, 6, v4
	s_mov_b32 s65, 0
	v_cndmask_b32_e64 v159, 0, -8, vcc
	v_cndmask_b32_e64 v160, 8, 0, vcc
	v_add_u32_e32 v161, s16, v19
	v_mov_b32_e32 v143, v2
	v_lshl_add_u32 v144, v17, 1, v4
	v_mov_b32_e32 v145, v2
	v_add_u32_e32 v163, 0, v21
	s_barrier
	s_sub_u32 s36, s36, s85
	s_subb_u32 s37, s37, 0
	s_sub_u32 s30, s30, s85
	s_subb_u32 s31, s31, 0
	v_readfirstlane_b32 s98, v0
	s_nop 3
	s_and_b32 s98, s98, 0x3ff
	s_lshr_b32 s98, s98, 6
	s_cmp_ge_u32 s98, 4
	s_cbranch_scc0 .Lprio_done5
	s_setprio 1
.Lprio_done5:
	s_branch .LBB0_1377
.LBB0_1375:
	s_mov_b64 s[22:23], 0

;     DI bool next(int i, Unit& u) const { const int L = i * 32 + rank; if (L >= ppg * nN) return false; u.pm = ppg * grp + (L % ppg); const int p0 = L / ppg, p1 = p0 + rot; u.pn = rev ? nN - 1 - p0 : (p1 >= nN ? p1 - nN : p1); return true; }
; #define PG8_STAGE(bufoff, gbase, voff) do { _Pragma("unroll") for (int _i = 0; _i < 2; ++_i) \
;         __builtin_amdgcn_global_load_lds((const unsigned*)((const char*)(gbase) + (voff)[_i]), (PG8_LAS unsigned*)(lds + (bufoff) + ldsw + _i * 8192), 16, 0, 0); } while (0)
; #define PG8_LDA(dst, b, h) do { _Pragma("unroll") for (int m = 0; m < 4; ++m) _Pragma("unroll") for (int k = 0; k < 2; ++k) dst[m][k] = *(const PG8_LAS bf16x8*)(lds + PG8_SA(b, h) + aoff + m * 2048 + k * 1024); } while (0)
; #define PG8_LDB(dst, b, h) do { _Pragma("unroll") for (int n = 0; n < 2; ++n) _Pragma("unroll") for (int k = 0; k < 2; ++k) dst[n][k] = *(const PG8_LAS bf16x8*)(lds + PG8_SB(b, h) + boff + n * 2048 + k * 1024); } while (0)
; #define PG8_WAIT_V(n) asm volatile("s_waitcnt vmcnt(" #n ")" ::: "memory")
; #define PG8_WAIT_L(n) asm volatile("s_waitcnt lgkmcnt(" #n ")" ::: "memory")
; template <class Epi, class Sched, bool ALIGN_EPI = false, bool SP2 = false>
; __device__ __forceinline__ void gemm_phase(PG8_LAS unsigned char* lds, const Gemm g, const Sched& S, const Epi& E, const int tid) {
;     ...
;         const bool has_next = S.next(ui + 1, nxt);
;         const char* nA = has_next ? (const char*)g.A + (size_t)nxt.pm * tstep : cA; const char* nB = has_next ? (const char*)g.Bt + (size_t)nxt.pn * tstep : cB;
;         for (int t = 0; t < nt; t += 2) {
;             const bool last = (t == nt - 2);
;             const char* a1 = cA + (size_t)(t + 1) * kstep;
;             const char* a2 = last ? nA : cA + (size_t)(t + 2) * kstep; const char* b2 = last ? nB : cB + (size_t)(t + 2) * kstep;
;             const char* a3 = a2 + kstep; const char* b3 = b2 + kstep;
;             if (last && has_next) S.a_ready(nxt);
;             if constexpr (SP2) {
;             PG8_LDB(B0, 0, 0); PG8_LDB(B1, 0, 1); PG8_SCHED; PG8_LDA(At, 0, 0); PG8_STAGE(PG8_SA(1, 1), a1 + hstep, voffA);
;             PG8_WAIT_V(8); PG8_WAIT_L(0); PG8_BAR; PG8_MMA(0, 0, At, B0); PG8_MMA(0, 1, At, B1); PG8_BAR; PG8_SCHED;
;             PG8_LDA(At, 0, 1); PG8_STAGE(PG8_SB(0, 0), b2, voffB); PG8_STAGE(PG8_SB(0, 1), b2 + hstepB, voffB); PG8_STAGE(PG8_SA(0, 0), a2, voffA);
.LBB0_1380:
	s_lshl_b32 s98, s79, 7
	s_add_i32 s98, s98, s84
	s_add_i32 s99, s98, 0x100
	s_and_b32 s98, s98, 0x700
	s_and_b32 s99, s99, 0x700
	s_add_u32 s100, s30, s98
	s_addc_u32 s101, s31, 0
	s_add_u32 s36, s30, 0xfffbff80
	s_addc_u32 s37, s31, -1
	s_add_u32 s36, s36, s99
	s_addc_u32 s37, s37, 0
	s_add_u32 s92, s76, s99
	s_addc_u32 s93, s78, 0
	s_add_i32 s80, 0, 0x10000
	s_cmp_eq_u32 s79, 12
	s_cselect_b32 s39, s17, s37
	s_cselect_b32 s38, s66, s36
	v_add_u32_e32 v150, s80, v158
	s_cselect_b32 s37, s19, s93
	s_cselect_b32 s36, s67, s92
	s_cmp_eq_u32 s79, 12
	s_cselect_b32 s32, 1, 0
	s_andn2_b32 s32, s32, s22
	s_add_i32 s82, 0, 0x14000
	ds_read_b128 v[146:149], v150
	ds_read_b128 v[164:167], v150 offset:1024
	ds_read_b128 v[170:173], v150 offset:2048
	ds_read_b128 v[174:177], v150 offset:3072
	v_add_u32_e32 v150, s82, v158
	ds_read_b128 v[178:181], v150
	ds_read_b128 v[182:185], v150 offset:1024
	ds_read_b128 v[186:189], v150 offset:2048
	ds_read_b128 v[190:193], v150 offset:3072
	v_lshl_add_u64 v[150:151], s[100:101], 0, v[142:143]
	s_add_i32 m0, s29, 0xc000
	ds_read_b128 v[194:197], v163
	ds_read_b128 v[198:201], v163 offset:1024
	ds_read_b128 v[212:215], v163 offset:2048
	ds_read_b128 v[216:219], v163 offset:3072
	ds_read_b128 v[220:223], v163 offset:4096
	ds_read_b128 v[224:227], v163 offset:5120
	ds_read_b128 v[228:231], v163 offset:6144
	ds_read_b128 v[232:235], v163 offset:7168
	global_load_lds_dwordx4 v[150:151], off
	v_lshl_add_u64 v[150:151], s[100:101], 0, v[144:145]
	s_add_i32 m0, s29, 0xe000
	s_nop 0
	global_load_lds_dwordx4 v[150:151], off
	s_waitcnt vmcnt(8)
	s_waitcnt lgkmcnt(0)
	s_barrier
	s_waitcnt lgkmcnt(0)
	v_mfma_f32_16x16x32_bf16 v[128:131], v[146:149], v[194:197], v[128:131]
	v_mfma_f32_16x16x32_bf16 v[124:127], v[170:173], v[194:197], v[124:127]
	v_mfma_f32_16x16x32_bf16 v[112:115], v[146:149], v[212:215], v[112:115]
	v_mfma_f32_16x16x32_bf16 v[108:111], v[170:173], v[212:215], v[108:111]
	v_mfma_f32_16x16x32_bf16 v[96:99], v[146:149], v[220:223], v[96:99]
	v_mfma_f32_16x16x32_bf16 v[92:95], v[170:173], v[220:223], v[92:95]
	v_mfma_f32_16x16x32_bf16 v[80:83], v[146:149], v[228:231], v[80:83]
	v_mfma_f32_16x16x32_bf16 v[76:79], v[170:173], v[228:231], v[76:79]
	v_mfma_f32_16x16x32_bf16 v[128:131], v[164:167], v[198:201], v[128:131]
	v_mfma_f32_16x16x32_bf16 v[124:127], v[174:177], v[198:201], v[124:127]
	v_mfma_f32_16x16x32_bf16 v[112:115], v[164:167], v[216:219], v[112:115]
	v_mfma_f32_16x16x32_bf16 v[108:111], v[174:177], v[216:219], v[108:111]
	v_mfma_f32_16x16x32_bf16 v[96:99], v[164:167], v[224:227], v[96:99]
	v_mfma_f32_16x16x32_bf16 v[92:95], v[174:177], v[224:227], v[92:95]
	v_mfma_f32_16x16x32_bf16 v[80:83], v[164:167], v[232:235], v[80:83]
	v_mfma_f32_16x16x32_bf16 v[76:79], v[174:177], v[232:235], v[76:79]
	v_mfma_f32_16x16x32_bf16 v[120:123], v[178:181], v[194:197], v[120:123]
	v_mfma_f32_16x16x32_bf16 v[116:119], v[186:189], v[194:197], v[116:119]
	v_mfma_f32_16x16x32_bf16 v[104:107], v[178:181], v[212:215], v[104:107]
	v_mfma_f32_16x16x32_bf16 v[100:103], v[186:189], v[212:215], v[100:103]
	v_mfma_f32_16x16x32_bf16 v[88:91], v[178:181], v[220:223], v[88:91]
	v_mfma_f32_16x16x32_bf16 v[84:87], v[186:189], v[220:223], v[84:87]
	v_mfma_f32_16x16x32_bf16 v[72:75], v[178:181], v[228:231], v[72:75]
	v_mfma_f32_16x16x32_bf16 v[68:71], v[186:189], v[228:231], v[68:71]
	v_mfma_f32_16x16x32_bf16 v[120:123], v[182:185], v[198:201], v[120:123]
	v_mfma_f32_16x16x32_bf16 v[116:119], v[190:193], v[198:201], v[116:119]
	v_mfma_f32_16x16x32_bf16 v[104:107], v[182:185], v[216:219], v[104:107]
	v_mfma_f32_16x16x32_bf16 v[100:103], v[190:193], v[216:219], v[100:103]
	v_mfma_f32_16x16x32_bf16 v[88:91], v[182:185], v[224:227], v[88:91]
	v_mfma_f32_16x16x32_bf16 v[84:87], v[190:193], v[224:227], v[84:87]
	v_mfma_f32_16x16x32_bf16 v[72:75], v[182:185], v[232:235], v[72:75]
	v_mfma_f32_16x16x32_bf16 v[68:71], v[190:193], v[232:235], v[68:71]
	s_barrier
	s_add_i32 s80, s80, s42
	v_lshl_add_u64 v[150:151], s[36:37], 0, v[138:139]
	s_mov_b32 m0, s80
	ds_read_b128 v[194:197], v163 offset:16384
	ds_read_b128 v[198:201], v163 offset:17408
	ds_read_b128 v[212:215], v163 offset:18432
	ds_read_b128 v[216:219], v163 offset:19456
	ds_read_b128 v[220:223], v163 offset:20480
	ds_read_b128 v[224:227], v163 offset:21504
	ds_read_b128 v[228:231], v163 offset:22528
	ds_read_b128 v[232:235], v163 offset:23552
	s_cmp_lg_u32 s32, 0
	s_cbranch_scc1 .Lbt5_0
	global_load_lds_dwordx4 v[150:151], off

; #define PG8_STAGE(bufoff, gbase, voff) do { _Pragma("unroll") for (int _i = 0; _i < 2; ++_i) \
;         __builtin_amdgcn_global_load_lds((const unsigned*)((const char*)(gbase) + (voff)[_i]), (PG8_LAS unsigned*)(lds + (bufoff) + ldsw + _i * 8192), 16, 0, 0); } while (0)
; #define PG8_LDA(dst, b, h) do { _Pragma("unroll") for (int m = 0; m < 4; ++m) _Pragma("unroll") for (int k = 0; k < 2; ++k) dst[m][k] = *(const PG8_LAS bf16x8*)(lds + PG8_SA(b, h) + aoff + m * 2048 + k * 1024); } while (0)
; #define PG8_LDB(dst, b, h) do { _Pragma("unroll") for (int n = 0; n < 2; ++n) _Pragma("unroll") for (int k = 0; k < 2; ++k) dst[n][k] = *(const PG8_LAS bf16x8*)(lds + PG8_SB(b, h) + boff + n * 2048 + k * 1024); } while (0)
; #define PG8_MMA(ai, bj, At, Bt) do { __builtin_amdgcn_s_setprio(1); _Pragma("unroll") for (int m = 0; m < 4; ++m) _Pragma("unroll") for (int n = 0; n < 2; ++n) _Pragma("unroll") for (int k = 0; k < 2; ++k) \
;         acc[ai][bj][m][n] = __builtin_amdgcn_mfma_f32_16x16x32_bf16(Bt[n][k], At[m][k], acc[ai][bj][m][n], 0, 0, 0); __builtin_amdgcn_s_setprio(0); } while (0)
; #define PG8_WAIT_V(n) asm volatile("s_waitcnt vmcnt(" #n ")" ::: "memory")
; #define PG8_WAIT_L(n) asm volatile("s_waitcnt lgkmcnt(" #n ")" ::: "memory")
; #define PG8_BAR __builtin_amdgcn_s_barrier()
; #define PG8_SCHED __builtin_amdgcn_sched_barrier(0)
; template <class Epi, class Sched, bool ALIGN_EPI = false, bool SP2 = false>
; __device__ __forceinline__ void gemm_phase(PG8_LAS unsigned char* lds, const Gemm g, const Sched& S, const Epi& E, const int tid) {
;     ...
;             PG8_WAIT_V(8); PG8_WAIT_L(0); PG8_BAR; PG8_MMA(1, 0, At, B0); PG8_MMA(1, 1, At, B1); PG8_BAR; PG8_SCHED;
;             PG8_LDB(B0, 1, 0); PG8_LDB(B1, 1, 1); PG8_SCHED; PG8_LDA(At, 1, 0); PG8_STAGE(PG8_SA(0, 1), a2 + hstep, voffA);
;             PG8_WAIT_V(8); PG8_WAIT_L(0); PG8_BAR; PG8_MMA(0, 0, At, B0); PG8_MMA(0, 1, At, B1); PG8_BAR; PG8_SCHED;
.Lbw5_2:
	s_waitcnt lgkmcnt(0)
	s_barrier
	s_waitcnt lgkmcnt(0)
	v_mfma_f32_16x16x32_bf16 v[64:67], v[146:149], v[194:197], v[64:67]
	v_mfma_f32_16x16x32_bf16 v[60:63], v[170:173], v[194:197], v[60:63]
	v_mfma_f32_16x16x32_bf16 v[48:51], v[146:149], v[212:215], v[48:51]
	v_mfma_f32_16x16x32_bf16 v[44:47], v[170:173], v[212:215], v[44:47]
	v_mfma_f32_16x16x32_bf16 v[32:35], v[146:149], v[220:223], v[32:35]
	v_mfma_f32_16x16x32_bf16 v[28:31], v[170:173], v[220:223], v[28:31]
	v_mfma_f32_16x16x32_bf16 v[16:19], v[146:149], v[228:231], v[16:19]
	v_mfma_f32_16x16x32_bf16 v[12:15], v[170:173], v[228:231], v[12:15]
	v_mfma_f32_16x16x32_bf16 v[64:67], v[164:167], v[198:201], v[64:67]
	v_mfma_f32_16x16x32_bf16 v[60:63], v[174:177], v[198:201], v[60:63]
	v_mfma_f32_16x16x32_bf16 v[48:51], v[164:167], v[216:219], v[48:51]
	v_mfma_f32_16x16x32_bf16 v[44:47], v[174:177], v[216:219], v[44:47]
	v_mfma_f32_16x16x32_bf16 v[32:35], v[164:167], v[224:227], v[32:35]
	v_mfma_f32_16x16x32_bf16 v[28:31], v[174:177], v[224:227], v[28:31]
	v_mfma_f32_16x16x32_bf16 v[16:19], v[164:167], v[232:235], v[16:19]
	v_mfma_f32_16x16x32_bf16 v[12:15], v[174:177], v[232:235], v[12:15]
	v_mfma_f32_16x16x32_bf16 v[56:59], v[178:181], v[194:197], v[56:59]
	v_mfma_f32_16x16x32_bf16 v[52:55], v[186:189], v[194:197], v[52:55]
	v_mfma_f32_16x16x32_bf16 v[40:43], v[178:181], v[212:215], v[40:43]
	v_mfma_f32_16x16x32_bf16 v[36:39], v[186:189], v[212:215], v[36:39]
	v_mfma_f32_16x16x32_bf16 v[24:27], v[178:181], v[220:223], v[24:27]
	v_mfma_f32_16x16x32_bf16 v[20:23], v[186:189], v[220:223], v[20:23]
	v_mfma_f32_16x16x32_bf16 v[8:11], v[178:181], v[228:231], v[8:11]
	v_mfma_f32_16x16x32_bf16 v[4:7], v[186:189], v[228:231], v[4:7]
	v_mfma_f32_16x16x32_bf16 v[56:59], v[182:185], v[198:201], v[56:59]
	v_mfma_f32_16x16x32_bf16 v[52:55], v[190:193], v[198:201], v[52:55]
	v_mfma_f32_16x16x32_bf16 v[40:43], v[182:185], v[216:219], v[40:43]
	v_mfma_f32_16x16x32_bf16 v[36:39], v[190:193], v[216:219], v[36:39]
	v_mfma_f32_16x16x32_bf16 v[24:27], v[182:185], v[224:227], v[24:27]
	v_mfma_f32_16x16x32_bf16 v[20:23], v[190:193], v[224:227], v[20:23]
	v_mfma_f32_16x16x32_bf16 v[8:11], v[182:185], v[232:235], v[8:11]
	v_mfma_f32_16x16x32_bf16 v[4:7], v[190:193], v[232:235], v[4:7]
	s_barrier
	s_add_i32 s80, 0, 0x18000
	s_add_i32 s81, 0, 0x1c000
	v_add_u32_e32 v174, s80, v158
	v_add_u32_e32 v190, s81, v158
	ds_read_b128 v[146:149], v174
	ds_read_b128 v[164:167], v174 offset:1024
	ds_read_b128 v[170:173], v174 offset:2048
	ds_read_b128 v[174:177], v174 offset:3072
	ds_read_b128 v[178:181], v190
	ds_read_b128 v[182:185], v190 offset:1024
	ds_read_b128 v[186:189], v190 offset:2048
	ds_read_b128 v[190:193], v190 offset:3072
	s_add_u32 s38, s38, 0x40000
	s_addc_u32 s39, s39, 0
	s_mov_b32 m0, s55
	v_lshl_add_u64 v[242:243], s[38:39], 0, v[140:141]
	ds_read_b128 v[194:197], v163 offset:32768
	ds_read_b128 v[198:201], v163 offset:33792
	ds_read_b128 v[212:215], v163 offset:34816
	ds_read_b128 v[216:219], v163 offset:35840
	ds_read_b128 v[220:223], v163 offset:36864
	ds_read_b128 v[224:227], v163 offset:37888
	ds_read_b128 v[228:231], v163 offset:38912
	ds_read_b128 v[232:235], v163 offset:39936
	s_cmp_lg_u32 s32, 0
	s_cbranch_scc1 .Lbt5_6
	global_load_lds_dwordx4 v[242:243], off

; #define PG8_STAGE(bufoff, gbase, voff) do { _Pragma("unroll") for (int _i = 0; _i < 2; ++_i) \
;         __builtin_amdgcn_global_load_lds((const unsigned*)((const char*)(gbase) + (voff)[_i]), (PG8_LAS unsigned*)(lds + (bufoff) + ldsw + _i * 8192), 16, 0, 0); } while (0)
; #define PG8_LDA(dst, b, h) do { _Pragma("unroll") for (int m = 0; m < 4; ++m) _Pragma("unroll") for (int k = 0; k < 2; ++k) dst[m][k] = *(const PG8_LAS bf16x8*)(lds + PG8_SA(b, h) + aoff + m * 2048 + k * 1024); } while (0)
; #define PG8_MMA(ai, bj, At, Bt) do { __builtin_amdgcn_s_setprio(1); _Pragma("unroll") for (int m = 0; m < 4; ++m) _Pragma("unroll") for (int n = 0; n < 2; ++n) _Pragma("unroll") for (int k = 0; k < 2; ++k) \
;         acc[ai][bj][m][n] = __builtin_amdgcn_mfma_f32_16x16x32_bf16(Bt[n][k], At[m][k], acc[ai][bj][m][n], 0, 0, 0); __builtin_amdgcn_s_setprio(0); } while (0)
; #define PG8_WAIT_V(n) asm volatile("s_waitcnt vmcnt(" #n ")" ::: "memory")
; #define PG8_WAIT_L(n) asm volatile("s_waitcnt lgkmcnt(" #n ")" ::: "memory")
; #define PG8_BAR __builtin_amdgcn_s_barrier()
; #define PG8_SCHED __builtin_amdgcn_sched_barrier(0)
; template <class Epi, class Sched, bool ALIGN_EPI = false, bool SP2 = false>
; __device__ __forceinline__ void gemm_phase(PG8_LAS unsigned char* lds, const Gemm g, const Sched& S, const Epi& E, const int tid) {
;     ...
;             PG8_WAIT_V(8); PG8_WAIT_L(0); PG8_BAR; PG8_MMA(0, 0, At, B0); PG8_MMA(0, 1, At, B1); PG8_BAR; PG8_SCHED;
;             PG8_LDA(At, 1, 1); PG8_STAGE(PG8_SB(1, 0), b3, voffB); PG8_STAGE(PG8_SB(1, 1), b3 + hstepB, voffB); PG8_STAGE(PG8_SA(1, 0), a3, voffA);
.Lbw5_0:
	s_waitcnt lgkmcnt(0)
	s_barrier
	s_waitcnt lgkmcnt(0)
	v_mfma_f32_16x16x32_bf16 v[128:131], v[146:149], v[194:197], v[128:131]
	v_mfma_f32_16x16x32_bf16 v[124:127], v[170:173], v[194:197], v[124:127]
	v_mfma_f32_16x16x32_bf16 v[112:115], v[146:149], v[212:215], v[112:115]
	v_mfma_f32_16x16x32_bf16 v[108:111], v[170:173], v[212:215], v[108:111]
	v_mfma_f32_16x16x32_bf16 v[96:99], v[146:149], v[220:223], v[96:99]
	v_mfma_f32_16x16x32_bf16 v[92:95], v[170:173], v[220:223], v[92:95]
	v_mfma_f32_16x16x32_bf16 v[80:83], v[146:149], v[228:231], v[80:83]
	v_mfma_f32_16x16x32_bf16 v[76:79], v[170:173], v[228:231], v[76:79]
	v_mfma_f32_16x16x32_bf16 v[128:131], v[164:167], v[198:201], v[128:131]
	v_mfma_f32_16x16x32_bf16 v[124:127], v[174:177], v[198:201], v[124:127]
	v_mfma_f32_16x16x32_bf16 v[112:115], v[164:167], v[216:219], v[112:115]
	v_mfma_f32_16x16x32_bf16 v[108:111], v[174:177], v[216:219], v[108:111]
	v_mfma_f32_16x16x32_bf16 v[96:99], v[164:167], v[224:227], v[96:99]
	v_mfma_f32_16x16x32_bf16 v[92:95], v[174:177], v[224:227], v[92:95]
	v_mfma_f32_16x16x32_bf16 v[80:83], v[164:167], v[232:235], v[80:83]
	v_mfma_f32_16x16x32_bf16 v[76:79], v[174:177], v[232:235], v[76:79]
	v_mfma_f32_16x16x32_bf16 v[120:123], v[178:181], v[194:197], v[120:123]
	v_mfma_f32_16x16x32_bf16 v[116:119], v[186:189], v[194:197], v[116:119]
	v_mfma_f32_16x16x32_bf16 v[104:107], v[178:181], v[212:215], v[104:107]
	v_mfma_f32_16x16x32_bf16 v[100:103], v[186:189], v[212:215], v[100:103]
	v_mfma_f32_16x16x32_bf16 v[88:91], v[178:181], v[220:223], v[88:91]
	v_mfma_f32_16x16x32_bf16 v[84:87], v[186:189], v[220:223], v[84:87]
	v_mfma_f32_16x16x32_bf16 v[72:75], v[178:181], v[228:231], v[72:75]
	v_mfma_f32_16x16x32_bf16 v[68:71], v[186:189], v[228:231], v[68:71]
	v_mfma_f32_16x16x32_bf16 v[120:123], v[182:185], v[198:201], v[120:123]
	v_mfma_f32_16x16x32_bf16 v[116:119], v[190:193], v[198:201], v[116:119]
	v_mfma_f32_16x16x32_bf16 v[104:107], v[182:185], v[216:219], v[104:107]
	v_mfma_f32_16x16x32_bf16 v[100:103], v[190:193], v[216:219], v[100:103]
	v_mfma_f32_16x16x32_bf16 v[88:91], v[182:185], v[224:227], v[88:91]
	v_mfma_f32_16x16x32_bf16 v[84:87], v[190:193], v[224:227], v[84:87]
	v_mfma_f32_16x16x32_bf16 v[72:75], v[182:185], v[232:235], v[72:75]
	v_mfma_f32_16x16x32_bf16 v[68:71], v[190:193], v[232:235], v[68:71]
	s_barrier
	s_add_i32 s38, s80, s42
	v_lshl_add_u64 v[150:151], v[150:151], 0, s[52:53]
	s_mov_b32 m0, s38
	ds_read_b128 v[194:197], v163 offset:49152
	ds_read_b128 v[198:201], v163 offset:50176
	ds_read_b128 v[212:215], v163 offset:51200
	ds_read_b128 v[216:219], v163 offset:52224
	ds_read_b128 v[220:223], v163 offset:53248
	ds_read_b128 v[224:227], v163 offset:54272
	ds_read_b128 v[228:231], v163 offset:55296
	ds_read_b128 v[232:235], v163 offset:56320
	s_cmp_lg_u32 s32, 0
	s_cbranch_scc1 .Lbt5_8
	global_load_lds_dwordx4 v[150:151], off

; #define PG8_STAGE(bufoff, gbase, voff) do { _Pragma("unroll") for (int _i = 0; _i < 2; ++_i) \
;         __builtin_amdgcn_global_load_lds((const unsigned*)((const char*)(gbase) + (voff)[_i]), (PG8_LAS unsigned*)(lds + (bufoff) + ldsw + _i * 8192), 16, 0, 0); } while (0)
; #define PG8_LDA(dst, b, h) do { _Pragma("unroll") for (int m = 0; m < 4; ++m) _Pragma("unroll") for (int k = 0; k < 2; ++k) dst[m][k] = *(const PG8_LAS bf16x8*)(lds + PG8_SA(b, h) + aoff + m * 2048 + k * 1024); } while (0)
; #define PG8_MMA(ai, bj, At, Bt) do { __builtin_amdgcn_s_setprio(1); _Pragma("unroll") for (int m = 0; m < 4; ++m) _Pragma("unroll") for (int n = 0; n < 2; ++n) _Pragma("unroll") for (int k = 0; k < 2; ++k) \
;         acc[ai][bj][m][n] = __builtin_amdgcn_mfma_f32_16x16x32_bf16(Bt[n][k], At[m][k], acc[ai][bj][m][n], 0, 0, 0); __builtin_amdgcn_s_setprio(0); } while (0)
; #define PG8_WAIT_V(n) asm volatile("s_waitcnt vmcnt(" #n ")" ::: "memory")
; #define PG8_WAIT_L(n) asm volatile("s_waitcnt lgkmcnt(" #n ")" ::: "memory")
; #define PG8_BAR __builtin_amdgcn_s_barrier()
; #define PG8_SCHED __builtin_amdgcn_sched_barrier(0)
; template <class Epi, class Sched, bool ALIGN_EPI = false, bool SP2 = false>
; __device__ __forceinline__ void gemm_phase(PG8_LAS unsigned char* lds, const Gemm g, const Sched& S, const Epi& E, const int tid) {
;     ...
;         for (int t = 0; t < nt; t += 2) {
;             const bool last = (t == nt - 2);
;             const char* a1 = cA + (size_t)(t + 1) * kstep;
;             const char* a2 = last ? nA : cA + (size_t)(t + 2) * kstep; const char* b2 = last ? nB : cB + (size_t)(t + 2) * kstep;
;             const char* a3 = a2 + kstep; const char* b3 = b2 + kstep;
;     ...
;             PG8_LDA(At, 1, 1); PG8_STAGE(PG8_SB(1, 0), b3, voffB); PG8_STAGE(PG8_SB(1, 1), b3 + hstepB, voffB); PG8_STAGE(PG8_SA(1, 0), a3, voffA);
;             PG8_WAIT_V(8); PG8_WAIT_L(0); PG8_BAR; PG8_MMA(1, 0, At, B0); PG8_MMA(1, 1, At, B1); PG8_BAR; PG8_SCHED;
.Lbt5_13:
	s_waitcnt vmcnt(8)
	s_waitcnt lgkmcnt(0)
	s_barrier
	s_waitcnt lgkmcnt(0)
	v_mfma_f32_16x16x32_bf16 v[64:67], v[146:149], v[194:197], v[64:67]
	v_mfma_f32_16x16x32_bf16 v[60:63], v[170:173], v[194:197], v[60:63]
	v_mfma_f32_16x16x32_bf16 v[48:51], v[146:149], v[212:215], v[48:51]
	v_mfma_f32_16x16x32_bf16 v[44:47], v[170:173], v[212:215], v[44:47]
	v_mfma_f32_16x16x32_bf16 v[32:35], v[146:149], v[220:223], v[32:35]
	v_mfma_f32_16x16x32_bf16 v[28:31], v[170:173], v[220:223], v[28:31]
	v_mfma_f32_16x16x32_bf16 v[16:19], v[146:149], v[228:231], v[16:19]
	v_mfma_f32_16x16x32_bf16 v[12:15], v[170:173], v[228:231], v[12:15]
	v_mfma_f32_16x16x32_bf16 v[64:67], v[164:167], v[198:201], v[64:67]
	v_mfma_f32_16x16x32_bf16 v[60:63], v[174:177], v[198:201], v[60:63]
	v_mfma_f32_16x16x32_bf16 v[48:51], v[164:167], v[216:219], v[48:51]
	v_mfma_f32_16x16x32_bf16 v[44:47], v[174:177], v[216:219], v[44:47]
	v_mfma_f32_16x16x32_bf16 v[32:35], v[164:167], v[224:227], v[32:35]
	v_mfma_f32_16x16x32_bf16 v[28:31], v[174:177], v[224:227], v[28:31]
	v_mfma_f32_16x16x32_bf16 v[16:19], v[164:167], v[232:235], v[16:19]
	v_mfma_f32_16x16x32_bf16 v[12:15], v[174:177], v[232:235], v[12:15]
	v_mfma_f32_16x16x32_bf16 v[56:59], v[178:181], v[194:197], v[56:59]
	v_mfma_f32_16x16x32_bf16 v[52:55], v[186:189], v[194:197], v[52:55]
	v_mfma_f32_16x16x32_bf16 v[40:43], v[178:181], v[212:215], v[40:43]
	v_mfma_f32_16x16x32_bf16 v[36:39], v[186:189], v[212:215], v[36:39]
	v_mfma_f32_16x16x32_bf16 v[24:27], v[178:181], v[220:223], v[24:27]
	v_mfma_f32_16x16x32_bf16 v[20:23], v[186:189], v[220:223], v[20:23]
	v_mfma_f32_16x16x32_bf16 v[8:11], v[178:181], v[228:231], v[8:11]
	v_mfma_f32_16x16x32_bf16 v[4:7], v[186:189], v[228:231], v[4:7]
	v_mfma_f32_16x16x32_bf16 v[56:59], v[182:185], v[198:201], v[56:59]
	v_mfma_f32_16x16x32_bf16 v[52:55], v[190:193], v[198:201], v[52:55]
	v_mfma_f32_16x16x32_bf16 v[40:43], v[182:185], v[216:219], v[40:43]
	v_mfma_f32_16x16x32_bf16 v[36:39], v[190:193], v[216:219], v[36:39]
	v_mfma_f32_16x16x32_bf16 v[24:27], v[182:185], v[224:227], v[24:27]
	v_mfma_f32_16x16x32_bf16 v[20:23], v[190:193], v[224:227], v[20:23]
	v_mfma_f32_16x16x32_bf16 v[8:11], v[182:185], v[232:235], v[8:11]
	v_mfma_f32_16x16x32_bf16 v[4:7], v[190:193], v[232:235], v[4:7]
	s_barrier
	s_add_i32 s79, s79, 2
	s_cmp_gt_u32 s79, 13
	s_cbranch_scc0 .LBB0_1380
	s_and_b64 vcc, exec, s[14:15]
	s_cbranch_vccz .LBB0_1383
	s_barrier

; DI float bf_lo(unsigned u) { return __uint_as_float(u << 16); }
; DI float bf_hi(unsigned u) { return __uint_as_float(u & 0xffff0000u); }
; #define PG8_STAGE(bufoff, gbase, voff) do { _Pragma("unroll") for (int _i = 0; _i < 2; ++_i) \
;         __builtin_amdgcn_global_load_lds((const unsigned*)((const char*)(gbase) + (voff)[_i]), (PG8_LAS unsigned*)(lds + (bufoff) + ldsw + _i * 8192), 16, 0, 0); } while (0)
; #define PG8_WAIT_V(n) asm volatile("s_waitcnt vmcnt(" #n ")" ::: "memory")
; #define PG8_BAR __builtin_amdgcn_s_barrier()
;     DI void init_finish(f32x4 (&acc)[2][2][4][2], const u32x4 (&w)[R8::HAS_PRE ? 16 : 1]) const {
;         if constexpr (R8::HAS_PRE) {
; #pragma unroll
;             for (int ai = 0; ai < 2; ++ai)
; #pragma unroll
;                 for (int m = 0; m < 4; ++m)
; #pragma unroll
;                     for (int bj = 0; bj < 2; ++bj) { const u32x4 v = w[(ai * 4 + m) * 2 + bj];
;                         acc[ai][bj][m][0] = (f32x4){bf_lo(v.x), bf_hi(v.x), bf_lo(v.y), bf_hi(v.y)}; acc[ai][bj][m][1] = (f32x4){bf_lo(v.z), bf_hi(v.z), bf_lo(v.w), bf_hi(v.w)}; }
;         }
;     }
; template <class Epi, class Sched, bool ALIGN_EPI = false, bool SP2 = false>
; __device__ __forceinline__ void gemm_phase(PG8_LAS unsigned char* lds, const Gemm g, const Sched& S, const Epi& E, const int tid) {
;     ...
;     if constexpr (SP2) {
;         PG8_STAGE(PG8_SB(0, 0), cB, voffB); PG8_STAGE(PG8_SB(0, 1), cB + hstepB, voffB); PG8_STAGE(PG8_SA(0, 0), cA, voffA); PG8_STAGE(PG8_SA(0, 1), cA + hstep, voffA);
;         if (wr == 1) PG8_BAR;
;         PG8_WAIT_V(2); PG8_BAR;
;         PG8_STAGE(PG8_SB(1, 0), cB + kstep, voffB); PG8_STAGE(PG8_SA(1, 0), cA + kstep, voffA); PG8_STAGE(PG8_SB(1, 1), cB + hstepB + kstep, voffB);
;         PG8_WAIT_V(6); PG8_BAR;
;     } else {
;         PG8_STAGE(PG8_SB(0, 0), cB, voffB); PG8_STAGE(PG8_SA(0, 0), cA, voffA); PG8_STAGE(PG8_SB(0, 1), cB + hstepB, voffB); PG8_STAGE(PG8_SA(0, 1), cA + hstep, voffA);
;         if (wr == 1) PG8_BAR;
;         PG8_WAIT_V(4); PG8_BAR;
;         PG8_STAGE(PG8_SB(1, 0), cB + kstep, voffB); PG8_STAGE(PG8_SA(1, 0), cA + kstep, voffA); PG8_STAGE(PG8_SB(1, 1), cB + hstepB + kstep, voffB);
;         PG8_WAIT_V(6); PG8_BAR;
;     }
;     if constexpr (Epi::HAS_INIT) E.init_finish(acc, iw_);
.LBB0_1454:
	v_or_b32_e32 v157, s15, v152
	v_lshlrev_b32_e32 v76, 6, v157
	v_lshlrev_b32_e32 v77, 4, v146
	s_movk_i32 s15, 0x3c0
	v_lshlrev_b32_e32 v78, 2, v157
	v_and_or_b32 v76, v76, s15, v77
	s_lshl_b32 s5, s5, 13
	v_and_b32_e32 v78, 32, v78
	v_bitop3_b32 v149, v76, s5, v78 bitop3:0xde
	v_lshl_or_b32 v76, v152, 6, v77
	v_lshlrev_b32_e32 v77, 2, v152
	s_add_i32 m0, s29, 0x18000
	v_lshl_add_u64 v[74:75], v[74:75], 0, s[52:53]
	s_lshl_b32 s4, s4, 12
	v_and_b32_e32 v77, 32, v77
	s_waitcnt vmcnt(2)
	s_barrier
	global_load_lds_dwordx4 v[74:75], off
	v_lshl_add_u64 v[72:73], v[72:73], 0, s[52:53]
	s_add_i32 m0, s29, 0x1a000
	s_add_i32 s64, s29, 0x8000
	s_add_i32 s65, s29, 0xa000
	v_bitop3_b32 v158, v76, s4, v77 bitop3:0xde
	global_load_lds_dwordx4 v[72:73], off
	v_lshl_add_u64 v[68:69], v[68:69], 0, s[52:53]
	s_mov_b32 m0, s64
	s_add_u32 s4, s36, 0x40080
	global_load_lds_dwordx4 v[68:69], off
	v_lshl_add_u64 v[68:69], v[70:71], 0, s[52:53]
	s_mov_b32 m0, s65
	s_addc_u32 s5, s37, 0
	global_load_lds_dwordx4 v[68:69], off
	s_add_i32 m0, s29, 0x1c000
	v_lshl_add_u64 v[68:69], s[4:5], 0, v[136:137]
	global_load_lds_dwordx4 v[68:69], off
	v_lshl_add_u64 v[68:69], s[4:5], 0, v[140:141]
	s_add_i32 m0, s29, 0x1e000
	v_cmp_eq_u32_e64 s[4:5], 0, v146
	global_load_lds_dwordx4 v[68:69], off
	v_lshlrev_b32_e32 v146, 16, v142
	v_and_b32_e32 v146, 0xfffe0000, v146
	v_lshl_add_u32 v143, v143, 13, v146
	v_and_b32_e32 v142, 1, v142
	v_lshl_or_b32 v142, v142, 6, v143
	v_lshl_add_u32 v142, v144, 1, v142
	v_lshlrev_b32_e32 v144, 16, v145
	v_and_b32_e32 v144, 0xfffe0000, v144
	s_waitcnt vmcnt(6)
	v_lshl_add_u32 v144, v147, 13, v144
	v_and_b32_e32 v145, 1, v145
	s_cmpk_lt_u32 s14, 0x100
	v_lshl_or_b32 v144, v145, 6, v144
	s_waitcnt vmcnt(0)
	v_lshlrev_b32_e32 v120, 16, v64
	v_and_b32_e32 v121, 0xffff0000, v64
	v_lshlrev_b32_e32 v122, 16, v65
	v_and_b32_e32 v123, 0xffff0000, v65
	v_lshlrev_b32_e32 v128, 16, v66
	v_and_b32_e32 v129, 0xffff0000, v66
	v_lshlrev_b32_e32 v130, 16, v67
	v_and_b32_e32 v131, 0xffff0000, v67
	v_lshlrev_b32_e32 v116, 16, v56
	v_and_b32_e32 v117, 0xffff0000, v56
	v_lshlrev_b32_e32 v118, 16, v57
	v_and_b32_e32 v119, 0xffff0000, v57
	v_lshlrev_b32_e32 v124, 16, v58
	v_and_b32_e32 v125, 0xffff0000, v58
	v_lshlrev_b32_e32 v126, 16, v59
	v_and_b32_e32 v127, 0xffff0000, v59
	v_lshlrev_b32_e32 v100, 16, v60
	v_and_b32_e32 v101, 0xffff0000, v60
	v_lshlrev_b32_e32 v102, 16, v61
	v_and_b32_e32 v103, 0xffff0000, v61
	v_lshlrev_b32_e32 v108, 16, v62
	v_and_b32_e32 v109, 0xffff0000, v62
	v_lshlrev_b32_e32 v110, 16, v63
	v_and_b32_e32 v111, 0xffff0000, v63
	v_lshlrev_b32_e32 v104, 16, v48
	v_and_b32_e32 v105, 0xffff0000, v48
	v_lshlrev_b32_e32 v106, 16, v49
	v_and_b32_e32 v107, 0xffff0000, v49
	v_lshlrev_b32_e32 v112, 16, v50
	v_and_b32_e32 v113, 0xffff0000, v50
	v_lshlrev_b32_e32 v114, 16, v51
	v_and_b32_e32 v115, 0xffff0000, v51
	v_lshlrev_b32_e32 v84, 16, v52
	v_and_b32_e32 v85, 0xffff0000, v52
	v_lshlrev_b32_e32 v86, 16, v53
	v_and_b32_e32 v87, 0xffff0000, v53
	v_lshlrev_b32_e32 v92, 16, v54
	v_and_b32_e32 v93, 0xffff0000, v54
	v_lshlrev_b32_e32 v94, 16, v55
	v_and_b32_e32 v95, 0xffff0000, v55
	v_lshlrev_b32_e32 v88, 16, v40
	v_and_b32_e32 v89, 0xffff0000, v40
	v_lshlrev_b32_e32 v90, 16, v41
	v_and_b32_e32 v91, 0xffff0000, v41
	v_lshlrev_b32_e32 v96, 16, v42
	v_and_b32_e32 v97, 0xffff0000, v42
	v_lshlrev_b32_e32 v98, 16, v43
	v_and_b32_e32 v99, 0xffff0000, v43
	v_lshlrev_b32_e32 v68, 16, v44
	v_and_b32_e32 v69, 0xffff0000, v44
	v_lshlrev_b32_e32 v70, 16, v45
	v_and_b32_e32 v71, 0xffff0000, v45
	v_lshlrev_b32_e32 v76, 16, v46
	v_and_b32_e32 v77, 0xffff0000, v46
	v_lshlrev_b32_e32 v78, 16, v47
	v_and_b32_e32 v79, 0xffff0000, v47
	v_lshlrev_b32_e32 v72, 16, v36
	v_and_b32_e32 v73, 0xffff0000, v36
	v_lshlrev_b32_e32 v74, 16, v37
	v_and_b32_e32 v75, 0xffff0000, v37
	v_lshlrev_b32_e32 v80, 16, v38
	v_and_b32_e32 v81, 0xffff0000, v38
	v_lshlrev_b32_e32 v82, 16, v39
	v_and_b32_e32 v83, 0xffff0000, v39
	v_lshlrev_b32_e32 v52, 16, v32
	v_and_b32_e32 v53, 0xffff0000, v32
	v_lshlrev_b32_e32 v54, 16, v33
	v_and_b32_e32 v55, 0xffff0000, v33
	v_lshlrev_b32_e32 v60, 16, v34
	v_and_b32_e32 v61, 0xffff0000, v34
	v_lshlrev_b32_e32 v62, 16, v35
	v_and_b32_e32 v63, 0xffff0000, v35
	v_lshlrev_b32_e32 v56, 16, v28
	v_and_b32_e32 v57, 0xffff0000, v28
	v_lshlrev_b32_e32 v58, 16, v29
	v_and_b32_e32 v59, 0xffff0000, v29
	v_lshlrev_b32_e32 v64, 16, v30
	v_and_b32_e32 v65, 0xffff0000, v30
	v_lshlrev_b32_e32 v66, 16, v31
	v_and_b32_e32 v67, 0xffff0000, v31
	v_lshlrev_b32_e32 v36, 16, v24
	v_and_b32_e32 v37, 0xffff0000, v24
	v_lshlrev_b32_e32 v38, 16, v25
	v_and_b32_e32 v39, 0xffff0000, v25
	v_lshlrev_b32_e32 v44, 16, v26
	v_and_b32_e32 v45, 0xffff0000, v26
	v_lshlrev_b32_e32 v46, 16, v27
	v_and_b32_e32 v47, 0xffff0000, v27
	v_lshlrev_b32_e32 v40, 16, v20
	v_and_b32_e32 v41, 0xffff0000, v20
	v_lshlrev_b32_e32 v42, 16, v21
	v_and_b32_e32 v43, 0xffff0000, v21
	v_lshlrev_b32_e32 v48, 16, v22
	v_and_b32_e32 v49, 0xffff0000, v22
	v_lshlrev_b32_e32 v50, 16, v23
	v_and_b32_e32 v51, 0xffff0000, v23
	v_lshlrev_b32_e32 v20, 16, v12
	v_and_b32_e32 v21, 0xffff0000, v12
	v_lshlrev_b32_e32 v22, 16, v13
	v_and_b32_e32 v23, 0xffff0000, v13
	v_lshlrev_b32_e32 v28, 16, v14
	v_and_b32_e32 v29, 0xffff0000, v14
	v_lshlrev_b32_e32 v30, 16, v15
	v_and_b32_e32 v31, 0xffff0000, v15
	v_lshlrev_b32_e32 v24, 16, v4
	v_and_b32_e32 v25, 0xffff0000, v4
	v_lshlrev_b32_e32 v26, 16, v5
	v_and_b32_e32 v27, 0xffff0000, v5
	v_lshlrev_b32_e32 v32, 16, v6
	v_and_b32_e32 v33, 0xffff0000, v6
	v_lshlrev_b32_e32 v34, 16, v7
	v_and_b32_e32 v35, 0xffff0000, v7
	v_lshlrev_b32_e32 v4, 16, v8
	v_and_b32_e32 v5, 0xffff0000, v8
	v_lshlrev_b32_e32 v6, 16, v9
	v_and_b32_e32 v7, 0xffff0000, v9
	v_lshlrev_b32_e32 v12, 16, v10
	v_and_b32_e32 v13, 0xffff0000, v10
	v_lshlrev_b32_e32 v14, 16, v11
	v_and_b32_e32 v15, 0xffff0000, v11
	v_lshlrev_b32_e32 v8, 16, v16
	v_and_b32_e32 v9, 0xffff0000, v16
	v_lshlrev_b32_e32 v10, 16, v17
	v_and_b32_e32 v11, 0xffff0000, v17
	v_lshlrev_b32_e32 v16, 16, v18
	v_and_b32_e32 v17, 0xffff0000, v18
	v_lshlrev_b32_e32 v18, 16, v19
	v_and_b32_e32 v19, 0xffff0000, v19
	s_cselect_b64 s[14:15], -1, 0
	s_mov_b32 s66, 0
	s_lshl_b32 s67, s27, 3
	v_or_b32_e32 v159, s54, v156
	v_mov_b32_e32 v143, v2
	v_lshl_add_u32 v144, v148, 1, v144
	v_mov_b32_e32 v145, v2
	v_add_u32_e32 v160, 0, v149
	s_barrier
	v_readfirstlane_b32 s98, v0
	s_nop 3
	s_and_b32 s98, s98, 0x3ff
	s_lshr_b32 s98, s98, 6
	s_cmp_ge_u32 s98, 4
	s_cbranch_scc0 .Lprio_done6
	s_setprio 1
; DI float bf_lo(unsigned u) { return __uint_as_float(u << 16); }
; DI float bf_hi(unsigned u) { return __uint_as_float(u & 0xffff0000u); }
;     DI void init_finish(f32x4 (&acc)[2][2][4][2], const u32x4 (&w)[R8::HAS_PRE ? 16 : 1]) const {
;         if constexpr (R8::HAS_PRE) {
; #pragma unroll
;             for (int ai = 0; ai < 2; ++ai)
; #pragma unroll
;                 for (int m = 0; m < 4; ++m)
; #pragma unroll
;                     for (int bj = 0; bj < 2; ++bj) { const u32x4 v = w[(ai * 4 + m) * 2 + bj];
;                         acc[ai][bj][m][0] = (f32x4){bf_lo(v.x), bf_hi(v.x), bf_lo(v.y), bf_hi(v.y)}; acc[ai][bj][m][1] = (f32x4){bf_lo(v.z), bf_hi(v.z), bf_lo(v.w), bf_hi(v.w)}; }
;         }
;     }
;     DI void init(f32x4 (&acc)[2][2][4][2], const Unit& u, int wr, int wc, int fr, int fq) const { u32x4 w[R8::HAS_PRE ? 16 : 1]; init_issue(w, u, wr, wc, fr, fq); init_finish(acc, w); }
; template <class Epi, class Sched, bool ALIGN_EPI = false, bool SP2 = false>
; __device__ __forceinline__ void gemm_phase(PG8_LAS unsigned char* lds, const Gemm g, const Sched& S, const Epi& E, const int tid) {
;     ...
;         if constexpr (!Epi::AFTER_DRAIN) { E(acc, cur, wr, wc, fr, fq); S.done(cur); }
;         if (!has_next) break;
;         if constexpr (Epi::HAS_INIT) E.init(acc, nxt, wr, wc, fr, fq);
.Lprio_done6:
	s_branch .LBB0_1457
.LBB0_1455:
	s_waitcnt vmcnt(0)
	v_lshlrev_b32_e32 v120, 16, v66
	v_and_b32_e32 v121, 0xffff0000, v66
	v_lshlrev_b32_e32 v122, 16, v67
	v_and_b32_e32 v123, 0xffff0000, v67
	v_lshlrev_b32_e32 v128, 16, v68
	v_and_b32_e32 v129, 0xffff0000, v68
	v_lshlrev_b32_e32 v130, 16, v69
	v_and_b32_e32 v131, 0xffff0000, v69
	v_lshlrev_b32_e32 v116, 16, v58
	v_and_b32_e32 v117, 0xffff0000, v58
	v_lshlrev_b32_e32 v118, 16, v59
	v_and_b32_e32 v119, 0xffff0000, v59
	v_lshlrev_b32_e32 v124, 16, v60
	v_and_b32_e32 v125, 0xffff0000, v60
	v_lshlrev_b32_e32 v126, 16, v61
	v_and_b32_e32 v127, 0xffff0000, v61
	v_lshlrev_b32_e32 v100, 16, v62
	v_and_b32_e32 v101, 0xffff0000, v62
	v_lshlrev_b32_e32 v102, 16, v63
	v_and_b32_e32 v103, 0xffff0000, v63
	v_lshlrev_b32_e32 v108, 16, v64
	v_and_b32_e32 v109, 0xffff0000, v64
	v_lshlrev_b32_e32 v110, 16, v65
	v_and_b32_e32 v111, 0xffff0000, v65
	v_lshlrev_b32_e32 v104, 16, v50
	v_and_b32_e32 v105, 0xffff0000, v50
	v_lshlrev_b32_e32 v106, 16, v51
	v_and_b32_e32 v107, 0xffff0000, v51
	v_lshlrev_b32_e32 v112, 16, v52
	v_and_b32_e32 v113, 0xffff0000, v52
	v_lshlrev_b32_e32 v114, 16, v53
	v_and_b32_e32 v115, 0xffff0000, v53
	v_lshlrev_b32_e32 v84, 16, v54
	v_and_b32_e32 v85, 0xffff0000, v54
	v_lshlrev_b32_e32 v86, 16, v55
	v_and_b32_e32 v87, 0xffff0000, v55
	v_lshlrev_b32_e32 v92, 16, v56
	v_and_b32_e32 v93, 0xffff0000, v56
	v_lshlrev_b32_e32 v94, 16, v57
	v_and_b32_e32 v95, 0xffff0000, v57
	v_lshlrev_b32_e32 v88, 16, v42
	v_and_b32_e32 v89, 0xffff0000, v42
	v_lshlrev_b32_e32 v90, 16, v43
	v_and_b32_e32 v91, 0xffff0000, v43
	v_lshlrev_b32_e32 v96, 16, v44
	v_and_b32_e32 v97, 0xffff0000, v44
	v_lshlrev_b32_e32 v98, 16, v45
	v_and_b32_e32 v99, 0xffff0000, v45
	v_lshlrev_b32_e32 v68, 16, v46
	v_and_b32_e32 v69, 0xffff0000, v46
	v_lshlrev_b32_e32 v70, 16, v47
	v_and_b32_e32 v71, 0xffff0000, v47
	v_lshlrev_b32_e32 v76, 16, v48
	v_and_b32_e32 v77, 0xffff0000, v48
	v_lshlrev_b32_e32 v78, 16, v49
	v_and_b32_e32 v79, 0xffff0000, v49
	v_lshlrev_b32_e32 v72, 16, v34
	v_and_b32_e32 v73, 0xffff0000, v34
	v_lshlrev_b32_e32 v74, 16, v35
	v_and_b32_e32 v75, 0xffff0000, v35
	v_lshlrev_b32_e32 v80, 16, v36
	v_and_b32_e32 v81, 0xffff0000, v36
	v_lshlrev_b32_e32 v82, 16, v37
	v_and_b32_e32 v83, 0xffff0000, v37
	v_lshlrev_b32_e32 v52, 16, v38
	v_and_b32_e32 v53, 0xffff0000, v38
	v_lshlrev_b32_e32 v54, 16, v39
	v_and_b32_e32 v55, 0xffff0000, v39
	v_lshlrev_b32_e32 v60, 16, v40
	v_and_b32_e32 v61, 0xffff0000, v40
	v_lshlrev_b32_e32 v62, 16, v41
	v_and_b32_e32 v63, 0xffff0000, v41
	v_lshlrev_b32_e32 v56, 16, v26
	v_and_b32_e32 v57, 0xffff0000, v26
	v_lshlrev_b32_e32 v58, 16, v27
	v_and_b32_e32 v59, 0xffff0000, v27
	v_lshlrev_b32_e32 v64, 16, v28
	v_and_b32_e32 v65, 0xffff0000, v28
	v_lshlrev_b32_e32 v66, 16, v29
	v_and_b32_e32 v67, 0xffff0000, v29
	v_lshlrev_b32_e32 v36, 16, v30
	v_and_b32_e32 v37, 0xffff0000, v30
	v_lshlrev_b32_e32 v38, 16, v31
	v_and_b32_e32 v39, 0xffff0000, v31
	v_lshlrev_b32_e32 v44, 16, v32
	v_and_b32_e32 v45, 0xffff0000, v32
	v_lshlrev_b32_e32 v46, 16, v33
	v_and_b32_e32 v47, 0xffff0000, v33
	v_lshlrev_b32_e32 v40, 16, v12
	v_and_b32_e32 v41, 0xffff0000, v12
	v_lshlrev_b32_e32 v42, 16, v13
	v_and_b32_e32 v43, 0xffff0000, v13
	v_lshlrev_b32_e32 v48, 16, v14
	v_and_b32_e32 v49, 0xffff0000, v14
	v_lshlrev_b32_e32 v50, 16, v15
	v_and_b32_e32 v51, 0xffff0000, v15
	v_lshlrev_b32_e32 v20, 16, v22
	v_and_b32_e32 v21, 0xffff0000, v22
	v_lshlrev_b32_e32 v22, 16, v23
	v_and_b32_e32 v23, 0xffff0000, v23
	v_lshlrev_b32_e32 v28, 16, v24
	v_and_b32_e32 v29, 0xffff0000, v24
	v_lshlrev_b32_e32 v30, 16, v25
	v_and_b32_e32 v31, 0xffff0000, v25
	v_lshlrev_b32_e32 v24, 16, v4
	v_and_b32_e32 v25, 0xffff0000, v4
	v_lshlrev_b32_e32 v26, 16, v5
	v_and_b32_e32 v27, 0xffff0000, v5
	v_lshlrev_b32_e32 v32, 16, v6
	v_and_b32_e32 v33, 0xffff0000, v6
	v_lshlrev_b32_e32 v34, 16, v7
	v_and_b32_e32 v35, 0xffff0000, v7
	v_lshlrev_b32_e32 v4, 16, v8
	v_and_b32_e32 v5, 0xffff0000, v8
	v_lshlrev_b32_e32 v6, 16, v9
	v_and_b32_e32 v7, 0xffff0000, v9
	v_lshlrev_b32_e32 v12, 16, v10
	v_and_b32_e32 v13, 0xffff0000, v10
	v_lshlrev_b32_e32 v14, 16, v11
	v_and_b32_e32 v15, 0xffff0000, v11
	v_lshlrev_b32_e32 v8, 16, v16
	v_and_b32_e32 v9, 0xffff0000, v16
	v_lshlrev_b32_e32 v10, 16, v17
	v_and_b32_e32 v11, 0xffff0000, v17
	v_lshlrev_b32_e32 v16, 16, v18
	v_and_b32_e32 v17, 0xffff0000, v18
	v_lshlrev_b32_e32 v18, 16, v19
	v_and_b32_e32 v19, 0xffff0000, v19
	s_mov_b64 s[24:25], 0

;     DI bool next(int i, Unit& u) const { const int L = i * 32 + rank; if (L >= ppg * nN) return false; u.pm = ppg * grp + (L % ppg); const int p0 = L / ppg, p1 = p0 + rot; u.pn = rev ? nN - 1 - p0 : (p1 >= nN ? p1 - nN : p1); return true; }
; #define PG8_STAGE(bufoff, gbase, voff) do { _Pragma("unroll") for (int _i = 0; _i < 2; ++_i) \
;         __builtin_amdgcn_global_load_lds((const unsigned*)((const char*)(gbase) + (voff)[_i]), (PG8_LAS unsigned*)(lds + (bufoff) + ldsw + _i * 8192), 16, 0, 0); } while (0)
; #define PG8_LDA(dst, b, h) do { _Pragma("unroll") for (int m = 0; m < 4; ++m) _Pragma("unroll") for (int k = 0; k < 2; ++k) dst[m][k] = *(const PG8_LAS bf16x8*)(lds + PG8_SA(b, h) + aoff + m * 2048 + k * 1024); } while (0)
; #define PG8_LDB(dst, b, h) do { _Pragma("unroll") for (int n = 0; n < 2; ++n) _Pragma("unroll") for (int k = 0; k < 2; ++k) dst[n][k] = *(const PG8_LAS bf16x8*)(lds + PG8_SB(b, h) + boff + n * 2048 + k * 1024); } while (0)
; #define PG8_WAIT_V(n) asm volatile("s_waitcnt vmcnt(" #n ")" ::: "memory")
; #define PG8_WAIT_L(n) asm volatile("s_waitcnt lgkmcnt(" #n ")" ::: "memory")
; template <class Epi, class Sched, bool ALIGN_EPI = false, bool SP2 = false>
; __device__ __forceinline__ void gemm_phase(PG8_LAS unsigned char* lds, const Gemm g, const Sched& S, const Epi& E, const int tid) {
;     ...
;         const bool has_next = S.next(ui + 1, nxt);
;         const char* nA = has_next ? (const char*)g.A + (size_t)nxt.pm * tstep : cA; const char* nB = has_next ? (const char*)g.Bt + (size_t)nxt.pn * tstep : cB;
;         for (int t = 0; t < nt; t += 2) {
;             const bool last = (t == nt - 2);
;             const char* a1 = cA + (size_t)(t + 1) * kstep;
;             const char* a2 = last ? nA : cA + (size_t)(t + 2) * kstep; const char* b2 = last ? nB : cB + (size_t)(t + 2) * kstep;
;             const char* a3 = a2 + kstep; const char* b3 = b2 + kstep;
;             if (last && has_next) S.a_ready(nxt);
;             if constexpr (SP2) {
;             PG8_LDB(B0, 0, 0); PG8_LDB(B1, 0, 1); PG8_SCHED; PG8_LDA(At, 0, 0); PG8_STAGE(PG8_SA(1, 1), a1 + hstep, voffA);
;             PG8_WAIT_V(8); PG8_WAIT_L(0); PG8_BAR; PG8_MMA(0, 0, At, B0); PG8_MMA(0, 1, At, B1); PG8_BAR; PG8_SCHED;
;             PG8_LDA(At, 0, 1); PG8_STAGE(PG8_SB(0, 0), b2, voffB); PG8_STAGE(PG8_SB(0, 1), b2 + hstepB, voffB); PG8_STAGE(PG8_SA(0, 0), a2, voffA);
.LBB0_1460:
	s_add_u32 s36, s38, 0xfff00080
	s_addc_u32 s37, s39, -1
	s_add_i32 s81, 0, 0x10000
	s_cmp_eq_u32 s80, 60
	s_cselect_b32 s41, s19, s37
	s_cselect_b32 s40, s25, s36
	v_add_u32_e32 v150, s81, v158
	s_cselect_b32 s37, s17, s79
	s_cselect_b32 s36, s76, s78
	s_cmp_eq_u32 s80, 60
	s_cselect_b32 s32, 1, 0
	s_andn2_b32 s32, s32, s30
	s_add_i32 s84, 0, 0x14000
	ds_read_b128 v[146:149], v150
	ds_read_b128 v[162:165], v150 offset:1024
	ds_read_b128 v[170:173], v150 offset:2048
	ds_read_b128 v[174:177], v150 offset:3072
	v_add_u32_e32 v150, s84, v158
	ds_read_b128 v[178:181], v150
	ds_read_b128 v[182:185], v150 offset:1024
	ds_read_b128 v[186:189], v150 offset:2048
	ds_read_b128 v[190:193], v150 offset:3072
	v_lshl_add_u64 v[150:151], s[38:39], 0, v[142:143]
	s_add_i32 m0, s29, 0xc000
	ds_read_b128 v[194:197], v160
	ds_read_b128 v[198:201], v160 offset:1024
	ds_read_b128 v[212:215], v160 offset:2048
	ds_read_b128 v[216:219], v160 offset:3072
	ds_read_b128 v[220:223], v160 offset:4096
	ds_read_b128 v[224:227], v160 offset:5120
	ds_read_b128 v[228:231], v160 offset:6144
	ds_read_b128 v[232:235], v160 offset:7168
	global_load_lds_dwordx4 v[150:151], off
	v_lshl_add_u64 v[150:151], s[38:39], 0, v[144:145]
	s_add_i32 m0, s29, 0xe000
	s_nop 0
	global_load_lds_dwordx4 v[150:151], off
	s_waitcnt vmcnt(8)
	s_waitcnt lgkmcnt(0)
	s_barrier
	s_waitcnt lgkmcnt(0)
	v_mfma_f32_16x16x32_bf16 v[120:123], v[146:149], v[194:197], v[120:123]
	v_mfma_f32_16x16x32_bf16 v[128:131], v[170:173], v[194:197], v[128:131]
	v_mfma_f32_16x16x32_bf16 v[100:103], v[146:149], v[212:215], v[100:103]
	v_mfma_f32_16x16x32_bf16 v[108:111], v[170:173], v[212:215], v[108:111]
	v_mfma_f32_16x16x32_bf16 v[84:87], v[146:149], v[220:223], v[84:87]
	v_mfma_f32_16x16x32_bf16 v[92:95], v[170:173], v[220:223], v[92:95]
	v_mfma_f32_16x16x32_bf16 v[68:71], v[146:149], v[228:231], v[68:71]
	v_mfma_f32_16x16x32_bf16 v[76:79], v[170:173], v[228:231], v[76:79]
	v_mfma_f32_16x16x32_bf16 v[120:123], v[162:165], v[198:201], v[120:123]
	v_mfma_f32_16x16x32_bf16 v[128:131], v[174:177], v[198:201], v[128:131]
	v_mfma_f32_16x16x32_bf16 v[100:103], v[162:165], v[216:219], v[100:103]
	v_mfma_f32_16x16x32_bf16 v[108:111], v[174:177], v[216:219], v[108:111]
	v_mfma_f32_16x16x32_bf16 v[84:87], v[162:165], v[224:227], v[84:87]
	v_mfma_f32_16x16x32_bf16 v[92:95], v[174:177], v[224:227], v[92:95]
	v_mfma_f32_16x16x32_bf16 v[68:71], v[162:165], v[232:235], v[68:71]
	v_mfma_f32_16x16x32_bf16 v[76:79], v[174:177], v[232:235], v[76:79]
	v_mfma_f32_16x16x32_bf16 v[116:119], v[178:181], v[194:197], v[116:119]
	v_mfma_f32_16x16x32_bf16 v[124:127], v[186:189], v[194:197], v[124:127]
	v_mfma_f32_16x16x32_bf16 v[104:107], v[178:181], v[212:215], v[104:107]
	v_mfma_f32_16x16x32_bf16 v[112:115], v[186:189], v[212:215], v[112:115]
	v_mfma_f32_16x16x32_bf16 v[88:91], v[178:181], v[220:223], v[88:91]
	v_mfma_f32_16x16x32_bf16 v[96:99], v[186:189], v[220:223], v[96:99]
	v_mfma_f32_16x16x32_bf16 v[72:75], v[178:181], v[228:231], v[72:75]
	v_mfma_f32_16x16x32_bf16 v[80:83], v[186:189], v[228:231], v[80:83]
	v_mfma_f32_16x16x32_bf16 v[116:119], v[182:185], v[198:201], v[116:119]
	v_mfma_f32_16x16x32_bf16 v[124:127], v[190:193], v[198:201], v[124:127]
	v_mfma_f32_16x16x32_bf16 v[104:107], v[182:185], v[216:219], v[104:107]
	v_mfma_f32_16x16x32_bf16 v[112:115], v[190:193], v[216:219], v[112:115]
	v_mfma_f32_16x16x32_bf16 v[88:91], v[182:185], v[224:227], v[88:91]
	v_mfma_f32_16x16x32_bf16 v[96:99], v[190:193], v[224:227], v[96:99]
	v_mfma_f32_16x16x32_bf16 v[72:75], v[182:185], v[232:235], v[72:75]
	v_mfma_f32_16x16x32_bf16 v[80:83], v[190:193], v[232:235], v[80:83]
	s_barrier
	s_add_i32 s81, s81, s43
	v_lshl_add_u64 v[150:151], s[36:37], 0, v[136:137]
	s_mov_b32 m0, s81
	ds_read_b128 v[194:197], v160 offset:16384
	ds_read_b128 v[198:201], v160 offset:17408
	ds_read_b128 v[212:215], v160 offset:18432
	ds_read_b128 v[216:219], v160 offset:19456
	ds_read_b128 v[220:223], v160 offset:20480
	ds_read_b128 v[224:227], v160 offset:21504
	ds_read_b128 v[228:231], v160 offset:22528
	ds_read_b128 v[232:235], v160 offset:23552
	s_cmp_lg_u32 s32, 0
	s_cbranch_scc1 .Lbt1460_0
	global_load_lds_dwordx4 v[150:151], off

; #define PG8_STAGE(bufoff, gbase, voff) do { _Pragma("unroll") for (int _i = 0; _i < 2; ++_i) \
;         __builtin_amdgcn_global_load_lds((const unsigned*)((const char*)(gbase) + (voff)[_i]), (PG8_LAS unsigned*)(lds + (bufoff) + ldsw + _i * 8192), 16, 0, 0); } while (0)
; #define PG8_LDA(dst, b, h) do { _Pragma("unroll") for (int m = 0; m < 4; ++m) _Pragma("unroll") for (int k = 0; k < 2; ++k) dst[m][k] = *(const PG8_LAS bf16x8*)(lds + PG8_SA(b, h) + aoff + m * 2048 + k * 1024); } while (0)
; #define PG8_LDB(dst, b, h) do { _Pragma("unroll") for (int n = 0; n < 2; ++n) _Pragma("unroll") for (int k = 0; k < 2; ++k) dst[n][k] = *(const PG8_LAS bf16x8*)(lds + PG8_SB(b, h) + boff + n * 2048 + k * 1024); } while (0)
; #define PG8_MMA(ai, bj, At, Bt) do { __builtin_amdgcn_s_setprio(1); _Pragma("unroll") for (int m = 0; m < 4; ++m) _Pragma("unroll") for (int n = 0; n < 2; ++n) _Pragma("unroll") for (int k = 0; k < 2; ++k) \
;         acc[ai][bj][m][n] = __builtin_amdgcn_mfma_f32_16x16x32_bf16(Bt[n][k], At[m][k], acc[ai][bj][m][n], 0, 0, 0); __builtin_amdgcn_s_setprio(0); } while (0)
; #define PG8_WAIT_V(n) asm volatile("s_waitcnt vmcnt(" #n ")" ::: "memory")
; #define PG8_WAIT_L(n) asm volatile("s_waitcnt lgkmcnt(" #n ")" ::: "memory")
; #define PG8_BAR __builtin_amdgcn_s_barrier()
; #define PG8_SCHED __builtin_amdgcn_sched_barrier(0)
; template <class Epi, class Sched, bool ALIGN_EPI = false, bool SP2 = false>
; __device__ __forceinline__ void gemm_phase(PG8_LAS unsigned char* lds, const Gemm g, const Sched& S, const Epi& E, const int tid) {
;     ...
;             PG8_WAIT_V(8); PG8_WAIT_L(0); PG8_BAR; PG8_MMA(1, 0, At, B0); PG8_MMA(1, 1, At, B1); PG8_BAR; PG8_SCHED;
;             PG8_LDB(B0, 1, 0); PG8_LDB(B1, 1, 1); PG8_SCHED; PG8_LDA(At, 1, 0); PG8_STAGE(PG8_SA(0, 1), a2 + hstep, voffA);
;             PG8_WAIT_V(8); PG8_WAIT_L(0); PG8_BAR; PG8_MMA(0, 0, At, B0); PG8_MMA(0, 1, At, B1); PG8_BAR; PG8_SCHED;
.Lbw1460_2:
	s_waitcnt lgkmcnt(0)
	s_barrier
	s_waitcnt lgkmcnt(0)
	v_mfma_f32_16x16x32_bf16 v[52:55], v[146:149], v[194:197], v[52:55]
	v_mfma_f32_16x16x32_bf16 v[60:63], v[170:173], v[194:197], v[60:63]
	v_mfma_f32_16x16x32_bf16 v[36:39], v[146:149], v[212:215], v[36:39]
	v_mfma_f32_16x16x32_bf16 v[44:47], v[170:173], v[212:215], v[44:47]
	v_mfma_f32_16x16x32_bf16 v[20:23], v[146:149], v[220:223], v[20:23]
	v_mfma_f32_16x16x32_bf16 v[28:31], v[170:173], v[220:223], v[28:31]
	v_mfma_f32_16x16x32_bf16 v[4:7], v[146:149], v[228:231], v[4:7]
	v_mfma_f32_16x16x32_bf16 v[12:15], v[170:173], v[228:231], v[12:15]
	v_mfma_f32_16x16x32_bf16 v[52:55], v[162:165], v[198:201], v[52:55]
	v_mfma_f32_16x16x32_bf16 v[60:63], v[174:177], v[198:201], v[60:63]
	v_mfma_f32_16x16x32_bf16 v[36:39], v[162:165], v[216:219], v[36:39]
	v_mfma_f32_16x16x32_bf16 v[44:47], v[174:177], v[216:219], v[44:47]
	v_mfma_f32_16x16x32_bf16 v[20:23], v[162:165], v[224:227], v[20:23]
	v_mfma_f32_16x16x32_bf16 v[28:31], v[174:177], v[224:227], v[28:31]
	v_mfma_f32_16x16x32_bf16 v[4:7], v[162:165], v[232:235], v[4:7]
	v_mfma_f32_16x16x32_bf16 v[12:15], v[174:177], v[232:235], v[12:15]
	v_mfma_f32_16x16x32_bf16 v[56:59], v[178:181], v[194:197], v[56:59]
	v_mfma_f32_16x16x32_bf16 v[64:67], v[186:189], v[194:197], v[64:67]
	v_mfma_f32_16x16x32_bf16 v[40:43], v[178:181], v[212:215], v[40:43]
	v_mfma_f32_16x16x32_bf16 v[48:51], v[186:189], v[212:215], v[48:51]
	v_mfma_f32_16x16x32_bf16 v[24:27], v[178:181], v[220:223], v[24:27]
	v_mfma_f32_16x16x32_bf16 v[32:35], v[186:189], v[220:223], v[32:35]
	v_mfma_f32_16x16x32_bf16 v[8:11], v[178:181], v[228:231], v[8:11]
	v_mfma_f32_16x16x32_bf16 v[16:19], v[186:189], v[228:231], v[16:19]
	v_mfma_f32_16x16x32_bf16 v[56:59], v[182:185], v[198:201], v[56:59]
	v_mfma_f32_16x16x32_bf16 v[64:67], v[190:193], v[198:201], v[64:67]
	v_mfma_f32_16x16x32_bf16 v[40:43], v[182:185], v[216:219], v[40:43]
	v_mfma_f32_16x16x32_bf16 v[48:51], v[190:193], v[216:219], v[48:51]
	v_mfma_f32_16x16x32_bf16 v[24:27], v[182:185], v[224:227], v[24:27]
	v_mfma_f32_16x16x32_bf16 v[32:35], v[190:193], v[224:227], v[32:35]
	v_mfma_f32_16x16x32_bf16 v[8:11], v[182:185], v[232:235], v[8:11]
	v_mfma_f32_16x16x32_bf16 v[16:19], v[190:193], v[232:235], v[16:19]
	s_barrier
	s_add_i32 s81, 0, 0x18000
	v_add_u32_e32 v161, s81, v158
	s_add_i32 s82, 0, 0x1c000
	ds_read_b128 v[146:149], v161
	ds_read_b128 v[162:165], v161 offset:1024
	ds_read_b128 v[170:173], v161 offset:2048
	ds_read_b128 v[174:177], v161 offset:3072
	v_add_u32_e32 v161, s82, v158
	ds_read_b128 v[178:181], v161
	ds_read_b128 v[182:185], v161 offset:1024
	ds_read_b128 v[186:189], v161 offset:2048
	ds_read_b128 v[190:193], v161 offset:3072
	s_add_u32 s40, s40, 0x100000
	s_addc_u32 s41, s41, 0
	s_mov_b32 m0, s62
	v_lshl_add_u64 v[240:241], s[40:41], 0, v[134:135]
	ds_read_b128 v[194:197], v160 offset:32768
	ds_read_b128 v[198:201], v160 offset:33792
	ds_read_b128 v[212:215], v160 offset:34816
	ds_read_b128 v[216:219], v160 offset:35840
	ds_read_b128 v[220:223], v160 offset:36864
	ds_read_b128 v[224:227], v160 offset:37888
	ds_read_b128 v[228:231], v160 offset:38912
	ds_read_b128 v[232:235], v160 offset:39936
	s_cmp_lg_u32 s32, 0
	s_cbranch_scc1 .Lbt1460_6
	global_load_lds_dwordx4 v[240:241], off

; #define PG8_STAGE(bufoff, gbase, voff) do { _Pragma("unroll") for (int _i = 0; _i < 2; ++_i) \
;         __builtin_amdgcn_global_load_lds((const unsigned*)((const char*)(gbase) + (voff)[_i]), (PG8_LAS unsigned*)(lds + (bufoff) + ldsw + _i * 8192), 16, 0, 0); } while (0)
; #define PG8_LDA(dst, b, h) do { _Pragma("unroll") for (int m = 0; m < 4; ++m) _Pragma("unroll") for (int k = 0; k < 2; ++k) dst[m][k] = *(const PG8_LAS bf16x8*)(lds + PG8_SA(b, h) + aoff + m * 2048 + k * 1024); } while (0)
; #define PG8_MMA(ai, bj, At, Bt) do { __builtin_amdgcn_s_setprio(1); _Pragma("unroll") for (int m = 0; m < 4; ++m) _Pragma("unroll") for (int n = 0; n < 2; ++n) _Pragma("unroll") for (int k = 0; k < 2; ++k) \
;         acc[ai][bj][m][n] = __builtin_amdgcn_mfma_f32_16x16x32_bf16(Bt[n][k], At[m][k], acc[ai][bj][m][n], 0, 0, 0); __builtin_amdgcn_s_setprio(0); } while (0)
; #define PG8_WAIT_V(n) asm volatile("s_waitcnt vmcnt(" #n ")" ::: "memory")
; #define PG8_WAIT_L(n) asm volatile("s_waitcnt lgkmcnt(" #n ")" ::: "memory")
; #define PG8_BAR __builtin_amdgcn_s_barrier()
; #define PG8_SCHED __builtin_amdgcn_sched_barrier(0)
; template <class Epi, class Sched, bool ALIGN_EPI = false, bool SP2 = false>
; __device__ __forceinline__ void gemm_phase(PG8_LAS unsigned char* lds, const Gemm g, const Sched& S, const Epi& E, const int tid) {
;     ...
;         for (int t = 0; t < nt; t += 2) {
;             const bool last = (t == nt - 2);
;             const char* a1 = cA + (size_t)(t + 1) * kstep;
;             const char* a2 = last ? nA : cA + (size_t)(t + 2) * kstep; const char* b2 = last ? nB : cB + (size_t)(t + 2) * kstep;
;             const char* a3 = a2 + kstep; const char* b3 = b2 + kstep;
;     ...
;             PG8_LDA(At, 1, 1); PG8_STAGE(PG8_SB(1, 0), b3, voffB); PG8_STAGE(PG8_SB(1, 1), b3 + hstepB, voffB); PG8_STAGE(PG8_SA(1, 0), a3, voffA);
;             PG8_WAIT_V(8); PG8_WAIT_L(0); PG8_BAR; PG8_MMA(1, 0, At, B0); PG8_MMA(1, 1, At, B1); PG8_BAR; PG8_SCHED;
.Lbt1460_13:
	s_waitcnt vmcnt(8)
	s_waitcnt lgkmcnt(0)
	s_barrier
	s_waitcnt lgkmcnt(0)
	v_mfma_f32_16x16x32_bf16 v[52:55], v[146:149], v[194:197], v[52:55]
	v_mfma_f32_16x16x32_bf16 v[60:63], v[170:173], v[194:197], v[60:63]
	v_mfma_f32_16x16x32_bf16 v[36:39], v[146:149], v[212:215], v[36:39]
	v_mfma_f32_16x16x32_bf16 v[44:47], v[170:173], v[212:215], v[44:47]
	v_mfma_f32_16x16x32_bf16 v[20:23], v[146:149], v[220:223], v[20:23]
	v_mfma_f32_16x16x32_bf16 v[28:31], v[170:173], v[220:223], v[28:31]
	v_mfma_f32_16x16x32_bf16 v[4:7], v[146:149], v[228:231], v[4:7]
	v_mfma_f32_16x16x32_bf16 v[12:15], v[170:173], v[228:231], v[12:15]
	v_mfma_f32_16x16x32_bf16 v[52:55], v[162:165], v[198:201], v[52:55]
	v_mfma_f32_16x16x32_bf16 v[60:63], v[174:177], v[198:201], v[60:63]
	v_mfma_f32_16x16x32_bf16 v[36:39], v[162:165], v[216:219], v[36:39]
	v_mfma_f32_16x16x32_bf16 v[44:47], v[174:177], v[216:219], v[44:47]
	v_mfma_f32_16x16x32_bf16 v[20:23], v[162:165], v[224:227], v[20:23]
	v_mfma_f32_16x16x32_bf16 v[28:31], v[174:177], v[224:227], v[28:31]
	v_mfma_f32_16x16x32_bf16 v[4:7], v[162:165], v[232:235], v[4:7]
	v_mfma_f32_16x16x32_bf16 v[12:15], v[174:177], v[232:235], v[12:15]
	v_mfma_f32_16x16x32_bf16 v[56:59], v[178:181], v[194:197], v[56:59]
	v_mfma_f32_16x16x32_bf16 v[64:67], v[186:189], v[194:197], v[64:67]
	v_mfma_f32_16x16x32_bf16 v[40:43], v[178:181], v[212:215], v[40:43]
	v_mfma_f32_16x16x32_bf16 v[48:51], v[186:189], v[212:215], v[48:51]
	v_mfma_f32_16x16x32_bf16 v[24:27], v[178:181], v[220:223], v[24:27]
	v_mfma_f32_16x16x32_bf16 v[32:35], v[186:189], v[220:223], v[32:35]
	v_mfma_f32_16x16x32_bf16 v[8:11], v[178:181], v[228:231], v[8:11]
	v_mfma_f32_16x16x32_bf16 v[16:19], v[186:189], v[228:231], v[16:19]
	v_mfma_f32_16x16x32_bf16 v[56:59], v[182:185], v[198:201], v[56:59]
	v_mfma_f32_16x16x32_bf16 v[64:67], v[190:193], v[198:201], v[64:67]
	v_mfma_f32_16x16x32_bf16 v[40:43], v[182:185], v[216:219], v[40:43]
	v_mfma_f32_16x16x32_bf16 v[48:51], v[190:193], v[216:219], v[48:51]
	v_mfma_f32_16x16x32_bf16 v[24:27], v[182:185], v[224:227], v[24:27]
	v_mfma_f32_16x16x32_bf16 v[32:35], v[190:193], v[224:227], v[32:35]
	v_mfma_f32_16x16x32_bf16 v[8:11], v[182:185], v[232:235], v[8:11]
	v_mfma_f32_16x16x32_bf16 v[16:19], v[190:193], v[232:235], v[16:19]
	s_barrier
	s_add_i32 s80, s80, 2
	s_add_u32 s38, s38, 0x100
	s_addc_u32 s39, s39, 0
	s_add_u32 s78, s78, 0x100
	s_addc_u32 s79, s79, 0
	s_cmp_gt_u32 s80, 61
	s_cbranch_scc0 .LBB0_1460
	s_and_b64 vcc, exec, s[14:15]
	s_cbranch_vccz .LBB0_1463
	s_barrier
